# pool K loops unrolled: B fragments 2 k-steps ahead via immediate offsets, LDS row ring, dot2c sums (all 4 window sizes)
# baseline (speedup 1.0000x reference)
.LBB0_332:
	s_or_b64 exec, exec, s[6:7]
	s_waitcnt lgkmcnt(0)
	global_load_dwordx4 v[82:85], v[144:145], off offset:512
	global_load_dwordx4 v[86:89], v[146:147], off offset:512
	global_load_dwordx4 v[90:93], v[148:149], off offset:512
	global_load_dwordx4 v[94:97], v[150:151], off offset:512
	v_or_b32_e32 v2, s28, v1
	v_min_u32_e32 v3, 15, v2
	v_add_u32_e32 v3, 1, v3
	v_cvt_f32_ubyte0_e32 v3, v3
	v_div_scale_f32 v4, s[6:7], v3, v3, 1.0
	v_rcp_f32_e32 v5, v4
	s_ashr_i32 s8, s30, 6
	s_mul_i32 s10, s8, 15
	v_cmp_lt_u32_e64 s[6:7], s41, v2
	v_fma_f32 v6, -v4, v5, 1.0
	v_fmac_f32_e32 v5, v6, v5
	v_div_scale_f32 v6, vcc, 1.0, v3, 1.0
	v_mul_f32_e32 v7, v6, v5
	v_fma_f32 v8, -v4, v7, v6
	v_fmac_f32_e32 v7, v8, v5
	v_fma_f32 v4, -v4, v7, v6
	v_div_fmas_f32 v4, v4, v5, v7
	v_div_fixup_f32 v159, v4, v3, 1.0
	s_ashr_i32 s11, s10, 31
	v_add_u32_e32 v2, 0xfffff80f, v2
	v_mov_b32_e32 v3, v155
	v_lshl_add_u64 v[2:3], v[2:3], 0, s[10:11]
	v_lshlrev_b64 v[2:3], 11, v[2:3]
	v_lshl_add_u64 v[2:3], s[70:71], 0, v[2:3]
	v_mov_b32_e32 v163, v155
	v_lshl_add_u64 v[2:3], v[2:3], 0, v[162:163]
	v_lshl_add_u64 v[192:193], v[2:3], 0, s[16:17]
	v_mov_b32_e32 v2, 0
	s_mov_b32 s49, 0
	s_mov_b64 s[10:11], 0
	v_mov_b32_e32 v3, v2
	v_mov_b32_e32 v4, v2
	v_mov_b32_e32 v5, v2
	v_mov_b32_e32 v6, v2
	v_mov_b32_e32 v7, v2
	v_mov_b32_e32 v8, v2
	v_mov_b32_e32 v9, v2
	v_mov_b32_e32 v10, v2
	v_mov_b32_e32 v11, v2
	v_mov_b32_e32 v12, v2
	v_mov_b32_e32 v13, v2
	v_mov_b32_e32 v14, v2
	v_mov_b32_e32 v15, v2
	v_mov_b32_e32 v16, v2
	v_mov_b32_e32 v17, v2
	v_mov_b32_e32 v18, v2
	v_mov_b32_e32 v19, v2
	v_mov_b32_e32 v20, v2
	v_mov_b32_e32 v21, v2
	v_mov_b32_e32 v22, v2
	v_mov_b32_e32 v23, v2
	v_mov_b32_e32 v24, v2
	v_mov_b32_e32 v25, v2
	v_mov_b32_e32 v26, v2
	v_mov_b32_e32 v27, v2
	v_mov_b32_e32 v28, v2
	v_mov_b32_e32 v29, v2
	v_mov_b32_e32 v30, v2
	v_mov_b32_e32 v31, v2
	v_mov_b32_e32 v32, v2
	v_mov_b32_e32 v33, v2
	v_mov_b32_e32 v34, v2
	v_mov_b32_e32 v35, v2
	v_mov_b32_e32 v36, v2
	v_mov_b32_e32 v37, v2
	v_mov_b32_e32 v38, v2
	v_mov_b32_e32 v39, v2
	v_mov_b32_e32 v40, v2
	v_mov_b32_e32 v41, v2
	v_mov_b32_e32 v42, v2
	v_mov_b32_e32 v43, v2
	v_mov_b32_e32 v44, v2
	v_mov_b32_e32 v45, v2
	v_mov_b32_e32 v46, v2
	v_mov_b32_e32 v47, v2
	v_mov_b32_e32 v48, v2
	v_mov_b32_e32 v49, v2
	v_mov_b32_e32 v50, v2
	v_mov_b32_e32 v51, v2
	v_mov_b32_e32 v52, v2
	v_mov_b32_e32 v53, v2
	v_mov_b32_e32 v54, v2
	v_mov_b32_e32 v55, v2
	v_mov_b32_e32 v56, v2
	v_mov_b32_e32 v57, v2
	v_mov_b32_e32 v58, v2
	v_mov_b32_e32 v59, v2
	v_mov_b32_e32 v60, v2
	v_mov_b32_e32 v61, v2
	v_mov_b32_e32 v62, v2
	v_mov_b32_e32 v63, v2
	v_mov_b32_e32 v64, v2
	v_mov_b32_e32 v65, v2
	s_mov_b32 s50, 0x3f80
	s_mov_b32 s51, 0x3f800000
	v_lshl_add_u32 v163, v197, 1, v214
	ds_read_b128 v[222:225], v163 offset:4080
	ds_read_b128 v[226:229], v163 offset:3808
	ds_read_b128 v[230:233], v163 offset:3536
	ds_read_b128 v[234:237], v163 offset:3264
	ds_read_b128 v[238:241], v163 offset:2992
	ds_read_b128 v[242:245], v163 offset:2720
	ds_read_b128 v[248:251], v163 offset:2448
	ds_read_b128 v[252:255], v163 offset:2176
	s_waitcnt lgkmcnt(7)
	v_lshlrev_b32_e32 v98, 16, v222
	v_and_b32_e32 v99, 0xffff0000, v222
	v_lshlrev_b32_e32 v100, 16, v223
	v_and_b32_e32 v101, 0xffff0000, v223
	v_lshlrev_b32_e32 v102, 16, v224
	v_and_b32_e32 v103, 0xffff0000, v224
	v_lshlrev_b32_e32 v104, 16, v225
	v_and_b32_e32 v105, 0xffff0000, v225
	v_mov_b64_e32 v[106:107], v[98:99]
	v_mov_b64_e32 v[108:109], v[100:101]
	v_mov_b64_e32 v[218:219], v[102:103]
	v_mov_b64_e32 v[220:221], v[104:105]
	ds_read_b128 v[222:225], v163 offset:1904
	s_waitcnt lgkmcnt(7)
	v_dot2c_f32_bf16 v106, s50, v226
	v_dot2c_f32_bf16 v107, s51, v226
	v_dot2c_f32_bf16 v108, s50, v227
	v_dot2c_f32_bf16 v109, s51, v227
	v_dot2c_f32_bf16 v218, s50, v228
	v_dot2c_f32_bf16 v219, s51, v228
	v_dot2c_f32_bf16 v220, s50, v229
	v_dot2c_f32_bf16 v221, s51, v229
	ds_read_b128 v[226:229], v163 offset:1632
	s_waitcnt lgkmcnt(7)
	v_dot2c_f32_bf16 v106, s50, v230
	v_dot2c_f32_bf16 v107, s51, v230
	v_dot2c_f32_bf16 v108, s50, v231
	v_dot2c_f32_bf16 v109, s51, v231
	v_dot2c_f32_bf16 v218, s50, v232
	v_dot2c_f32_bf16 v219, s51, v232
	v_dot2c_f32_bf16 v220, s50, v233
	v_dot2c_f32_bf16 v221, s51, v233
	ds_read_b128 v[230:233], v163 offset:1360
	s_waitcnt lgkmcnt(7)
	v_dot2c_f32_bf16 v106, s50, v234
	v_dot2c_f32_bf16 v107, s51, v234
	v_dot2c_f32_bf16 v108, s50, v235
	v_dot2c_f32_bf16 v109, s51, v235
	v_dot2c_f32_bf16 v218, s50, v236
	v_dot2c_f32_bf16 v219, s51, v236
	v_dot2c_f32_bf16 v220, s50, v237
	v_dot2c_f32_bf16 v221, s51, v237
	ds_read_b128 v[234:237], v163 offset:1088
	s_waitcnt lgkmcnt(7)
	v_dot2c_f32_bf16 v106, s50, v238
	v_dot2c_f32_bf16 v107, s51, v238
	v_dot2c_f32_bf16 v108, s50, v239
	v_dot2c_f32_bf16 v109, s51, v239
	v_dot2c_f32_bf16 v218, s50, v240
	v_dot2c_f32_bf16 v219, s51, v240
	v_dot2c_f32_bf16 v220, s50, v241
	v_dot2c_f32_bf16 v221, s51, v241
	ds_read_b128 v[238:241], v163 offset:816
	s_waitcnt lgkmcnt(7)
	v_dot2c_f32_bf16 v106, s50, v242
	v_dot2c_f32_bf16 v107, s51, v242
	v_dot2c_f32_bf16 v108, s50, v243
	v_dot2c_f32_bf16 v109, s51, v243
	v_dot2c_f32_bf16 v218, s50, v244
	v_dot2c_f32_bf16 v219, s51, v244
	v_dot2c_f32_bf16 v220, s50, v245
	v_dot2c_f32_bf16 v221, s51, v245
	ds_read_b128 v[242:245], v163 offset:544
	s_waitcnt lgkmcnt(7)
	v_dot2c_f32_bf16 v106, s50, v248
	v_dot2c_f32_bf16 v107, s51, v248
	v_dot2c_f32_bf16 v108, s50, v249
	v_dot2c_f32_bf16 v109, s51, v249
	v_dot2c_f32_bf16 v218, s50, v250
	v_dot2c_f32_bf16 v219, s51, v250
	v_dot2c_f32_bf16 v220, s50, v251
	v_dot2c_f32_bf16 v221, s51, v251
	ds_read_b128 v[248:251], v163 offset:272
	s_waitcnt lgkmcnt(7)
	v_dot2c_f32_bf16 v106, s50, v252
	v_dot2c_f32_bf16 v107, s51, v252
	v_dot2c_f32_bf16 v108, s50, v253
	v_dot2c_f32_bf16 v109, s51, v253
	v_dot2c_f32_bf16 v218, s50, v254
	v_dot2c_f32_bf16 v219, s51, v254
	v_dot2c_f32_bf16 v220, s50, v255
	v_dot2c_f32_bf16 v221, s51, v255
	ds_read_b128 v[252:255], v163 offset:0
	s_waitcnt lgkmcnt(7)
	v_dot2c_f32_bf16 v106, s50, v222
	v_dot2c_f32_bf16 v107, s51, v222
	v_dot2c_f32_bf16 v108, s50, v223
	v_dot2c_f32_bf16 v109, s51, v223
	v_dot2c_f32_bf16 v218, s50, v224
	v_dot2c_f32_bf16 v219, s51, v224
	v_dot2c_f32_bf16 v220, s50, v225
	v_dot2c_f32_bf16 v221, s51, v225
	ds_read_b128 v[222:225], v163 offset:4112
	s_waitcnt lgkmcnt(7)
	v_dot2c_f32_bf16 v106, s50, v226
	v_dot2c_f32_bf16 v107, s51, v226
	v_dot2c_f32_bf16 v108, s50, v227
	v_dot2c_f32_bf16 v109, s51, v227
	v_dot2c_f32_bf16 v218, s50, v228
	v_dot2c_f32_bf16 v219, s51, v228
	v_dot2c_f32_bf16 v220, s50, v229
	v_dot2c_f32_bf16 v221, s51, v229
	ds_read_b128 v[226:229], v163 offset:3840
	s_waitcnt lgkmcnt(7)
	v_dot2c_f32_bf16 v106, s50, v230
	v_dot2c_f32_bf16 v107, s51, v230
	v_dot2c_f32_bf16 v108, s50, v231
	v_dot2c_f32_bf16 v109, s51, v231
	v_dot2c_f32_bf16 v218, s50, v232
	v_dot2c_f32_bf16 v219, s51, v232
	v_dot2c_f32_bf16 v220, s50, v233
	v_dot2c_f32_bf16 v221, s51, v233
	ds_read_b128 v[230:233], v163 offset:3568
	s_waitcnt lgkmcnt(7)
	v_dot2c_f32_bf16 v106, s50, v234
	v_dot2c_f32_bf16 v107, s51, v234
	v_dot2c_f32_bf16 v108, s50, v235
	v_dot2c_f32_bf16 v109, s51, v235
	v_dot2c_f32_bf16 v218, s50, v236
	v_dot2c_f32_bf16 v219, s51, v236
	v_dot2c_f32_bf16 v220, s50, v237
	v_dot2c_f32_bf16 v221, s51, v237
	ds_read_b128 v[234:237], v163 offset:3296
	s_waitcnt lgkmcnt(7)
	v_dot2c_f32_bf16 v106, s50, v238
	v_dot2c_f32_bf16 v107, s51, v238
	v_dot2c_f32_bf16 v108, s50, v239
	v_dot2c_f32_bf16 v109, s51, v239
	v_dot2c_f32_bf16 v218, s50, v240
	v_dot2c_f32_bf16 v219, s51, v240
	v_dot2c_f32_bf16 v220, s50, v241
	v_dot2c_f32_bf16 v221, s51, v241
	ds_read_b128 v[238:241], v163 offset:3024
	s_waitcnt lgkmcnt(7)
	v_dot2c_f32_bf16 v106, s50, v242
	v_dot2c_f32_bf16 v107, s51, v242
	v_dot2c_f32_bf16 v108, s50, v243
	v_dot2c_f32_bf16 v109, s51, v243
	v_dot2c_f32_bf16 v218, s50, v244
	v_dot2c_f32_bf16 v219, s51, v244
	v_dot2c_f32_bf16 v220, s50, v245
	v_dot2c_f32_bf16 v221, s51, v245
	ds_read_b128 v[242:245], v163 offset:2752
	s_waitcnt lgkmcnt(7)
	v_dot2c_f32_bf16 v106, s50, v248
	v_dot2c_f32_bf16 v107, s51, v248
	v_dot2c_f32_bf16 v108, s50, v249
	v_dot2c_f32_bf16 v109, s51, v249
	v_dot2c_f32_bf16 v218, s50, v250
	v_dot2c_f32_bf16 v219, s51, v250
	v_dot2c_f32_bf16 v220, s50, v251
	v_dot2c_f32_bf16 v221, s51, v251
	ds_read_b128 v[248:251], v163 offset:2480
	s_waitcnt lgkmcnt(7)
	v_dot2c_f32_bf16 v106, s50, v252
	v_dot2c_f32_bf16 v107, s51, v252
	v_dot2c_f32_bf16 v108, s50, v253
	v_dot2c_f32_bf16 v109, s51, v253
	v_dot2c_f32_bf16 v218, s50, v254
	v_dot2c_f32_bf16 v219, s51, v254
	v_dot2c_f32_bf16 v220, s50, v255
	v_dot2c_f32_bf16 v221, s51, v255
	ds_read_b128 v[252:255], v163 offset:2208
	v_fma_f32 v106, v159, v106, -v98
	v_fma_f32 v107, v159, v107, -v99
	v_fma_f32 v108, v159, v108, -v100
	v_fma_f32 v109, v159, v109, -v101
	v_fma_f32 v218, v159, v218, -v102
	v_fma_f32 v219, v159, v219, -v103
	v_fma_f32 v220, v159, v220, -v104
	v_fma_f32 v221, v159, v221, -v105
	v_cvt_pk_bf16_f32 v106, v106, v107
	v_cvt_pk_bf16_f32 v107, v108, v109
	v_cvt_pk_bf16_f32 v108, v218, v219
	v_cvt_pk_bf16_f32 v109, v220, v221
	s_and_saveexec_b64 s[28:29], s[6:7]
	s_cbranch_execz .Lpu0_0
	global_store_dwordx4 v[192:193], v[98:101], off offset:0
	global_store_dwordx4 v[192:193], v[102:105], off offset:16
.Lpu0_0:
	s_or_b64 exec, exec, s[28:29]
	s_waitcnt vmcnt(4)
	v_mfma_f32_32x32x16_bf16 v[2:17], v[106:109], v[70:73], v[2:17]
	v_mfma_f32_32x32x16_bf16 v[18:33], v[106:109], v[74:77], v[18:33]
	v_mfma_f32_32x32x16_bf16 v[34:49], v[106:109], v[78:81], v[34:49]
	v_mfma_f32_32x32x16_bf16 v[50:65], v[106:109], v[66:69], v[50:65]
	global_load_dwordx4 v[70:73], v[144:145], off offset:1024
	global_load_dwordx4 v[74:77], v[146:147], off offset:1024
	global_load_dwordx4 v[78:81], v[148:149], off offset:1024
	global_load_dwordx4 v[66:69], v[150:151], off offset:1024
	s_waitcnt lgkmcnt(7)
	v_lshlrev_b32_e32 v98, 16, v222
	v_and_b32_e32 v99, 0xffff0000, v222
	v_lshlrev_b32_e32 v100, 16, v223
	v_and_b32_e32 v101, 0xffff0000, v223
	v_lshlrev_b32_e32 v102, 16, v224
	v_and_b32_e32 v103, 0xffff0000, v224
	v_lshlrev_b32_e32 v104, 16, v225
	v_and_b32_e32 v105, 0xffff0000, v225
	v_mov_b64_e32 v[106:107], v[98:99]
	v_mov_b64_e32 v[108:109], v[100:101]
	v_mov_b64_e32 v[218:219], v[102:103]
	v_mov_b64_e32 v[220:221], v[104:105]
	ds_read_b128 v[222:225], v163 offset:1936
	s_waitcnt lgkmcnt(7)
	v_dot2c_f32_bf16 v106, s50, v226
	v_dot2c_f32_bf16 v107, s51, v226
	v_dot2c_f32_bf16 v108, s50, v227
	v_dot2c_f32_bf16 v109, s51, v227
	v_dot2c_f32_bf16 v218, s50, v228
	v_dot2c_f32_bf16 v219, s51, v228
	v_dot2c_f32_bf16 v220, s50, v229
	v_dot2c_f32_bf16 v221, s51, v229
	ds_read_b128 v[226:229], v163 offset:1664
	s_waitcnt lgkmcnt(7)
	v_dot2c_f32_bf16 v106, s50, v230
	v_dot2c_f32_bf16 v107, s51, v230
	v_dot2c_f32_bf16 v108, s50, v231
	v_dot2c_f32_bf16 v109, s51, v231
	v_dot2c_f32_bf16 v218, s50, v232
	v_dot2c_f32_bf16 v219, s51, v232
	v_dot2c_f32_bf16 v220, s50, v233
	v_dot2c_f32_bf16 v221, s51, v233
	ds_read_b128 v[230:233], v163 offset:1392
	s_waitcnt lgkmcnt(7)
	v_dot2c_f32_bf16 v106, s50, v234
	v_dot2c_f32_bf16 v107, s51, v234
	v_dot2c_f32_bf16 v108, s50, v235
	v_dot2c_f32_bf16 v109, s51, v235
	v_dot2c_f32_bf16 v218, s50, v236
	v_dot2c_f32_bf16 v219, s51, v236
	v_dot2c_f32_bf16 v220, s50, v237
	v_dot2c_f32_bf16 v221, s51, v237
	ds_read_b128 v[234:237], v163 offset:1120
	s_waitcnt lgkmcnt(7)
	v_dot2c_f32_bf16 v106, s50, v238
	v_dot2c_f32_bf16 v107, s51, v238
	v_dot2c_f32_bf16 v108, s50, v239
	v_dot2c_f32_bf16 v109, s51, v239
	v_dot2c_f32_bf16 v218, s50, v240
	v_dot2c_f32_bf16 v219, s51, v240
	v_dot2c_f32_bf16 v220, s50, v241
	v_dot2c_f32_bf16 v221, s51, v241
	ds_read_b128 v[238:241], v163 offset:848
	s_waitcnt lgkmcnt(7)
	v_dot2c_f32_bf16 v106, s50, v242
	v_dot2c_f32_bf16 v107, s51, v242
	v_dot2c_f32_bf16 v108, s50, v243
	v_dot2c_f32_bf16 v109, s51, v243
	v_dot2c_f32_bf16 v218, s50, v244
	v_dot2c_f32_bf16 v219, s51, v244
	v_dot2c_f32_bf16 v220, s50, v245
	v_dot2c_f32_bf16 v221, s51, v245
	ds_read_b128 v[242:245], v163 offset:576
	s_waitcnt lgkmcnt(7)
	v_dot2c_f32_bf16 v106, s50, v248
	v_dot2c_f32_bf16 v107, s51, v248
	v_dot2c_f32_bf16 v108, s50, v249
	v_dot2c_f32_bf16 v109, s51, v249
	v_dot2c_f32_bf16 v218, s50, v250
	v_dot2c_f32_bf16 v219, s51, v250
	v_dot2c_f32_bf16 v220, s50, v251
	v_dot2c_f32_bf16 v221, s51, v251
	ds_read_b128 v[248:251], v163 offset:304
	s_waitcnt lgkmcnt(7)
	v_dot2c_f32_bf16 v106, s50, v252
	v_dot2c_f32_bf16 v107, s51, v252
	v_dot2c_f32_bf16 v108, s50, v253
	v_dot2c_f32_bf16 v109, s51, v253
	v_dot2c_f32_bf16 v218, s50, v254
	v_dot2c_f32_bf16 v219, s51, v254
	v_dot2c_f32_bf16 v220, s50, v255
	v_dot2c_f32_bf16 v221, s51, v255
	ds_read_b128 v[252:255], v163 offset:32
	s_waitcnt lgkmcnt(7)
	v_dot2c_f32_bf16 v106, s50, v222
	v_dot2c_f32_bf16 v107, s51, v222
	v_dot2c_f32_bf16 v108, s50, v223
	v_dot2c_f32_bf16 v109, s51, v223
	v_dot2c_f32_bf16 v218, s50, v224
	v_dot2c_f32_bf16 v219, s51, v224
	v_dot2c_f32_bf16 v220, s50, v225
	v_dot2c_f32_bf16 v221, s51, v225
	ds_read_b128 v[222:225], v163 offset:4144
	s_waitcnt lgkmcnt(7)
	v_dot2c_f32_bf16 v106, s50, v226
	v_dot2c_f32_bf16 v107, s51, v226
	v_dot2c_f32_bf16 v108, s50, v227
	v_dot2c_f32_bf16 v109, s51, v227
	v_dot2c_f32_bf16 v218, s50, v228
	v_dot2c_f32_bf16 v219, s51, v228
	v_dot2c_f32_bf16 v220, s50, v229
	v_dot2c_f32_bf16 v221, s51, v229
	ds_read_b128 v[226:229], v163 offset:3872
	s_waitcnt lgkmcnt(7)
	v_dot2c_f32_bf16 v106, s50, v230
	v_dot2c_f32_bf16 v107, s51, v230
	v_dot2c_f32_bf16 v108, s50, v231
	v_dot2c_f32_bf16 v109, s51, v231
	v_dot2c_f32_bf16 v218, s50, v232
	v_dot2c_f32_bf16 v219, s51, v232
	v_dot2c_f32_bf16 v220, s50, v233
	v_dot2c_f32_bf16 v221, s51, v233
	ds_read_b128 v[230:233], v163 offset:3600
	s_waitcnt lgkmcnt(7)
	v_dot2c_f32_bf16 v106, s50, v234
	v_dot2c_f32_bf16 v107, s51, v234
	v_dot2c_f32_bf16 v108, s50, v235
	v_dot2c_f32_bf16 v109, s51, v235
	v_dot2c_f32_bf16 v218, s50, v236
	v_dot2c_f32_bf16 v219, s51, v236
	v_dot2c_f32_bf16 v220, s50, v237
	v_dot2c_f32_bf16 v221, s51, v237
	ds_read_b128 v[234:237], v163 offset:3328
	s_waitcnt lgkmcnt(7)
	v_dot2c_f32_bf16 v106, s50, v238
	v_dot2c_f32_bf16 v107, s51, v238
	v_dot2c_f32_bf16 v108, s50, v239
	v_dot2c_f32_bf16 v109, s51, v239
	v_dot2c_f32_bf16 v218, s50, v240
	v_dot2c_f32_bf16 v219, s51, v240
	v_dot2c_f32_bf16 v220, s50, v241
	v_dot2c_f32_bf16 v221, s51, v241
	ds_read_b128 v[238:241], v163 offset:3056
	s_waitcnt lgkmcnt(7)
	v_dot2c_f32_bf16 v106, s50, v242
	v_dot2c_f32_bf16 v107, s51, v242
	v_dot2c_f32_bf16 v108, s50, v243
	v_dot2c_f32_bf16 v109, s51, v243
	v_dot2c_f32_bf16 v218, s50, v244
	v_dot2c_f32_bf16 v219, s51, v244
	v_dot2c_f32_bf16 v220, s50, v245
	v_dot2c_f32_bf16 v221, s51, v245
	ds_read_b128 v[242:245], v163 offset:2784
	s_waitcnt lgkmcnt(7)
	v_dot2c_f32_bf16 v106, s50, v248
	v_dot2c_f32_bf16 v107, s51, v248
	v_dot2c_f32_bf16 v108, s50, v249
	v_dot2c_f32_bf16 v109, s51, v249
	v_dot2c_f32_bf16 v218, s50, v250
	v_dot2c_f32_bf16 v219, s51, v250
	v_dot2c_f32_bf16 v220, s50, v251
	v_dot2c_f32_bf16 v221, s51, v251
	ds_read_b128 v[248:251], v163 offset:2512
	s_waitcnt lgkmcnt(7)
	v_dot2c_f32_bf16 v106, s50, v252
	v_dot2c_f32_bf16 v107, s51, v252
	v_dot2c_f32_bf16 v108, s50, v253
	v_dot2c_f32_bf16 v109, s51, v253
	v_dot2c_f32_bf16 v218, s50, v254
	v_dot2c_f32_bf16 v219, s51, v254
	v_dot2c_f32_bf16 v220, s50, v255
	v_dot2c_f32_bf16 v221, s51, v255
	ds_read_b128 v[252:255], v163 offset:2240
	v_fma_f32 v106, v159, v106, -v98
	v_fma_f32 v107, v159, v107, -v99
	v_fma_f32 v108, v159, v108, -v100
	v_fma_f32 v109, v159, v109, -v101
	v_fma_f32 v218, v159, v218, -v102
	v_fma_f32 v219, v159, v219, -v103
	v_fma_f32 v220, v159, v220, -v104
	v_fma_f32 v221, v159, v221, -v105
	v_cvt_pk_bf16_f32 v106, v106, v107
	v_cvt_pk_bf16_f32 v107, v108, v109
	v_cvt_pk_bf16_f32 v108, v218, v219
	v_cvt_pk_bf16_f32 v109, v220, v221
	s_and_saveexec_b64 s[28:29], s[6:7]
	s_cbranch_execz .Lpu0_1
	global_store_dwordx4 v[192:193], v[98:101], off offset:64
	global_store_dwordx4 v[192:193], v[102:105], off offset:80
.Lpu0_1:
	s_or_b64 exec, exec, s[28:29]
	s_waitcnt vmcnt(4)
	v_mfma_f32_32x32x16_bf16 v[2:17], v[106:109], v[82:85], v[2:17]
	v_mfma_f32_32x32x16_bf16 v[18:33], v[106:109], v[86:89], v[18:33]
	v_mfma_f32_32x32x16_bf16 v[34:49], v[106:109], v[90:93], v[34:49]
	v_mfma_f32_32x32x16_bf16 v[50:65], v[106:109], v[94:97], v[50:65]
	global_load_dwordx4 v[82:85], v[144:145], off offset:1536
	global_load_dwordx4 v[86:89], v[146:147], off offset:1536
	global_load_dwordx4 v[90:93], v[148:149], off offset:1536
	global_load_dwordx4 v[94:97], v[150:151], off offset:1536
	s_waitcnt lgkmcnt(7)
	v_lshlrev_b32_e32 v98, 16, v222
	v_and_b32_e32 v99, 0xffff0000, v222
	v_lshlrev_b32_e32 v100, 16, v223
	v_and_b32_e32 v101, 0xffff0000, v223
	v_lshlrev_b32_e32 v102, 16, v224
	v_and_b32_e32 v103, 0xffff0000, v224
	v_lshlrev_b32_e32 v104, 16, v225
	v_and_b32_e32 v105, 0xffff0000, v225
	v_mov_b64_e32 v[106:107], v[98:99]
	v_mov_b64_e32 v[108:109], v[100:101]
	v_mov_b64_e32 v[218:219], v[102:103]
	v_mov_b64_e32 v[220:221], v[104:105]
	ds_read_b128 v[222:225], v163 offset:1968
	s_waitcnt lgkmcnt(7)
	v_dot2c_f32_bf16 v106, s50, v226
	v_dot2c_f32_bf16 v107, s51, v226
	v_dot2c_f32_bf16 v108, s50, v227
	v_dot2c_f32_bf16 v109, s51, v227
	v_dot2c_f32_bf16 v218, s50, v228
	v_dot2c_f32_bf16 v219, s51, v228
	v_dot2c_f32_bf16 v220, s50, v229
	v_dot2c_f32_bf16 v221, s51, v229
	ds_read_b128 v[226:229], v163 offset:1696
	s_waitcnt lgkmcnt(7)
	v_dot2c_f32_bf16 v106, s50, v230
	v_dot2c_f32_bf16 v107, s51, v230
	v_dot2c_f32_bf16 v108, s50, v231
	v_dot2c_f32_bf16 v109, s51, v231
	v_dot2c_f32_bf16 v218, s50, v232
	v_dot2c_f32_bf16 v219, s51, v232
	v_dot2c_f32_bf16 v220, s50, v233
	v_dot2c_f32_bf16 v221, s51, v233
	ds_read_b128 v[230:233], v163 offset:1424
	s_waitcnt lgkmcnt(7)
	v_dot2c_f32_bf16 v106, s50, v234
	v_dot2c_f32_bf16 v107, s51, v234
	v_dot2c_f32_bf16 v108, s50, v235
	v_dot2c_f32_bf16 v109, s51, v235
	v_dot2c_f32_bf16 v218, s50, v236
	v_dot2c_f32_bf16 v219, s51, v236
	v_dot2c_f32_bf16 v220, s50, v237
	v_dot2c_f32_bf16 v221, s51, v237
	ds_read_b128 v[234:237], v163 offset:1152
	s_waitcnt lgkmcnt(7)
	v_dot2c_f32_bf16 v106, s50, v238
	v_dot2c_f32_bf16 v107, s51, v238
	v_dot2c_f32_bf16 v108, s50, v239
	v_dot2c_f32_bf16 v109, s51, v239
	v_dot2c_f32_bf16 v218, s50, v240
	v_dot2c_f32_bf16 v219, s51, v240
	v_dot2c_f32_bf16 v220, s50, v241
	v_dot2c_f32_bf16 v221, s51, v241
	ds_read_b128 v[238:241], v163 offset:880
	s_waitcnt lgkmcnt(7)
	v_dot2c_f32_bf16 v106, s50, v242
	v_dot2c_f32_bf16 v107, s51, v242
	v_dot2c_f32_bf16 v108, s50, v243
	v_dot2c_f32_bf16 v109, s51, v243
	v_dot2c_f32_bf16 v218, s50, v244
	v_dot2c_f32_bf16 v219, s51, v244
	v_dot2c_f32_bf16 v220, s50, v245
	v_dot2c_f32_bf16 v221, s51, v245
	ds_read_b128 v[242:245], v163 offset:608
	s_waitcnt lgkmcnt(7)
	v_dot2c_f32_bf16 v106, s50, v248
	v_dot2c_f32_bf16 v107, s51, v248
	v_dot2c_f32_bf16 v108, s50, v249
	v_dot2c_f32_bf16 v109, s51, v249
	v_dot2c_f32_bf16 v218, s50, v250
	v_dot2c_f32_bf16 v219, s51, v250
	v_dot2c_f32_bf16 v220, s50, v251
	v_dot2c_f32_bf16 v221, s51, v251
	ds_read_b128 v[248:251], v163 offset:336
	s_waitcnt lgkmcnt(7)
	v_dot2c_f32_bf16 v106, s50, v252
	v_dot2c_f32_bf16 v107, s51, v252
	v_dot2c_f32_bf16 v108, s50, v253
	v_dot2c_f32_bf16 v109, s51, v253
	v_dot2c_f32_bf16 v218, s50, v254
	v_dot2c_f32_bf16 v219, s51, v254
	v_dot2c_f32_bf16 v220, s50, v255
	v_dot2c_f32_bf16 v221, s51, v255
	ds_read_b128 v[252:255], v163 offset:64
	s_waitcnt lgkmcnt(7)
	v_dot2c_f32_bf16 v106, s50, v222
	v_dot2c_f32_bf16 v107, s51, v222
	v_dot2c_f32_bf16 v108, s50, v223
	v_dot2c_f32_bf16 v109, s51, v223
	v_dot2c_f32_bf16 v218, s50, v224
	v_dot2c_f32_bf16 v219, s51, v224
	v_dot2c_f32_bf16 v220, s50, v225
	v_dot2c_f32_bf16 v221, s51, v225
	ds_read_b128 v[222:225], v163 offset:4176
	s_waitcnt lgkmcnt(7)
	v_dot2c_f32_bf16 v106, s50, v226
	v_dot2c_f32_bf16 v107, s51, v226
	v_dot2c_f32_bf16 v108, s50, v227
	v_dot2c_f32_bf16 v109, s51, v227
	v_dot2c_f32_bf16 v218, s50, v228
	v_dot2c_f32_bf16 v219, s51, v228
	v_dot2c_f32_bf16 v220, s50, v229
	v_dot2c_f32_bf16 v221, s51, v229
	ds_read_b128 v[226:229], v163 offset:3904
	s_waitcnt lgkmcnt(7)
	v_dot2c_f32_bf16 v106, s50, v230
	v_dot2c_f32_bf16 v107, s51, v230
	v_dot2c_f32_bf16 v108, s50, v231
	v_dot2c_f32_bf16 v109, s51, v231
	v_dot2c_f32_bf16 v218, s50, v232
	v_dot2c_f32_bf16 v219, s51, v232
	v_dot2c_f32_bf16 v220, s50, v233
	v_dot2c_f32_bf16 v221, s51, v233
	ds_read_b128 v[230:233], v163 offset:3632
	s_waitcnt lgkmcnt(7)
	v_dot2c_f32_bf16 v106, s50, v234
	v_dot2c_f32_bf16 v107, s51, v234
	v_dot2c_f32_bf16 v108, s50, v235
	v_dot2c_f32_bf16 v109, s51, v235
	v_dot2c_f32_bf16 v218, s50, v236
	v_dot2c_f32_bf16 v219, s51, v236
	v_dot2c_f32_bf16 v220, s50, v237
	v_dot2c_f32_bf16 v221, s51, v237
	ds_read_b128 v[234:237], v163 offset:3360
	s_waitcnt lgkmcnt(7)
	v_dot2c_f32_bf16 v106, s50, v238
	v_dot2c_f32_bf16 v107, s51, v238
	v_dot2c_f32_bf16 v108, s50, v239
	v_dot2c_f32_bf16 v109, s51, v239
	v_dot2c_f32_bf16 v218, s50, v240
	v_dot2c_f32_bf16 v219, s51, v240
	v_dot2c_f32_bf16 v220, s50, v241
	v_dot2c_f32_bf16 v221, s51, v241
	ds_read_b128 v[238:241], v163 offset:3088
	s_waitcnt lgkmcnt(7)
	v_dot2c_f32_bf16 v106, s50, v242
	v_dot2c_f32_bf16 v107, s51, v242
	v_dot2c_f32_bf16 v108, s50, v243
	v_dot2c_f32_bf16 v109, s51, v243
	v_dot2c_f32_bf16 v218, s50, v244
	v_dot2c_f32_bf16 v219, s51, v244
	v_dot2c_f32_bf16 v220, s50, v245
	v_dot2c_f32_bf16 v221, s51, v245
	ds_read_b128 v[242:245], v163 offset:2816
	s_waitcnt lgkmcnt(7)
	v_dot2c_f32_bf16 v106, s50, v248
	v_dot2c_f32_bf16 v107, s51, v248
	v_dot2c_f32_bf16 v108, s50, v249
	v_dot2c_f32_bf16 v109, s51, v249
	v_dot2c_f32_bf16 v218, s50, v250
	v_dot2c_f32_bf16 v219, s51, v250
	v_dot2c_f32_bf16 v220, s50, v251
	v_dot2c_f32_bf16 v221, s51, v251
	ds_read_b128 v[248:251], v163 offset:2544
	s_waitcnt lgkmcnt(7)
	v_dot2c_f32_bf16 v106, s50, v252
	v_dot2c_f32_bf16 v107, s51, v252
	v_dot2c_f32_bf16 v108, s50, v253
	v_dot2c_f32_bf16 v109, s51, v253
	v_dot2c_f32_bf16 v218, s50, v254
	v_dot2c_f32_bf16 v219, s51, v254
	v_dot2c_f32_bf16 v220, s50, v255
	v_dot2c_f32_bf16 v221, s51, v255
	ds_read_b128 v[252:255], v163 offset:2272
	v_fma_f32 v106, v159, v106, -v98
	v_fma_f32 v107, v159, v107, -v99
	v_fma_f32 v108, v159, v108, -v100
	v_fma_f32 v109, v159, v109, -v101
	v_fma_f32 v218, v159, v218, -v102
	v_fma_f32 v219, v159, v219, -v103
	v_fma_f32 v220, v159, v220, -v104
	v_fma_f32 v221, v159, v221, -v105
	v_cvt_pk_bf16_f32 v106, v106, v107
	v_cvt_pk_bf16_f32 v107, v108, v109
	v_cvt_pk_bf16_f32 v108, v218, v219
	v_cvt_pk_bf16_f32 v109, v220, v221
	s_and_saveexec_b64 s[28:29], s[6:7]
	s_cbranch_execz .Lpu0_2
	global_store_dwordx4 v[192:193], v[98:101], off offset:128
	global_store_dwordx4 v[192:193], v[102:105], off offset:144
.Lpu0_2:
	s_or_b64 exec, exec, s[28:29]
	s_waitcnt vmcnt(4)
	v_mfma_f32_32x32x16_bf16 v[2:17], v[106:109], v[70:73], v[2:17]
	v_mfma_f32_32x32x16_bf16 v[18:33], v[106:109], v[74:77], v[18:33]
	v_mfma_f32_32x32x16_bf16 v[34:49], v[106:109], v[78:81], v[34:49]
	v_mfma_f32_32x32x16_bf16 v[50:65], v[106:109], v[66:69], v[50:65]
	global_load_dwordx4 v[70:73], v[144:145], off offset:2048
	global_load_dwordx4 v[74:77], v[146:147], off offset:2048
	global_load_dwordx4 v[78:81], v[148:149], off offset:2048
	global_load_dwordx4 v[66:69], v[150:151], off offset:2048
	s_waitcnt lgkmcnt(7)
	v_lshlrev_b32_e32 v98, 16, v222
	v_and_b32_e32 v99, 0xffff0000, v222
	v_lshlrev_b32_e32 v100, 16, v223
	v_and_b32_e32 v101, 0xffff0000, v223
	v_lshlrev_b32_e32 v102, 16, v224
	v_and_b32_e32 v103, 0xffff0000, v224
	v_lshlrev_b32_e32 v104, 16, v225
	v_and_b32_e32 v105, 0xffff0000, v225
	v_mov_b64_e32 v[106:107], v[98:99]
	v_mov_b64_e32 v[108:109], v[100:101]
	v_mov_b64_e32 v[218:219], v[102:103]
	v_mov_b64_e32 v[220:221], v[104:105]
	ds_read_b128 v[222:225], v163 offset:2000
	s_waitcnt lgkmcnt(7)
	v_dot2c_f32_bf16 v106, s50, v226
	v_dot2c_f32_bf16 v107, s51, v226
	v_dot2c_f32_bf16 v108, s50, v227
	v_dot2c_f32_bf16 v109, s51, v227
	v_dot2c_f32_bf16 v218, s50, v228
	v_dot2c_f32_bf16 v219, s51, v228
	v_dot2c_f32_bf16 v220, s50, v229
	v_dot2c_f32_bf16 v221, s51, v229
	ds_read_b128 v[226:229], v163 offset:1728
	s_waitcnt lgkmcnt(7)
	v_dot2c_f32_bf16 v106, s50, v230
	v_dot2c_f32_bf16 v107, s51, v230
	v_dot2c_f32_bf16 v108, s50, v231
	v_dot2c_f32_bf16 v109, s51, v231
	v_dot2c_f32_bf16 v218, s50, v232
	v_dot2c_f32_bf16 v219, s51, v232
	v_dot2c_f32_bf16 v220, s50, v233
	v_dot2c_f32_bf16 v221, s51, v233
	ds_read_b128 v[230:233], v163 offset:1456
	s_waitcnt lgkmcnt(7)
	v_dot2c_f32_bf16 v106, s50, v234
	v_dot2c_f32_bf16 v107, s51, v234
	v_dot2c_f32_bf16 v108, s50, v235
	v_dot2c_f32_bf16 v109, s51, v235
	v_dot2c_f32_bf16 v218, s50, v236
	v_dot2c_f32_bf16 v219, s51, v236
	v_dot2c_f32_bf16 v220, s50, v237
	v_dot2c_f32_bf16 v221, s51, v237
	ds_read_b128 v[234:237], v163 offset:1184
	s_waitcnt lgkmcnt(7)
	v_dot2c_f32_bf16 v106, s50, v238
	v_dot2c_f32_bf16 v107, s51, v238
	v_dot2c_f32_bf16 v108, s50, v239
	v_dot2c_f32_bf16 v109, s51, v239
	v_dot2c_f32_bf16 v218, s50, v240
	v_dot2c_f32_bf16 v219, s51, v240
	v_dot2c_f32_bf16 v220, s50, v241
	v_dot2c_f32_bf16 v221, s51, v241
	ds_read_b128 v[238:241], v163 offset:912
	s_waitcnt lgkmcnt(7)
	v_dot2c_f32_bf16 v106, s50, v242
	v_dot2c_f32_bf16 v107, s51, v242
	v_dot2c_f32_bf16 v108, s50, v243
	v_dot2c_f32_bf16 v109, s51, v243
	v_dot2c_f32_bf16 v218, s50, v244
	v_dot2c_f32_bf16 v219, s51, v244
	v_dot2c_f32_bf16 v220, s50, v245
	v_dot2c_f32_bf16 v221, s51, v245
	ds_read_b128 v[242:245], v163 offset:640
	s_waitcnt lgkmcnt(7)
	v_dot2c_f32_bf16 v106, s50, v248
	v_dot2c_f32_bf16 v107, s51, v248
	v_dot2c_f32_bf16 v108, s50, v249
	v_dot2c_f32_bf16 v109, s51, v249
	v_dot2c_f32_bf16 v218, s50, v250
	v_dot2c_f32_bf16 v219, s51, v250
	v_dot2c_f32_bf16 v220, s50, v251
	v_dot2c_f32_bf16 v221, s51, v251
	ds_read_b128 v[248:251], v163 offset:368
	s_waitcnt lgkmcnt(7)
	v_dot2c_f32_bf16 v106, s50, v252
	v_dot2c_f32_bf16 v107, s51, v252
	v_dot2c_f32_bf16 v108, s50, v253
	v_dot2c_f32_bf16 v109, s51, v253
	v_dot2c_f32_bf16 v218, s50, v254
	v_dot2c_f32_bf16 v219, s51, v254
	v_dot2c_f32_bf16 v220, s50, v255
	v_dot2c_f32_bf16 v221, s51, v255
	ds_read_b128 v[252:255], v163 offset:96
	s_waitcnt lgkmcnt(7)
	v_dot2c_f32_bf16 v106, s50, v222
	v_dot2c_f32_bf16 v107, s51, v222
	v_dot2c_f32_bf16 v108, s50, v223
	v_dot2c_f32_bf16 v109, s51, v223
	v_dot2c_f32_bf16 v218, s50, v224
	v_dot2c_f32_bf16 v219, s51, v224
	v_dot2c_f32_bf16 v220, s50, v225
	v_dot2c_f32_bf16 v221, s51, v225
	ds_read_b128 v[222:225], v163 offset:4208
	s_waitcnt lgkmcnt(7)
	v_dot2c_f32_bf16 v106, s50, v226
	v_dot2c_f32_bf16 v107, s51, v226
	v_dot2c_f32_bf16 v108, s50, v227
	v_dot2c_f32_bf16 v109, s51, v227
	v_dot2c_f32_bf16 v218, s50, v228
	v_dot2c_f32_bf16 v219, s51, v228
	v_dot2c_f32_bf16 v220, s50, v229
	v_dot2c_f32_bf16 v221, s51, v229
	ds_read_b128 v[226:229], v163 offset:3936
	s_waitcnt lgkmcnt(7)
	v_dot2c_f32_bf16 v106, s50, v230
	v_dot2c_f32_bf16 v107, s51, v230
	v_dot2c_f32_bf16 v108, s50, v231
	v_dot2c_f32_bf16 v109, s51, v231
	v_dot2c_f32_bf16 v218, s50, v232
	v_dot2c_f32_bf16 v219, s51, v232
	v_dot2c_f32_bf16 v220, s50, v233
	v_dot2c_f32_bf16 v221, s51, v233
	ds_read_b128 v[230:233], v163 offset:3664
	s_waitcnt lgkmcnt(7)
	v_dot2c_f32_bf16 v106, s50, v234
	v_dot2c_f32_bf16 v107, s51, v234
	v_dot2c_f32_bf16 v108, s50, v235
	v_dot2c_f32_bf16 v109, s51, v235
	v_dot2c_f32_bf16 v218, s50, v236
	v_dot2c_f32_bf16 v219, s51, v236
	v_dot2c_f32_bf16 v220, s50, v237
	v_dot2c_f32_bf16 v221, s51, v237
	ds_read_b128 v[234:237], v163 offset:3392
	s_waitcnt lgkmcnt(7)
	v_dot2c_f32_bf16 v106, s50, v238
	v_dot2c_f32_bf16 v107, s51, v238
	v_dot2c_f32_bf16 v108, s50, v239
	v_dot2c_f32_bf16 v109, s51, v239
	v_dot2c_f32_bf16 v218, s50, v240
	v_dot2c_f32_bf16 v219, s51, v240
	v_dot2c_f32_bf16 v220, s50, v241
	v_dot2c_f32_bf16 v221, s51, v241
	ds_read_b128 v[238:241], v163 offset:3120
	s_waitcnt lgkmcnt(7)
	v_dot2c_f32_bf16 v106, s50, v242
	v_dot2c_f32_bf16 v107, s51, v242
	v_dot2c_f32_bf16 v108, s50, v243
	v_dot2c_f32_bf16 v109, s51, v243
	v_dot2c_f32_bf16 v218, s50, v244
	v_dot2c_f32_bf16 v219, s51, v244
	v_dot2c_f32_bf16 v220, s50, v245
	v_dot2c_f32_bf16 v221, s51, v245
	ds_read_b128 v[242:245], v163 offset:2848
	s_waitcnt lgkmcnt(7)
	v_dot2c_f32_bf16 v106, s50, v248
	v_dot2c_f32_bf16 v107, s51, v248
	v_dot2c_f32_bf16 v108, s50, v249
	v_dot2c_f32_bf16 v109, s51, v249
	v_dot2c_f32_bf16 v218, s50, v250
	v_dot2c_f32_bf16 v219, s51, v250
	v_dot2c_f32_bf16 v220, s50, v251
	v_dot2c_f32_bf16 v221, s51, v251
	ds_read_b128 v[248:251], v163 offset:2576
	s_waitcnt lgkmcnt(7)
	v_dot2c_f32_bf16 v106, s50, v252
	v_dot2c_f32_bf16 v107, s51, v252
	v_dot2c_f32_bf16 v108, s50, v253
	v_dot2c_f32_bf16 v109, s51, v253
	v_dot2c_f32_bf16 v218, s50, v254
	v_dot2c_f32_bf16 v219, s51, v254
	v_dot2c_f32_bf16 v220, s50, v255
	v_dot2c_f32_bf16 v221, s51, v255
	ds_read_b128 v[252:255], v163 offset:2304
	v_fma_f32 v106, v159, v106, -v98
	v_fma_f32 v107, v159, v107, -v99
	v_fma_f32 v108, v159, v108, -v100
	v_fma_f32 v109, v159, v109, -v101
	v_fma_f32 v218, v159, v218, -v102
	v_fma_f32 v219, v159, v219, -v103
	v_fma_f32 v220, v159, v220, -v104
	v_fma_f32 v221, v159, v221, -v105
	v_cvt_pk_bf16_f32 v106, v106, v107
	v_cvt_pk_bf16_f32 v107, v108, v109
	v_cvt_pk_bf16_f32 v108, v218, v219
	v_cvt_pk_bf16_f32 v109, v220, v221
	s_and_saveexec_b64 s[28:29], s[6:7]
	s_cbranch_execz .Lpu0_3
	global_store_dwordx4 v[192:193], v[98:101], off offset:192
	global_store_dwordx4 v[192:193], v[102:105], off offset:208
.Lpu0_3:
	s_or_b64 exec, exec, s[28:29]
	s_waitcnt vmcnt(4)
	v_mfma_f32_32x32x16_bf16 v[2:17], v[106:109], v[82:85], v[2:17]
	v_mfma_f32_32x32x16_bf16 v[18:33], v[106:109], v[86:89], v[18:33]
	v_mfma_f32_32x32x16_bf16 v[34:49], v[106:109], v[90:93], v[34:49]
	v_mfma_f32_32x32x16_bf16 v[50:65], v[106:109], v[94:97], v[50:65]
	global_load_dwordx4 v[82:85], v[144:145], off offset:2560
	global_load_dwordx4 v[86:89], v[146:147], off offset:2560
	global_load_dwordx4 v[90:93], v[148:149], off offset:2560
	global_load_dwordx4 v[94:97], v[150:151], off offset:2560
	s_waitcnt lgkmcnt(7)
	v_lshlrev_b32_e32 v98, 16, v222
	v_and_b32_e32 v99, 0xffff0000, v222
	v_lshlrev_b32_e32 v100, 16, v223
	v_and_b32_e32 v101, 0xffff0000, v223
	v_lshlrev_b32_e32 v102, 16, v224
	v_and_b32_e32 v103, 0xffff0000, v224
	v_lshlrev_b32_e32 v104, 16, v225
	v_and_b32_e32 v105, 0xffff0000, v225
	v_mov_b64_e32 v[106:107], v[98:99]
	v_mov_b64_e32 v[108:109], v[100:101]
	v_mov_b64_e32 v[218:219], v[102:103]
	v_mov_b64_e32 v[220:221], v[104:105]
	ds_read_b128 v[222:225], v163 offset:2032
	s_waitcnt lgkmcnt(7)
	v_dot2c_f32_bf16 v106, s50, v226
	v_dot2c_f32_bf16 v107, s51, v226
	v_dot2c_f32_bf16 v108, s50, v227
	v_dot2c_f32_bf16 v109, s51, v227
	v_dot2c_f32_bf16 v218, s50, v228
	v_dot2c_f32_bf16 v219, s51, v228
	v_dot2c_f32_bf16 v220, s50, v229
	v_dot2c_f32_bf16 v221, s51, v229
	ds_read_b128 v[226:229], v163 offset:1760
	s_waitcnt lgkmcnt(7)
	v_dot2c_f32_bf16 v106, s50, v230
	v_dot2c_f32_bf16 v107, s51, v230
	v_dot2c_f32_bf16 v108, s50, v231
	v_dot2c_f32_bf16 v109, s51, v231
	v_dot2c_f32_bf16 v218, s50, v232
	v_dot2c_f32_bf16 v219, s51, v232
	v_dot2c_f32_bf16 v220, s50, v233
	v_dot2c_f32_bf16 v221, s51, v233
	ds_read_b128 v[230:233], v163 offset:1488
	s_waitcnt lgkmcnt(7)
	v_dot2c_f32_bf16 v106, s50, v234
	v_dot2c_f32_bf16 v107, s51, v234
	v_dot2c_f32_bf16 v108, s50, v235
	v_dot2c_f32_bf16 v109, s51, v235
	v_dot2c_f32_bf16 v218, s50, v236
	v_dot2c_f32_bf16 v219, s51, v236
	v_dot2c_f32_bf16 v220, s50, v237
	v_dot2c_f32_bf16 v221, s51, v237
	ds_read_b128 v[234:237], v163 offset:1216
	s_waitcnt lgkmcnt(7)
	v_dot2c_f32_bf16 v106, s50, v238
	v_dot2c_f32_bf16 v107, s51, v238
	v_dot2c_f32_bf16 v108, s50, v239
	v_dot2c_f32_bf16 v109, s51, v239
	v_dot2c_f32_bf16 v218, s50, v240
	v_dot2c_f32_bf16 v219, s51, v240
	v_dot2c_f32_bf16 v220, s50, v241
	v_dot2c_f32_bf16 v221, s51, v241
	ds_read_b128 v[238:241], v163 offset:944
	s_waitcnt lgkmcnt(7)
	v_dot2c_f32_bf16 v106, s50, v242
	v_dot2c_f32_bf16 v107, s51, v242
	v_dot2c_f32_bf16 v108, s50, v243
	v_dot2c_f32_bf16 v109, s51, v243
	v_dot2c_f32_bf16 v218, s50, v244
	v_dot2c_f32_bf16 v219, s51, v244
	v_dot2c_f32_bf16 v220, s50, v245
	v_dot2c_f32_bf16 v221, s51, v245
	ds_read_b128 v[242:245], v163 offset:672
	s_waitcnt lgkmcnt(7)
	v_dot2c_f32_bf16 v106, s50, v248
	v_dot2c_f32_bf16 v107, s51, v248
	v_dot2c_f32_bf16 v108, s50, v249
	v_dot2c_f32_bf16 v109, s51, v249
	v_dot2c_f32_bf16 v218, s50, v250
	v_dot2c_f32_bf16 v219, s51, v250
	v_dot2c_f32_bf16 v220, s50, v251
	v_dot2c_f32_bf16 v221, s51, v251
	ds_read_b128 v[248:251], v163 offset:400
	s_waitcnt lgkmcnt(7)
	v_dot2c_f32_bf16 v106, s50, v252
	v_dot2c_f32_bf16 v107, s51, v252
	v_dot2c_f32_bf16 v108, s50, v253
	v_dot2c_f32_bf16 v109, s51, v253
	v_dot2c_f32_bf16 v218, s50, v254
	v_dot2c_f32_bf16 v219, s51, v254
	v_dot2c_f32_bf16 v220, s50, v255
	v_dot2c_f32_bf16 v221, s51, v255
	ds_read_b128 v[252:255], v163 offset:128
	s_waitcnt lgkmcnt(7)
	v_dot2c_f32_bf16 v106, s50, v222
	v_dot2c_f32_bf16 v107, s51, v222
	v_dot2c_f32_bf16 v108, s50, v223
	v_dot2c_f32_bf16 v109, s51, v223
	v_dot2c_f32_bf16 v218, s50, v224
	v_dot2c_f32_bf16 v219, s51, v224
	v_dot2c_f32_bf16 v220, s50, v225
	v_dot2c_f32_bf16 v221, s51, v225
	ds_read_b128 v[222:225], v163 offset:4240
	s_waitcnt lgkmcnt(7)
	v_dot2c_f32_bf16 v106, s50, v226
	v_dot2c_f32_bf16 v107, s51, v226
	v_dot2c_f32_bf16 v108, s50, v227
	v_dot2c_f32_bf16 v109, s51, v227
	v_dot2c_f32_bf16 v218, s50, v228
	v_dot2c_f32_bf16 v219, s51, v228
	v_dot2c_f32_bf16 v220, s50, v229
	v_dot2c_f32_bf16 v221, s51, v229
	ds_read_b128 v[226:229], v163 offset:3968
	s_waitcnt lgkmcnt(7)
	v_dot2c_f32_bf16 v106, s50, v230
	v_dot2c_f32_bf16 v107, s51, v230
	v_dot2c_f32_bf16 v108, s50, v231
	v_dot2c_f32_bf16 v109, s51, v231
	v_dot2c_f32_bf16 v218, s50, v232
	v_dot2c_f32_bf16 v219, s51, v232
	v_dot2c_f32_bf16 v220, s50, v233
	v_dot2c_f32_bf16 v221, s51, v233
	ds_read_b128 v[230:233], v163 offset:3696
	s_waitcnt lgkmcnt(7)
	v_dot2c_f32_bf16 v106, s50, v234
	v_dot2c_f32_bf16 v107, s51, v234
	v_dot2c_f32_bf16 v108, s50, v235
	v_dot2c_f32_bf16 v109, s51, v235
	v_dot2c_f32_bf16 v218, s50, v236
	v_dot2c_f32_bf16 v219, s51, v236
	v_dot2c_f32_bf16 v220, s50, v237
	v_dot2c_f32_bf16 v221, s51, v237
	ds_read_b128 v[234:237], v163 offset:3424
	s_waitcnt lgkmcnt(7)
	v_dot2c_f32_bf16 v106, s50, v238
	v_dot2c_f32_bf16 v107, s51, v238
	v_dot2c_f32_bf16 v108, s50, v239
	v_dot2c_f32_bf16 v109, s51, v239
	v_dot2c_f32_bf16 v218, s50, v240
	v_dot2c_f32_bf16 v219, s51, v240
	v_dot2c_f32_bf16 v220, s50, v241
	v_dot2c_f32_bf16 v221, s51, v241
	ds_read_b128 v[238:241], v163 offset:3152
	s_waitcnt lgkmcnt(7)
	v_dot2c_f32_bf16 v106, s50, v242
	v_dot2c_f32_bf16 v107, s51, v242
	v_dot2c_f32_bf16 v108, s50, v243
	v_dot2c_f32_bf16 v109, s51, v243
	v_dot2c_f32_bf16 v218, s50, v244
	v_dot2c_f32_bf16 v219, s51, v244
	v_dot2c_f32_bf16 v220, s50, v245
	v_dot2c_f32_bf16 v221, s51, v245
	ds_read_b128 v[242:245], v163 offset:2880
	s_waitcnt lgkmcnt(7)
	v_dot2c_f32_bf16 v106, s50, v248
	v_dot2c_f32_bf16 v107, s51, v248
	v_dot2c_f32_bf16 v108, s50, v249
	v_dot2c_f32_bf16 v109, s51, v249
	v_dot2c_f32_bf16 v218, s50, v250
	v_dot2c_f32_bf16 v219, s51, v250
	v_dot2c_f32_bf16 v220, s50, v251
	v_dot2c_f32_bf16 v221, s51, v251
	ds_read_b128 v[248:251], v163 offset:2608
	s_waitcnt lgkmcnt(7)
	v_dot2c_f32_bf16 v106, s50, v252
	v_dot2c_f32_bf16 v107, s51, v252
	v_dot2c_f32_bf16 v108, s50, v253
	v_dot2c_f32_bf16 v109, s51, v253
	v_dot2c_f32_bf16 v218, s50, v254
	v_dot2c_f32_bf16 v219, s51, v254
	v_dot2c_f32_bf16 v220, s50, v255
	v_dot2c_f32_bf16 v221, s51, v255
	ds_read_b128 v[252:255], v163 offset:2336
	v_fma_f32 v106, v159, v106, -v98
	v_fma_f32 v107, v159, v107, -v99
	v_fma_f32 v108, v159, v108, -v100
	v_fma_f32 v109, v159, v109, -v101
	v_fma_f32 v218, v159, v218, -v102
	v_fma_f32 v219, v159, v219, -v103
	v_fma_f32 v220, v159, v220, -v104
	v_fma_f32 v221, v159, v221, -v105
	v_cvt_pk_bf16_f32 v106, v106, v107
	v_cvt_pk_bf16_f32 v107, v108, v109
	v_cvt_pk_bf16_f32 v108, v218, v219
	v_cvt_pk_bf16_f32 v109, v220, v221
	s_and_saveexec_b64 s[28:29], s[6:7]
	s_cbranch_execz .Lpu0_4
	global_store_dwordx4 v[192:193], v[98:101], off offset:256
	global_store_dwordx4 v[192:193], v[102:105], off offset:272
.Lpu0_4:
	s_or_b64 exec, exec, s[28:29]
	s_waitcnt vmcnt(4)
	v_mfma_f32_32x32x16_bf16 v[2:17], v[106:109], v[70:73], v[2:17]
	v_mfma_f32_32x32x16_bf16 v[18:33], v[106:109], v[74:77], v[18:33]
	v_mfma_f32_32x32x16_bf16 v[34:49], v[106:109], v[78:81], v[34:49]
	v_mfma_f32_32x32x16_bf16 v[50:65], v[106:109], v[66:69], v[50:65]
	global_load_dwordx4 v[70:73], v[144:145], off offset:3072
	global_load_dwordx4 v[74:77], v[146:147], off offset:3072
	global_load_dwordx4 v[78:81], v[148:149], off offset:3072
	global_load_dwordx4 v[66:69], v[150:151], off offset:3072
	s_waitcnt lgkmcnt(7)
	v_lshlrev_b32_e32 v98, 16, v222
	v_and_b32_e32 v99, 0xffff0000, v222
	v_lshlrev_b32_e32 v100, 16, v223
	v_and_b32_e32 v101, 0xffff0000, v223
	v_lshlrev_b32_e32 v102, 16, v224
	v_and_b32_e32 v103, 0xffff0000, v224
	v_lshlrev_b32_e32 v104, 16, v225
	v_and_b32_e32 v105, 0xffff0000, v225
	v_mov_b64_e32 v[106:107], v[98:99]
	v_mov_b64_e32 v[108:109], v[100:101]
	v_mov_b64_e32 v[218:219], v[102:103]
	v_mov_b64_e32 v[220:221], v[104:105]
	ds_read_b128 v[222:225], v163 offset:2064
	s_waitcnt lgkmcnt(7)
	v_dot2c_f32_bf16 v106, s50, v226
	v_dot2c_f32_bf16 v107, s51, v226
	v_dot2c_f32_bf16 v108, s50, v227
	v_dot2c_f32_bf16 v109, s51, v227
	v_dot2c_f32_bf16 v218, s50, v228
	v_dot2c_f32_bf16 v219, s51, v228
	v_dot2c_f32_bf16 v220, s50, v229
	v_dot2c_f32_bf16 v221, s51, v229
	ds_read_b128 v[226:229], v163 offset:1792
	s_waitcnt lgkmcnt(7)
	v_dot2c_f32_bf16 v106, s50, v230
	v_dot2c_f32_bf16 v107, s51, v230
	v_dot2c_f32_bf16 v108, s50, v231
	v_dot2c_f32_bf16 v109, s51, v231
	v_dot2c_f32_bf16 v218, s50, v232
	v_dot2c_f32_bf16 v219, s51, v232
	v_dot2c_f32_bf16 v220, s50, v233
	v_dot2c_f32_bf16 v221, s51, v233
	ds_read_b128 v[230:233], v163 offset:1520
	s_waitcnt lgkmcnt(7)
	v_dot2c_f32_bf16 v106, s50, v234
	v_dot2c_f32_bf16 v107, s51, v234
	v_dot2c_f32_bf16 v108, s50, v235
	v_dot2c_f32_bf16 v109, s51, v235
	v_dot2c_f32_bf16 v218, s50, v236
	v_dot2c_f32_bf16 v219, s51, v236
	v_dot2c_f32_bf16 v220, s50, v237
	v_dot2c_f32_bf16 v221, s51, v237
	ds_read_b128 v[234:237], v163 offset:1248
	s_waitcnt lgkmcnt(7)
	v_dot2c_f32_bf16 v106, s50, v238
	v_dot2c_f32_bf16 v107, s51, v238
	v_dot2c_f32_bf16 v108, s50, v239
	v_dot2c_f32_bf16 v109, s51, v239
	v_dot2c_f32_bf16 v218, s50, v240
	v_dot2c_f32_bf16 v219, s51, v240
	v_dot2c_f32_bf16 v220, s50, v241
	v_dot2c_f32_bf16 v221, s51, v241
	ds_read_b128 v[238:241], v163 offset:976
	s_waitcnt lgkmcnt(7)
	v_dot2c_f32_bf16 v106, s50, v242
	v_dot2c_f32_bf16 v107, s51, v242
	v_dot2c_f32_bf16 v108, s50, v243
	v_dot2c_f32_bf16 v109, s51, v243
	v_dot2c_f32_bf16 v218, s50, v244
	v_dot2c_f32_bf16 v219, s51, v244
	v_dot2c_f32_bf16 v220, s50, v245
	v_dot2c_f32_bf16 v221, s51, v245
	ds_read_b128 v[242:245], v163 offset:704
	s_waitcnt lgkmcnt(7)
	v_dot2c_f32_bf16 v106, s50, v248
	v_dot2c_f32_bf16 v107, s51, v248
	v_dot2c_f32_bf16 v108, s50, v249
	v_dot2c_f32_bf16 v109, s51, v249
	v_dot2c_f32_bf16 v218, s50, v250
	v_dot2c_f32_bf16 v219, s51, v250
	v_dot2c_f32_bf16 v220, s50, v251
	v_dot2c_f32_bf16 v221, s51, v251
	ds_read_b128 v[248:251], v163 offset:432
	s_waitcnt lgkmcnt(7)
	v_dot2c_f32_bf16 v106, s50, v252
	v_dot2c_f32_bf16 v107, s51, v252
	v_dot2c_f32_bf16 v108, s50, v253
	v_dot2c_f32_bf16 v109, s51, v253
	v_dot2c_f32_bf16 v218, s50, v254
	v_dot2c_f32_bf16 v219, s51, v254
	v_dot2c_f32_bf16 v220, s50, v255
	v_dot2c_f32_bf16 v221, s51, v255
	ds_read_b128 v[252:255], v163 offset:160
	s_waitcnt lgkmcnt(7)
	v_dot2c_f32_bf16 v106, s50, v222
	v_dot2c_f32_bf16 v107, s51, v222
	v_dot2c_f32_bf16 v108, s50, v223
	v_dot2c_f32_bf16 v109, s51, v223
	v_dot2c_f32_bf16 v218, s50, v224
	v_dot2c_f32_bf16 v219, s51, v224
	v_dot2c_f32_bf16 v220, s50, v225
	v_dot2c_f32_bf16 v221, s51, v225
	ds_read_b128 v[222:225], v163 offset:4272
	s_waitcnt lgkmcnt(7)
	v_dot2c_f32_bf16 v106, s50, v226
	v_dot2c_f32_bf16 v107, s51, v226
	v_dot2c_f32_bf16 v108, s50, v227
	v_dot2c_f32_bf16 v109, s51, v227
	v_dot2c_f32_bf16 v218, s50, v228
	v_dot2c_f32_bf16 v219, s51, v228
	v_dot2c_f32_bf16 v220, s50, v229
	v_dot2c_f32_bf16 v221, s51, v229
	ds_read_b128 v[226:229], v163 offset:4000
	s_waitcnt lgkmcnt(7)
	v_dot2c_f32_bf16 v106, s50, v230
	v_dot2c_f32_bf16 v107, s51, v230
	v_dot2c_f32_bf16 v108, s50, v231
	v_dot2c_f32_bf16 v109, s51, v231
	v_dot2c_f32_bf16 v218, s50, v232
	v_dot2c_f32_bf16 v219, s51, v232
	v_dot2c_f32_bf16 v220, s50, v233
	v_dot2c_f32_bf16 v221, s51, v233
	ds_read_b128 v[230:233], v163 offset:3728
	s_waitcnt lgkmcnt(7)
	v_dot2c_f32_bf16 v106, s50, v234
	v_dot2c_f32_bf16 v107, s51, v234
	v_dot2c_f32_bf16 v108, s50, v235
	v_dot2c_f32_bf16 v109, s51, v235
	v_dot2c_f32_bf16 v218, s50, v236
	v_dot2c_f32_bf16 v219, s51, v236
	v_dot2c_f32_bf16 v220, s50, v237
	v_dot2c_f32_bf16 v221, s51, v237
	ds_read_b128 v[234:237], v163 offset:3456
	s_waitcnt lgkmcnt(7)
	v_dot2c_f32_bf16 v106, s50, v238
	v_dot2c_f32_bf16 v107, s51, v238
	v_dot2c_f32_bf16 v108, s50, v239
	v_dot2c_f32_bf16 v109, s51, v239
	v_dot2c_f32_bf16 v218, s50, v240
	v_dot2c_f32_bf16 v219, s51, v240
	v_dot2c_f32_bf16 v220, s50, v241
	v_dot2c_f32_bf16 v221, s51, v241
	ds_read_b128 v[238:241], v163 offset:3184
	s_waitcnt lgkmcnt(7)
	v_dot2c_f32_bf16 v106, s50, v242
	v_dot2c_f32_bf16 v107, s51, v242
	v_dot2c_f32_bf16 v108, s50, v243
	v_dot2c_f32_bf16 v109, s51, v243
	v_dot2c_f32_bf16 v218, s50, v244
	v_dot2c_f32_bf16 v219, s51, v244
	v_dot2c_f32_bf16 v220, s50, v245
	v_dot2c_f32_bf16 v221, s51, v245
	ds_read_b128 v[242:245], v163 offset:2912
	s_waitcnt lgkmcnt(7)
	v_dot2c_f32_bf16 v106, s50, v248
	v_dot2c_f32_bf16 v107, s51, v248
	v_dot2c_f32_bf16 v108, s50, v249
	v_dot2c_f32_bf16 v109, s51, v249
	v_dot2c_f32_bf16 v218, s50, v250
	v_dot2c_f32_bf16 v219, s51, v250
	v_dot2c_f32_bf16 v220, s50, v251
	v_dot2c_f32_bf16 v221, s51, v251
	ds_read_b128 v[248:251], v163 offset:2640
	s_waitcnt lgkmcnt(7)
	v_dot2c_f32_bf16 v106, s50, v252
	v_dot2c_f32_bf16 v107, s51, v252
	v_dot2c_f32_bf16 v108, s50, v253
	v_dot2c_f32_bf16 v109, s51, v253
	v_dot2c_f32_bf16 v218, s50, v254
	v_dot2c_f32_bf16 v219, s51, v254
	v_dot2c_f32_bf16 v220, s50, v255
	v_dot2c_f32_bf16 v221, s51, v255
	ds_read_b128 v[252:255], v163 offset:2368
	v_fma_f32 v106, v159, v106, -v98
	v_fma_f32 v107, v159, v107, -v99
	v_fma_f32 v108, v159, v108, -v100
	v_fma_f32 v109, v159, v109, -v101
	v_fma_f32 v218, v159, v218, -v102
	v_fma_f32 v219, v159, v219, -v103
	v_fma_f32 v220, v159, v220, -v104
	v_fma_f32 v221, v159, v221, -v105
	v_cvt_pk_bf16_f32 v106, v106, v107
	v_cvt_pk_bf16_f32 v107, v108, v109
	v_cvt_pk_bf16_f32 v108, v218, v219
	v_cvt_pk_bf16_f32 v109, v220, v221
	s_and_saveexec_b64 s[28:29], s[6:7]
	s_cbranch_execz .Lpu0_5
	global_store_dwordx4 v[192:193], v[98:101], off offset:320
	global_store_dwordx4 v[192:193], v[102:105], off offset:336
.Lpu0_5:
	s_or_b64 exec, exec, s[28:29]
	s_waitcnt vmcnt(4)
	v_mfma_f32_32x32x16_bf16 v[2:17], v[106:109], v[82:85], v[2:17]
	v_mfma_f32_32x32x16_bf16 v[18:33], v[106:109], v[86:89], v[18:33]
	v_mfma_f32_32x32x16_bf16 v[34:49], v[106:109], v[90:93], v[34:49]
	v_mfma_f32_32x32x16_bf16 v[50:65], v[106:109], v[94:97], v[50:65]
	global_load_dwordx4 v[82:85], v[144:145], off offset:3584
	global_load_dwordx4 v[86:89], v[146:147], off offset:3584
	global_load_dwordx4 v[90:93], v[148:149], off offset:3584
	global_load_dwordx4 v[94:97], v[150:151], off offset:3584
	s_waitcnt lgkmcnt(7)
	v_lshlrev_b32_e32 v98, 16, v222
	v_and_b32_e32 v99, 0xffff0000, v222
	v_lshlrev_b32_e32 v100, 16, v223
	v_and_b32_e32 v101, 0xffff0000, v223
	v_lshlrev_b32_e32 v102, 16, v224
	v_and_b32_e32 v103, 0xffff0000, v224
	v_lshlrev_b32_e32 v104, 16, v225
	v_and_b32_e32 v105, 0xffff0000, v225
	v_mov_b64_e32 v[106:107], v[98:99]
	v_mov_b64_e32 v[108:109], v[100:101]
	v_mov_b64_e32 v[218:219], v[102:103]
	v_mov_b64_e32 v[220:221], v[104:105]
	ds_read_b128 v[222:225], v163 offset:2096
	s_waitcnt lgkmcnt(7)
	v_dot2c_f32_bf16 v106, s50, v226
	v_dot2c_f32_bf16 v107, s51, v226
	v_dot2c_f32_bf16 v108, s50, v227
	v_dot2c_f32_bf16 v109, s51, v227
	v_dot2c_f32_bf16 v218, s50, v228
	v_dot2c_f32_bf16 v219, s51, v228
	v_dot2c_f32_bf16 v220, s50, v229
	v_dot2c_f32_bf16 v221, s51, v229
	ds_read_b128 v[226:229], v163 offset:1824
	s_waitcnt lgkmcnt(7)
	v_dot2c_f32_bf16 v106, s50, v230
	v_dot2c_f32_bf16 v107, s51, v230
	v_dot2c_f32_bf16 v108, s50, v231
	v_dot2c_f32_bf16 v109, s51, v231
	v_dot2c_f32_bf16 v218, s50, v232
	v_dot2c_f32_bf16 v219, s51, v232
	v_dot2c_f32_bf16 v220, s50, v233
	v_dot2c_f32_bf16 v221, s51, v233
	ds_read_b128 v[230:233], v163 offset:1552
	s_waitcnt lgkmcnt(7)
	v_dot2c_f32_bf16 v106, s50, v234
	v_dot2c_f32_bf16 v107, s51, v234
	v_dot2c_f32_bf16 v108, s50, v235
	v_dot2c_f32_bf16 v109, s51, v235
	v_dot2c_f32_bf16 v218, s50, v236
	v_dot2c_f32_bf16 v219, s51, v236
	v_dot2c_f32_bf16 v220, s50, v237
	v_dot2c_f32_bf16 v221, s51, v237
	ds_read_b128 v[234:237], v163 offset:1280
	s_waitcnt lgkmcnt(7)
	v_dot2c_f32_bf16 v106, s50, v238
	v_dot2c_f32_bf16 v107, s51, v238
	v_dot2c_f32_bf16 v108, s50, v239
	v_dot2c_f32_bf16 v109, s51, v239
	v_dot2c_f32_bf16 v218, s50, v240
	v_dot2c_f32_bf16 v219, s51, v240
	v_dot2c_f32_bf16 v220, s50, v241
	v_dot2c_f32_bf16 v221, s51, v241
	ds_read_b128 v[238:241], v163 offset:1008
	s_waitcnt lgkmcnt(7)
	v_dot2c_f32_bf16 v106, s50, v242
	v_dot2c_f32_bf16 v107, s51, v242
	v_dot2c_f32_bf16 v108, s50, v243
	v_dot2c_f32_bf16 v109, s51, v243
	v_dot2c_f32_bf16 v218, s50, v244
	v_dot2c_f32_bf16 v219, s51, v244
	v_dot2c_f32_bf16 v220, s50, v245
	v_dot2c_f32_bf16 v221, s51, v245
	ds_read_b128 v[242:245], v163 offset:736
	s_waitcnt lgkmcnt(7)
	v_dot2c_f32_bf16 v106, s50, v248
	v_dot2c_f32_bf16 v107, s51, v248
	v_dot2c_f32_bf16 v108, s50, v249
	v_dot2c_f32_bf16 v109, s51, v249
	v_dot2c_f32_bf16 v218, s50, v250
	v_dot2c_f32_bf16 v219, s51, v250
	v_dot2c_f32_bf16 v220, s50, v251
	v_dot2c_f32_bf16 v221, s51, v251
	ds_read_b128 v[248:251], v163 offset:464
	s_waitcnt lgkmcnt(7)
	v_dot2c_f32_bf16 v106, s50, v252
	v_dot2c_f32_bf16 v107, s51, v252
	v_dot2c_f32_bf16 v108, s50, v253
	v_dot2c_f32_bf16 v109, s51, v253
	v_dot2c_f32_bf16 v218, s50, v254
	v_dot2c_f32_bf16 v219, s51, v254
	v_dot2c_f32_bf16 v220, s50, v255
	v_dot2c_f32_bf16 v221, s51, v255
	ds_read_b128 v[252:255], v163 offset:192
	s_waitcnt lgkmcnt(7)
	v_dot2c_f32_bf16 v106, s50, v222
	v_dot2c_f32_bf16 v107, s51, v222
	v_dot2c_f32_bf16 v108, s50, v223
	v_dot2c_f32_bf16 v109, s51, v223
	v_dot2c_f32_bf16 v218, s50, v224
	v_dot2c_f32_bf16 v219, s51, v224
	v_dot2c_f32_bf16 v220, s50, v225
	v_dot2c_f32_bf16 v221, s51, v225
	ds_read_b128 v[222:225], v163 offset:4304
	s_waitcnt lgkmcnt(7)
	v_dot2c_f32_bf16 v106, s50, v226
	v_dot2c_f32_bf16 v107, s51, v226
	v_dot2c_f32_bf16 v108, s50, v227
	v_dot2c_f32_bf16 v109, s51, v227
	v_dot2c_f32_bf16 v218, s50, v228
	v_dot2c_f32_bf16 v219, s51, v228
	v_dot2c_f32_bf16 v220, s50, v229
	v_dot2c_f32_bf16 v221, s51, v229
	ds_read_b128 v[226:229], v163 offset:4032
	s_waitcnt lgkmcnt(7)
	v_dot2c_f32_bf16 v106, s50, v230
	v_dot2c_f32_bf16 v107, s51, v230
	v_dot2c_f32_bf16 v108, s50, v231
	v_dot2c_f32_bf16 v109, s51, v231
	v_dot2c_f32_bf16 v218, s50, v232
	v_dot2c_f32_bf16 v219, s51, v232
	v_dot2c_f32_bf16 v220, s50, v233
	v_dot2c_f32_bf16 v221, s51, v233
	ds_read_b128 v[230:233], v163 offset:3760
	s_waitcnt lgkmcnt(7)
	v_dot2c_f32_bf16 v106, s50, v234
	v_dot2c_f32_bf16 v107, s51, v234
	v_dot2c_f32_bf16 v108, s50, v235
	v_dot2c_f32_bf16 v109, s51, v235
	v_dot2c_f32_bf16 v218, s50, v236
	v_dot2c_f32_bf16 v219, s51, v236
	v_dot2c_f32_bf16 v220, s50, v237
	v_dot2c_f32_bf16 v221, s51, v237
	ds_read_b128 v[234:237], v163 offset:3488
	s_waitcnt lgkmcnt(7)
	v_dot2c_f32_bf16 v106, s50, v238
	v_dot2c_f32_bf16 v107, s51, v238
	v_dot2c_f32_bf16 v108, s50, v239
	v_dot2c_f32_bf16 v109, s51, v239
	v_dot2c_f32_bf16 v218, s50, v240
	v_dot2c_f32_bf16 v219, s51, v240
	v_dot2c_f32_bf16 v220, s50, v241
	v_dot2c_f32_bf16 v221, s51, v241
	ds_read_b128 v[238:241], v163 offset:3216
	s_waitcnt lgkmcnt(7)
	v_dot2c_f32_bf16 v106, s50, v242
	v_dot2c_f32_bf16 v107, s51, v242
	v_dot2c_f32_bf16 v108, s50, v243
	v_dot2c_f32_bf16 v109, s51, v243
	v_dot2c_f32_bf16 v218, s50, v244
	v_dot2c_f32_bf16 v219, s51, v244
	v_dot2c_f32_bf16 v220, s50, v245
	v_dot2c_f32_bf16 v221, s51, v245
	ds_read_b128 v[242:245], v163 offset:2944
	s_waitcnt lgkmcnt(7)
	v_dot2c_f32_bf16 v106, s50, v248
	v_dot2c_f32_bf16 v107, s51, v248
	v_dot2c_f32_bf16 v108, s50, v249
	v_dot2c_f32_bf16 v109, s51, v249
	v_dot2c_f32_bf16 v218, s50, v250
	v_dot2c_f32_bf16 v219, s51, v250
	v_dot2c_f32_bf16 v220, s50, v251
	v_dot2c_f32_bf16 v221, s51, v251
	ds_read_b128 v[248:251], v163 offset:2672
	s_waitcnt lgkmcnt(7)
	v_dot2c_f32_bf16 v106, s50, v252
	v_dot2c_f32_bf16 v107, s51, v252
	v_dot2c_f32_bf16 v108, s50, v253
	v_dot2c_f32_bf16 v109, s51, v253
	v_dot2c_f32_bf16 v218, s50, v254
	v_dot2c_f32_bf16 v219, s51, v254
	v_dot2c_f32_bf16 v220, s50, v255
	v_dot2c_f32_bf16 v221, s51, v255
	ds_read_b128 v[252:255], v163 offset:2400
	v_fma_f32 v106, v159, v106, -v98
	v_fma_f32 v107, v159, v107, -v99
	v_fma_f32 v108, v159, v108, -v100
	v_fma_f32 v109, v159, v109, -v101
	v_fma_f32 v218, v159, v218, -v102
	v_fma_f32 v219, v159, v219, -v103
	v_fma_f32 v220, v159, v220, -v104
	v_fma_f32 v221, v159, v221, -v105
	v_cvt_pk_bf16_f32 v106, v106, v107
	v_cvt_pk_bf16_f32 v107, v108, v109
	v_cvt_pk_bf16_f32 v108, v218, v219
	v_cvt_pk_bf16_f32 v109, v220, v221
	s_and_saveexec_b64 s[28:29], s[6:7]
	s_cbranch_execz .Lpu0_6
	global_store_dwordx4 v[192:193], v[98:101], off offset:384
	global_store_dwordx4 v[192:193], v[102:105], off offset:400
.Lpu0_6:
	s_or_b64 exec, exec, s[28:29]
	s_waitcnt vmcnt(4)
	v_mfma_f32_32x32x16_bf16 v[2:17], v[106:109], v[70:73], v[2:17]
	v_mfma_f32_32x32x16_bf16 v[18:33], v[106:109], v[74:77], v[18:33]
	v_mfma_f32_32x32x16_bf16 v[34:49], v[106:109], v[78:81], v[34:49]
	v_mfma_f32_32x32x16_bf16 v[50:65], v[106:109], v[66:69], v[50:65]
	s_waitcnt lgkmcnt(7)
	v_lshlrev_b32_e32 v98, 16, v222
	v_and_b32_e32 v99, 0xffff0000, v222
	v_lshlrev_b32_e32 v100, 16, v223
	v_and_b32_e32 v101, 0xffff0000, v223
	v_lshlrev_b32_e32 v102, 16, v224
	v_and_b32_e32 v103, 0xffff0000, v224
	v_lshlrev_b32_e32 v104, 16, v225
	v_and_b32_e32 v105, 0xffff0000, v225
	v_mov_b64_e32 v[106:107], v[98:99]
	v_mov_b64_e32 v[108:109], v[100:101]
	v_mov_b64_e32 v[218:219], v[102:103]
	v_mov_b64_e32 v[220:221], v[104:105]
	ds_read_b128 v[222:225], v163 offset:2128
	s_waitcnt lgkmcnt(7)
	v_dot2c_f32_bf16 v106, s50, v226
	v_dot2c_f32_bf16 v107, s51, v226
	v_dot2c_f32_bf16 v108, s50, v227
	v_dot2c_f32_bf16 v109, s51, v227
	v_dot2c_f32_bf16 v218, s50, v228
	v_dot2c_f32_bf16 v219, s51, v228
	v_dot2c_f32_bf16 v220, s50, v229
	v_dot2c_f32_bf16 v221, s51, v229
	ds_read_b128 v[226:229], v163 offset:1856
	s_waitcnt lgkmcnt(7)
	v_dot2c_f32_bf16 v106, s50, v230
	v_dot2c_f32_bf16 v107, s51, v230
	v_dot2c_f32_bf16 v108, s50, v231
	v_dot2c_f32_bf16 v109, s51, v231
	v_dot2c_f32_bf16 v218, s50, v232
	v_dot2c_f32_bf16 v219, s51, v232
	v_dot2c_f32_bf16 v220, s50, v233
	v_dot2c_f32_bf16 v221, s51, v233
	ds_read_b128 v[230:233], v163 offset:1584
	s_waitcnt lgkmcnt(7)
	v_dot2c_f32_bf16 v106, s50, v234
	v_dot2c_f32_bf16 v107, s51, v234
	v_dot2c_f32_bf16 v108, s50, v235
	v_dot2c_f32_bf16 v109, s51, v235
	v_dot2c_f32_bf16 v218, s50, v236
	v_dot2c_f32_bf16 v219, s51, v236
	v_dot2c_f32_bf16 v220, s50, v237
	v_dot2c_f32_bf16 v221, s51, v237
	ds_read_b128 v[234:237], v163 offset:1312
	s_waitcnt lgkmcnt(7)
	v_dot2c_f32_bf16 v106, s50, v238
	v_dot2c_f32_bf16 v107, s51, v238
	v_dot2c_f32_bf16 v108, s50, v239
	v_dot2c_f32_bf16 v109, s51, v239
	v_dot2c_f32_bf16 v218, s50, v240
	v_dot2c_f32_bf16 v219, s51, v240
	v_dot2c_f32_bf16 v220, s50, v241
	v_dot2c_f32_bf16 v221, s51, v241
	ds_read_b128 v[238:241], v163 offset:1040
	s_waitcnt lgkmcnt(7)
	v_dot2c_f32_bf16 v106, s50, v242
	v_dot2c_f32_bf16 v107, s51, v242
	v_dot2c_f32_bf16 v108, s50, v243
	v_dot2c_f32_bf16 v109, s51, v243
	v_dot2c_f32_bf16 v218, s50, v244
	v_dot2c_f32_bf16 v219, s51, v244
	v_dot2c_f32_bf16 v220, s50, v245
	v_dot2c_f32_bf16 v221, s51, v245
	ds_read_b128 v[242:245], v163 offset:768
	s_waitcnt lgkmcnt(7)
	v_dot2c_f32_bf16 v106, s50, v248
	v_dot2c_f32_bf16 v107, s51, v248
	v_dot2c_f32_bf16 v108, s50, v249
	v_dot2c_f32_bf16 v109, s51, v249
	v_dot2c_f32_bf16 v218, s50, v250
	v_dot2c_f32_bf16 v219, s51, v250
	v_dot2c_f32_bf16 v220, s50, v251
	v_dot2c_f32_bf16 v221, s51, v251
	ds_read_b128 v[248:251], v163 offset:496
	s_waitcnt lgkmcnt(7)
	v_dot2c_f32_bf16 v106, s50, v252
	v_dot2c_f32_bf16 v107, s51, v252
	v_dot2c_f32_bf16 v108, s50, v253
	v_dot2c_f32_bf16 v109, s51, v253
	v_dot2c_f32_bf16 v218, s50, v254
	v_dot2c_f32_bf16 v219, s51, v254
	v_dot2c_f32_bf16 v220, s50, v255
	v_dot2c_f32_bf16 v221, s51, v255
	ds_read_b128 v[252:255], v163 offset:224
	s_waitcnt lgkmcnt(7)
	v_dot2c_f32_bf16 v106, s50, v222
	v_dot2c_f32_bf16 v107, s51, v222
	v_dot2c_f32_bf16 v108, s50, v223
	v_dot2c_f32_bf16 v109, s51, v223
	v_dot2c_f32_bf16 v218, s50, v224
	v_dot2c_f32_bf16 v219, s51, v224
	v_dot2c_f32_bf16 v220, s50, v225
	v_dot2c_f32_bf16 v221, s51, v225
	s_waitcnt lgkmcnt(6)
	v_dot2c_f32_bf16 v106, s50, v226
	v_dot2c_f32_bf16 v107, s51, v226
	v_dot2c_f32_bf16 v108, s50, v227
	v_dot2c_f32_bf16 v109, s51, v227
	v_dot2c_f32_bf16 v218, s50, v228
	v_dot2c_f32_bf16 v219, s51, v228
	v_dot2c_f32_bf16 v220, s50, v229
	v_dot2c_f32_bf16 v221, s51, v229
	s_waitcnt lgkmcnt(5)
	v_dot2c_f32_bf16 v106, s50, v230
	v_dot2c_f32_bf16 v107, s51, v230
	v_dot2c_f32_bf16 v108, s50, v231
	v_dot2c_f32_bf16 v109, s51, v231
	v_dot2c_f32_bf16 v218, s50, v232
	v_dot2c_f32_bf16 v219, s51, v232
	v_dot2c_f32_bf16 v220, s50, v233
	v_dot2c_f32_bf16 v221, s51, v233
	s_waitcnt lgkmcnt(4)
	v_dot2c_f32_bf16 v106, s50, v234
	v_dot2c_f32_bf16 v107, s51, v234
	v_dot2c_f32_bf16 v108, s50, v235
	v_dot2c_f32_bf16 v109, s51, v235
	v_dot2c_f32_bf16 v218, s50, v236
	v_dot2c_f32_bf16 v219, s51, v236
	v_dot2c_f32_bf16 v220, s50, v237
	v_dot2c_f32_bf16 v221, s51, v237
	s_waitcnt lgkmcnt(3)
	v_dot2c_f32_bf16 v106, s50, v238
	v_dot2c_f32_bf16 v107, s51, v238
	v_dot2c_f32_bf16 v108, s50, v239
	v_dot2c_f32_bf16 v109, s51, v239
	v_dot2c_f32_bf16 v218, s50, v240
	v_dot2c_f32_bf16 v219, s51, v240
	v_dot2c_f32_bf16 v220, s50, v241
	v_dot2c_f32_bf16 v221, s51, v241
	s_waitcnt lgkmcnt(2)
	v_dot2c_f32_bf16 v106, s50, v242
	v_dot2c_f32_bf16 v107, s51, v242
	v_dot2c_f32_bf16 v108, s50, v243
	v_dot2c_f32_bf16 v109, s51, v243
	v_dot2c_f32_bf16 v218, s50, v244
	v_dot2c_f32_bf16 v219, s51, v244
	v_dot2c_f32_bf16 v220, s50, v245
	v_dot2c_f32_bf16 v221, s51, v245
	s_waitcnt lgkmcnt(1)
	v_dot2c_f32_bf16 v106, s50, v248
	v_dot2c_f32_bf16 v107, s51, v248
	v_dot2c_f32_bf16 v108, s50, v249
	v_dot2c_f32_bf16 v109, s51, v249
	v_dot2c_f32_bf16 v218, s50, v250
	v_dot2c_f32_bf16 v219, s51, v250
	v_dot2c_f32_bf16 v220, s50, v251
	v_dot2c_f32_bf16 v221, s51, v251
	s_waitcnt lgkmcnt(0)
	v_dot2c_f32_bf16 v106, s50, v252
	v_dot2c_f32_bf16 v107, s51, v252
	v_dot2c_f32_bf16 v108, s50, v253
	v_dot2c_f32_bf16 v109, s51, v253
	v_dot2c_f32_bf16 v218, s50, v254
	v_dot2c_f32_bf16 v219, s51, v254
	v_dot2c_f32_bf16 v220, s50, v255
	v_dot2c_f32_bf16 v221, s51, v255
	v_fma_f32 v106, v159, v106, -v98
	v_fma_f32 v107, v159, v107, -v99
	v_fma_f32 v108, v159, v108, -v100
	v_fma_f32 v109, v159, v109, -v101
	v_fma_f32 v218, v159, v218, -v102
	v_fma_f32 v219, v159, v219, -v103
	v_fma_f32 v220, v159, v220, -v104
	v_fma_f32 v221, v159, v221, -v105
	v_cvt_pk_bf16_f32 v106, v106, v107
	v_cvt_pk_bf16_f32 v107, v108, v109
	v_cvt_pk_bf16_f32 v108, v218, v219
	v_cvt_pk_bf16_f32 v109, v220, v221
	s_and_saveexec_b64 s[28:29], s[6:7]
	s_cbranch_execz .Lpu0_7
	global_store_dwordx4 v[192:193], v[98:101], off offset:448
	global_store_dwordx4 v[192:193], v[102:105], off offset:464
.Lpu0_7:
	s_or_b64 exec, exec, s[28:29]
	s_waitcnt vmcnt(0)
	v_mfma_f32_32x32x16_bf16 v[2:17], v[106:109], v[82:85], v[2:17]
	v_mfma_f32_32x32x16_bf16 v[18:33], v[106:109], v[86:89], v[18:33]
	v_mfma_f32_32x32x16_bf16 v[34:49], v[106:109], v[90:93], v[34:49]
	v_mfma_f32_32x32x16_bf16 v[50:65], v[106:109], v[94:97], v[50:65]
	s_branch .LBB0_338

.LBB0_355:
	s_or_b64 exec, exec, s[6:7]
	s_waitcnt lgkmcnt(0)
	global_load_dwordx4 v[82:85], v[112:113], off offset:512
	global_load_dwordx4 v[86:89], v[114:115], off offset:512
	global_load_dwordx4 v[90:93], v[116:117], off offset:512
	global_load_dwordx4 v[94:97], v[118:119], off offset:512
	global_load_dwordx4 v[222:225], v[112:113], off offset:1024
	global_load_dwordx4 v[226:229], v[114:115], off offset:1024
	global_load_dwordx4 v[230:233], v[116:117], off offset:1024
	global_load_dwordx4 v[234:237], v[118:119], off offset:1024
	v_or_b32_e32 v2, s28, v1
	v_min_u32_e32 v3, 7, v2
	v_add_u32_e32 v3, 1, v3
	v_cvt_f32_ubyte0_e32 v3, v3
	v_div_scale_f32 v4, s[6:7], v3, v3, 1.0
	v_rcp_f32_e32 v5, v4
	s_ashr_i32 s8, s30, 6
	s_mul_i32 s10, s8, 15
	v_cmp_lt_u32_e64 s[6:7], s41, v2
	v_fma_f32 v6, -v4, v5, 1.0
	v_fmac_f32_e32 v5, v6, v5
	v_div_scale_f32 v6, vcc, 1.0, v3, 1.0
	v_mul_f32_e32 v7, v6, v5
	v_fma_f32 v8, -v4, v7, v6
	v_fmac_f32_e32 v7, v8, v5
	v_fma_f32 v4, -v4, v7, v6
	v_div_fmas_f32 v4, v4, v5, v7
	v_div_fixup_f32 v159, v4, v3, 1.0
	s_ashr_i32 s11, s10, 31
	v_add_u32_e32 v2, 0xfffff80f, v2
	v_mov_b32_e32 v3, v155
	v_lshl_add_u64 v[2:3], v[2:3], 0, s[10:11]
	v_lshlrev_b64 v[2:3], 11, v[2:3]
	v_lshl_add_u64 v[2:3], s[70:71], 0, v[2:3]
	v_mov_b32_e32 v163, v155
	v_lshl_add_u64 v[2:3], v[2:3], 0, v[162:163]
	v_lshl_add_u64 v[192:193], v[2:3], 0, s[20:21]
	v_mov_b32_e32 v2, 0
	s_mov_b32 s49, 0
	s_mov_b64 s[10:11], 0
	v_mov_b32_e32 v3, v2
	v_mov_b32_e32 v4, v2
	v_mov_b32_e32 v5, v2
	v_mov_b32_e32 v6, v2
	v_mov_b32_e32 v7, v2
	v_mov_b32_e32 v8, v2
	v_mov_b32_e32 v9, v2
	v_mov_b32_e32 v10, v2
	v_mov_b32_e32 v11, v2
	v_mov_b32_e32 v12, v2
	v_mov_b32_e32 v13, v2
	v_mov_b32_e32 v14, v2
	v_mov_b32_e32 v15, v2
	v_mov_b32_e32 v16, v2
	v_mov_b32_e32 v17, v2
	v_mov_b32_e32 v18, v2
	v_mov_b32_e32 v19, v2
	v_mov_b32_e32 v20, v2
	v_mov_b32_e32 v21, v2
	v_mov_b32_e32 v22, v2
	v_mov_b32_e32 v23, v2
	v_mov_b32_e32 v24, v2
	v_mov_b32_e32 v25, v2
	v_mov_b32_e32 v26, v2
	v_mov_b32_e32 v27, v2
	v_mov_b32_e32 v28, v2
	v_mov_b32_e32 v29, v2
	v_mov_b32_e32 v30, v2
	v_mov_b32_e32 v31, v2
	v_mov_b32_e32 v32, v2
	v_mov_b32_e32 v33, v2
	v_mov_b32_e32 v34, v2
	v_mov_b32_e32 v35, v2
	v_mov_b32_e32 v36, v2
	v_mov_b32_e32 v37, v2
	v_mov_b32_e32 v38, v2
	v_mov_b32_e32 v39, v2
	v_mov_b32_e32 v40, v2
	v_mov_b32_e32 v41, v2
	v_mov_b32_e32 v42, v2
	v_mov_b32_e32 v43, v2
	v_mov_b32_e32 v44, v2
	v_mov_b32_e32 v45, v2
	v_mov_b32_e32 v46, v2
	v_mov_b32_e32 v47, v2
	v_mov_b32_e32 v48, v2
	v_mov_b32_e32 v49, v2
	v_mov_b32_e32 v50, v2
	v_mov_b32_e32 v51, v2
	v_mov_b32_e32 v52, v2
	v_mov_b32_e32 v53, v2
	v_mov_b32_e32 v54, v2
	v_mov_b32_e32 v55, v2
	v_mov_b32_e32 v56, v2
	v_mov_b32_e32 v57, v2
	v_mov_b32_e32 v58, v2
	v_mov_b32_e32 v59, v2
	v_mov_b32_e32 v60, v2
	v_mov_b32_e32 v61, v2
	v_mov_b32_e32 v62, v2
	v_mov_b32_e32 v63, v2
	v_mov_b32_e32 v64, v2
	v_mov_b32_e32 v65, v2
	s_mov_b32 s50, 0x3f80
	s_mov_b32 s51, 0x3f800000
	v_lshl_add_u32 v163, v197, 1, v214
	ds_read_b128 v[238:241], v163 offset:4080
	ds_read_b128 v[242:245], v163 offset:3808
	ds_read_b128 v[248:251], v163 offset:3536
	ds_read_b128 v[252:255], v163 offset:3264
	s_waitcnt lgkmcnt(3)
	v_lshlrev_b32_e32 v98, 16, v238
	v_and_b32_e32 v99, 0xffff0000, v238
	v_lshlrev_b32_e32 v100, 16, v239
	v_and_b32_e32 v101, 0xffff0000, v239
	v_lshlrev_b32_e32 v102, 16, v240
	v_and_b32_e32 v103, 0xffff0000, v240
	v_lshlrev_b32_e32 v104, 16, v241
	v_and_b32_e32 v105, 0xffff0000, v241
	v_mov_b64_e32 v[106:107], v[98:99]
	v_mov_b64_e32 v[108:109], v[100:101]
	v_mov_b64_e32 v[218:219], v[102:103]
	v_mov_b64_e32 v[220:221], v[104:105]
	ds_read_b128 v[238:241], v163 offset:2992
	s_waitcnt lgkmcnt(3)
	v_dot2c_f32_bf16 v106, s50, v242
	v_dot2c_f32_bf16 v107, s51, v242
	v_dot2c_f32_bf16 v108, s50, v243
	v_dot2c_f32_bf16 v109, s51, v243
	v_dot2c_f32_bf16 v218, s50, v244
	v_dot2c_f32_bf16 v219, s51, v244
	v_dot2c_f32_bf16 v220, s50, v245
	v_dot2c_f32_bf16 v221, s51, v245
	ds_read_b128 v[242:245], v163 offset:2720
	s_waitcnt lgkmcnt(3)
	v_dot2c_f32_bf16 v106, s50, v248
	v_dot2c_f32_bf16 v107, s51, v248
	v_dot2c_f32_bf16 v108, s50, v249
	v_dot2c_f32_bf16 v109, s51, v249
	v_dot2c_f32_bf16 v218, s50, v250
	v_dot2c_f32_bf16 v219, s51, v250
	v_dot2c_f32_bf16 v220, s50, v251
	v_dot2c_f32_bf16 v221, s51, v251
	ds_read_b128 v[248:251], v163 offset:2448
	s_waitcnt lgkmcnt(3)
	v_dot2c_f32_bf16 v106, s50, v252
	v_dot2c_f32_bf16 v107, s51, v252
	v_dot2c_f32_bf16 v108, s50, v253
	v_dot2c_f32_bf16 v109, s51, v253
	v_dot2c_f32_bf16 v218, s50, v254
	v_dot2c_f32_bf16 v219, s51, v254
	v_dot2c_f32_bf16 v220, s50, v255
	v_dot2c_f32_bf16 v221, s51, v255
	ds_read_b128 v[252:255], v163 offset:2176
	s_waitcnt lgkmcnt(3)
	v_dot2c_f32_bf16 v106, s50, v238
	v_dot2c_f32_bf16 v107, s51, v238
	v_dot2c_f32_bf16 v108, s50, v239
	v_dot2c_f32_bf16 v109, s51, v239
	v_dot2c_f32_bf16 v218, s50, v240
	v_dot2c_f32_bf16 v219, s51, v240
	v_dot2c_f32_bf16 v220, s50, v241
	v_dot2c_f32_bf16 v221, s51, v241
	ds_read_b128 v[238:241], v163 offset:4112
	s_waitcnt lgkmcnt(3)
	v_dot2c_f32_bf16 v106, s50, v242
	v_dot2c_f32_bf16 v107, s51, v242
	v_dot2c_f32_bf16 v108, s50, v243
	v_dot2c_f32_bf16 v109, s51, v243
	v_dot2c_f32_bf16 v218, s50, v244
	v_dot2c_f32_bf16 v219, s51, v244
	v_dot2c_f32_bf16 v220, s50, v245
	v_dot2c_f32_bf16 v221, s51, v245
	ds_read_b128 v[242:245], v163 offset:3840
	s_waitcnt lgkmcnt(3)
	v_dot2c_f32_bf16 v106, s50, v248
	v_dot2c_f32_bf16 v107, s51, v248
	v_dot2c_f32_bf16 v108, s50, v249
	v_dot2c_f32_bf16 v109, s51, v249
	v_dot2c_f32_bf16 v218, s50, v250
	v_dot2c_f32_bf16 v219, s51, v250
	v_dot2c_f32_bf16 v220, s50, v251
	v_dot2c_f32_bf16 v221, s51, v251
	ds_read_b128 v[248:251], v163 offset:3568
	s_waitcnt lgkmcnt(3)
	v_dot2c_f32_bf16 v106, s50, v252
	v_dot2c_f32_bf16 v107, s51, v252
	v_dot2c_f32_bf16 v108, s50, v253
	v_dot2c_f32_bf16 v109, s51, v253
	v_dot2c_f32_bf16 v218, s50, v254
	v_dot2c_f32_bf16 v219, s51, v254
	v_dot2c_f32_bf16 v220, s50, v255
	v_dot2c_f32_bf16 v221, s51, v255
	ds_read_b128 v[252:255], v163 offset:3296
	v_fma_f32 v106, v159, v106, -v98
	v_fma_f32 v107, v159, v107, -v99
	v_fma_f32 v108, v159, v108, -v100
	v_fma_f32 v109, v159, v109, -v101
	v_fma_f32 v218, v159, v218, -v102
	v_fma_f32 v219, v159, v219, -v103
	v_fma_f32 v220, v159, v220, -v104
	v_fma_f32 v221, v159, v221, -v105
	v_cvt_pk_bf16_f32 v106, v106, v107
	v_cvt_pk_bf16_f32 v107, v108, v109
	v_cvt_pk_bf16_f32 v108, v218, v219
	v_cvt_pk_bf16_f32 v109, v220, v221
	s_and_saveexec_b64 s[28:29], s[6:7]
	s_cbranch_execz .Lpu1_0
	global_store_dwordx4 v[192:193], v[98:101], off offset:0
	global_store_dwordx4 v[192:193], v[102:105], off offset:16
.Lpu1_0:
	s_or_b64 exec, exec, s[28:29]
	s_waitcnt vmcnt(8)
	v_mfma_f32_32x32x16_bf16 v[2:17], v[106:109], v[70:73], v[2:17]
	v_mfma_f32_32x32x16_bf16 v[18:33], v[106:109], v[74:77], v[18:33]
	v_mfma_f32_32x32x16_bf16 v[34:49], v[106:109], v[78:81], v[34:49]
	v_mfma_f32_32x32x16_bf16 v[50:65], v[106:109], v[66:69], v[50:65]
	global_load_dwordx4 v[70:73], v[112:113], off offset:1536
	global_load_dwordx4 v[74:77], v[114:115], off offset:1536
	global_load_dwordx4 v[78:81], v[116:117], off offset:1536
	global_load_dwordx4 v[66:69], v[118:119], off offset:1536
	s_waitcnt lgkmcnt(3)
	v_lshlrev_b32_e32 v98, 16, v238
	v_and_b32_e32 v99, 0xffff0000, v238
	v_lshlrev_b32_e32 v100, 16, v239
	v_and_b32_e32 v101, 0xffff0000, v239
	v_lshlrev_b32_e32 v102, 16, v240
	v_and_b32_e32 v103, 0xffff0000, v240
	v_lshlrev_b32_e32 v104, 16, v241
	v_and_b32_e32 v105, 0xffff0000, v241
	v_mov_b64_e32 v[106:107], v[98:99]
	v_mov_b64_e32 v[108:109], v[100:101]
	v_mov_b64_e32 v[218:219], v[102:103]
	v_mov_b64_e32 v[220:221], v[104:105]
	ds_read_b128 v[238:241], v163 offset:3024
	s_waitcnt lgkmcnt(3)
	v_dot2c_f32_bf16 v106, s50, v242
	v_dot2c_f32_bf16 v107, s51, v242
	v_dot2c_f32_bf16 v108, s50, v243
	v_dot2c_f32_bf16 v109, s51, v243
	v_dot2c_f32_bf16 v218, s50, v244
	v_dot2c_f32_bf16 v219, s51, v244
	v_dot2c_f32_bf16 v220, s50, v245
	v_dot2c_f32_bf16 v221, s51, v245
	ds_read_b128 v[242:245], v163 offset:2752
	s_waitcnt lgkmcnt(3)
	v_dot2c_f32_bf16 v106, s50, v248
	v_dot2c_f32_bf16 v107, s51, v248
	v_dot2c_f32_bf16 v108, s50, v249
	v_dot2c_f32_bf16 v109, s51, v249
	v_dot2c_f32_bf16 v218, s50, v250
	v_dot2c_f32_bf16 v219, s51, v250
	v_dot2c_f32_bf16 v220, s50, v251
	v_dot2c_f32_bf16 v221, s51, v251
	ds_read_b128 v[248:251], v163 offset:2480
	s_waitcnt lgkmcnt(3)
	v_dot2c_f32_bf16 v106, s50, v252
	v_dot2c_f32_bf16 v107, s51, v252
	v_dot2c_f32_bf16 v108, s50, v253
	v_dot2c_f32_bf16 v109, s51, v253
	v_dot2c_f32_bf16 v218, s50, v254
	v_dot2c_f32_bf16 v219, s51, v254
	v_dot2c_f32_bf16 v220, s50, v255
	v_dot2c_f32_bf16 v221, s51, v255
	ds_read_b128 v[252:255], v163 offset:2208
	s_waitcnt lgkmcnt(3)
	v_dot2c_f32_bf16 v106, s50, v238
	v_dot2c_f32_bf16 v107, s51, v238
	v_dot2c_f32_bf16 v108, s50, v239
	v_dot2c_f32_bf16 v109, s51, v239
	v_dot2c_f32_bf16 v218, s50, v240
	v_dot2c_f32_bf16 v219, s51, v240
	v_dot2c_f32_bf16 v220, s50, v241
	v_dot2c_f32_bf16 v221, s51, v241
	ds_read_b128 v[238:241], v163 offset:4144
	s_waitcnt lgkmcnt(3)
	v_dot2c_f32_bf16 v106, s50, v242
	v_dot2c_f32_bf16 v107, s51, v242
	v_dot2c_f32_bf16 v108, s50, v243
	v_dot2c_f32_bf16 v109, s51, v243
	v_dot2c_f32_bf16 v218, s50, v244
	v_dot2c_f32_bf16 v219, s51, v244
	v_dot2c_f32_bf16 v220, s50, v245
	v_dot2c_f32_bf16 v221, s51, v245
	ds_read_b128 v[242:245], v163 offset:3872
	s_waitcnt lgkmcnt(3)
	v_dot2c_f32_bf16 v106, s50, v248
	v_dot2c_f32_bf16 v107, s51, v248
	v_dot2c_f32_bf16 v108, s50, v249
	v_dot2c_f32_bf16 v109, s51, v249
	v_dot2c_f32_bf16 v218, s50, v250
	v_dot2c_f32_bf16 v219, s51, v250
	v_dot2c_f32_bf16 v220, s50, v251
	v_dot2c_f32_bf16 v221, s51, v251
	ds_read_b128 v[248:251], v163 offset:3600
	s_waitcnt lgkmcnt(3)
	v_dot2c_f32_bf16 v106, s50, v252
	v_dot2c_f32_bf16 v107, s51, v252
	v_dot2c_f32_bf16 v108, s50, v253
	v_dot2c_f32_bf16 v109, s51, v253
	v_dot2c_f32_bf16 v218, s50, v254
	v_dot2c_f32_bf16 v219, s51, v254
	v_dot2c_f32_bf16 v220, s50, v255
	v_dot2c_f32_bf16 v221, s51, v255
	ds_read_b128 v[252:255], v163 offset:3328
	v_fma_f32 v106, v159, v106, -v98
	v_fma_f32 v107, v159, v107, -v99
	v_fma_f32 v108, v159, v108, -v100
	v_fma_f32 v109, v159, v109, -v101
	v_fma_f32 v218, v159, v218, -v102
	v_fma_f32 v219, v159, v219, -v103
	v_fma_f32 v220, v159, v220, -v104
	v_fma_f32 v221, v159, v221, -v105
	v_cvt_pk_bf16_f32 v106, v106, v107
	v_cvt_pk_bf16_f32 v107, v108, v109
	v_cvt_pk_bf16_f32 v108, v218, v219
	v_cvt_pk_bf16_f32 v109, v220, v221
	s_and_saveexec_b64 s[28:29], s[6:7]
	s_cbranch_execz .Lpu1_1
	global_store_dwordx4 v[192:193], v[98:101], off offset:64
	global_store_dwordx4 v[192:193], v[102:105], off offset:80
.Lpu1_1:
	s_or_b64 exec, exec, s[28:29]
	s_waitcnt vmcnt(8)
	v_mfma_f32_32x32x16_bf16 v[2:17], v[106:109], v[82:85], v[2:17]
	v_mfma_f32_32x32x16_bf16 v[18:33], v[106:109], v[86:89], v[18:33]
	v_mfma_f32_32x32x16_bf16 v[34:49], v[106:109], v[90:93], v[34:49]
	v_mfma_f32_32x32x16_bf16 v[50:65], v[106:109], v[94:97], v[50:65]
	global_load_dwordx4 v[82:85], v[112:113], off offset:2048
	global_load_dwordx4 v[86:89], v[114:115], off offset:2048
	global_load_dwordx4 v[90:93], v[116:117], off offset:2048
	global_load_dwordx4 v[94:97], v[118:119], off offset:2048
	s_waitcnt lgkmcnt(3)
	v_lshlrev_b32_e32 v98, 16, v238
	v_and_b32_e32 v99, 0xffff0000, v238
	v_lshlrev_b32_e32 v100, 16, v239
	v_and_b32_e32 v101, 0xffff0000, v239
	v_lshlrev_b32_e32 v102, 16, v240
	v_and_b32_e32 v103, 0xffff0000, v240
	v_lshlrev_b32_e32 v104, 16, v241
	v_and_b32_e32 v105, 0xffff0000, v241
	v_mov_b64_e32 v[106:107], v[98:99]
	v_mov_b64_e32 v[108:109], v[100:101]
	v_mov_b64_e32 v[218:219], v[102:103]
	v_mov_b64_e32 v[220:221], v[104:105]
	ds_read_b128 v[238:241], v163 offset:3056
	s_waitcnt lgkmcnt(3)
	v_dot2c_f32_bf16 v106, s50, v242
	v_dot2c_f32_bf16 v107, s51, v242
	v_dot2c_f32_bf16 v108, s50, v243
	v_dot2c_f32_bf16 v109, s51, v243
	v_dot2c_f32_bf16 v218, s50, v244
	v_dot2c_f32_bf16 v219, s51, v244
	v_dot2c_f32_bf16 v220, s50, v245
	v_dot2c_f32_bf16 v221, s51, v245
	ds_read_b128 v[242:245], v163 offset:2784
	s_waitcnt lgkmcnt(3)
	v_dot2c_f32_bf16 v106, s50, v248
	v_dot2c_f32_bf16 v107, s51, v248
	v_dot2c_f32_bf16 v108, s50, v249
	v_dot2c_f32_bf16 v109, s51, v249
	v_dot2c_f32_bf16 v218, s50, v250
	v_dot2c_f32_bf16 v219, s51, v250
	v_dot2c_f32_bf16 v220, s50, v251
	v_dot2c_f32_bf16 v221, s51, v251
	ds_read_b128 v[248:251], v163 offset:2512
	s_waitcnt lgkmcnt(3)
	v_dot2c_f32_bf16 v106, s50, v252
	v_dot2c_f32_bf16 v107, s51, v252
	v_dot2c_f32_bf16 v108, s50, v253
	v_dot2c_f32_bf16 v109, s51, v253
	v_dot2c_f32_bf16 v218, s50, v254
	v_dot2c_f32_bf16 v219, s51, v254
	v_dot2c_f32_bf16 v220, s50, v255
	v_dot2c_f32_bf16 v221, s51, v255
	ds_read_b128 v[252:255], v163 offset:2240
	s_waitcnt lgkmcnt(3)
	v_dot2c_f32_bf16 v106, s50, v238
	v_dot2c_f32_bf16 v107, s51, v238
	v_dot2c_f32_bf16 v108, s50, v239
	v_dot2c_f32_bf16 v109, s51, v239
	v_dot2c_f32_bf16 v218, s50, v240
	v_dot2c_f32_bf16 v219, s51, v240
	v_dot2c_f32_bf16 v220, s50, v241
	v_dot2c_f32_bf16 v221, s51, v241
	ds_read_b128 v[238:241], v163 offset:4176
	s_waitcnt lgkmcnt(3)
	v_dot2c_f32_bf16 v106, s50, v242
	v_dot2c_f32_bf16 v107, s51, v242
	v_dot2c_f32_bf16 v108, s50, v243
	v_dot2c_f32_bf16 v109, s51, v243
	v_dot2c_f32_bf16 v218, s50, v244
	v_dot2c_f32_bf16 v219, s51, v244
	v_dot2c_f32_bf16 v220, s50, v245
	v_dot2c_f32_bf16 v221, s51, v245
	ds_read_b128 v[242:245], v163 offset:3904
	s_waitcnt lgkmcnt(3)
	v_dot2c_f32_bf16 v106, s50, v248
	v_dot2c_f32_bf16 v107, s51, v248
	v_dot2c_f32_bf16 v108, s50, v249
	v_dot2c_f32_bf16 v109, s51, v249
	v_dot2c_f32_bf16 v218, s50, v250
	v_dot2c_f32_bf16 v219, s51, v250
	v_dot2c_f32_bf16 v220, s50, v251
	v_dot2c_f32_bf16 v221, s51, v251
	ds_read_b128 v[248:251], v163 offset:3632
	s_waitcnt lgkmcnt(3)
	v_dot2c_f32_bf16 v106, s50, v252
	v_dot2c_f32_bf16 v107, s51, v252
	v_dot2c_f32_bf16 v108, s50, v253
	v_dot2c_f32_bf16 v109, s51, v253
	v_dot2c_f32_bf16 v218, s50, v254
	v_dot2c_f32_bf16 v219, s51, v254
	v_dot2c_f32_bf16 v220, s50, v255
	v_dot2c_f32_bf16 v221, s51, v255
	ds_read_b128 v[252:255], v163 offset:3360
	v_fma_f32 v106, v159, v106, -v98
	v_fma_f32 v107, v159, v107, -v99
	v_fma_f32 v108, v159, v108, -v100
	v_fma_f32 v109, v159, v109, -v101
	v_fma_f32 v218, v159, v218, -v102
	v_fma_f32 v219, v159, v219, -v103
	v_fma_f32 v220, v159, v220, -v104
	v_fma_f32 v221, v159, v221, -v105
	v_cvt_pk_bf16_f32 v106, v106, v107
	v_cvt_pk_bf16_f32 v107, v108, v109
	v_cvt_pk_bf16_f32 v108, v218, v219
	v_cvt_pk_bf16_f32 v109, v220, v221
	s_and_saveexec_b64 s[28:29], s[6:7]
	s_cbranch_execz .Lpu1_2
	global_store_dwordx4 v[192:193], v[98:101], off offset:128
	global_store_dwordx4 v[192:193], v[102:105], off offset:144
.Lpu1_2:
	s_or_b64 exec, exec, s[28:29]
	s_waitcnt vmcnt(8)
	v_mfma_f32_32x32x16_bf16 v[2:17], v[106:109], v[222:225], v[2:17]
	v_mfma_f32_32x32x16_bf16 v[18:33], v[106:109], v[226:229], v[18:33]
	v_mfma_f32_32x32x16_bf16 v[34:49], v[106:109], v[230:233], v[34:49]
	v_mfma_f32_32x32x16_bf16 v[50:65], v[106:109], v[234:237], v[50:65]
	global_load_dwordx4 v[222:225], v[112:113], off offset:2560
	global_load_dwordx4 v[226:229], v[114:115], off offset:2560
	global_load_dwordx4 v[230:233], v[116:117], off offset:2560
	global_load_dwordx4 v[234:237], v[118:119], off offset:2560
	s_waitcnt lgkmcnt(3)
	v_lshlrev_b32_e32 v98, 16, v238
	v_and_b32_e32 v99, 0xffff0000, v238
	v_lshlrev_b32_e32 v100, 16, v239
	v_and_b32_e32 v101, 0xffff0000, v239
	v_lshlrev_b32_e32 v102, 16, v240
	v_and_b32_e32 v103, 0xffff0000, v240
	v_lshlrev_b32_e32 v104, 16, v241
	v_and_b32_e32 v105, 0xffff0000, v241
	v_mov_b64_e32 v[106:107], v[98:99]
	v_mov_b64_e32 v[108:109], v[100:101]
	v_mov_b64_e32 v[218:219], v[102:103]
	v_mov_b64_e32 v[220:221], v[104:105]
	ds_read_b128 v[238:241], v163 offset:3088
	s_waitcnt lgkmcnt(3)
	v_dot2c_f32_bf16 v106, s50, v242
	v_dot2c_f32_bf16 v107, s51, v242
	v_dot2c_f32_bf16 v108, s50, v243
	v_dot2c_f32_bf16 v109, s51, v243
	v_dot2c_f32_bf16 v218, s50, v244
	v_dot2c_f32_bf16 v219, s51, v244
	v_dot2c_f32_bf16 v220, s50, v245
	v_dot2c_f32_bf16 v221, s51, v245
	ds_read_b128 v[242:245], v163 offset:2816
	s_waitcnt lgkmcnt(3)
	v_dot2c_f32_bf16 v106, s50, v248
	v_dot2c_f32_bf16 v107, s51, v248
	v_dot2c_f32_bf16 v108, s50, v249
	v_dot2c_f32_bf16 v109, s51, v249
	v_dot2c_f32_bf16 v218, s50, v250
	v_dot2c_f32_bf16 v219, s51, v250
	v_dot2c_f32_bf16 v220, s50, v251
	v_dot2c_f32_bf16 v221, s51, v251
	ds_read_b128 v[248:251], v163 offset:2544
	s_waitcnt lgkmcnt(3)
	v_dot2c_f32_bf16 v106, s50, v252
	v_dot2c_f32_bf16 v107, s51, v252
	v_dot2c_f32_bf16 v108, s50, v253
	v_dot2c_f32_bf16 v109, s51, v253
	v_dot2c_f32_bf16 v218, s50, v254
	v_dot2c_f32_bf16 v219, s51, v254
	v_dot2c_f32_bf16 v220, s50, v255
	v_dot2c_f32_bf16 v221, s51, v255
	ds_read_b128 v[252:255], v163 offset:2272
	s_waitcnt lgkmcnt(3)
	v_dot2c_f32_bf16 v106, s50, v238
	v_dot2c_f32_bf16 v107, s51, v238
	v_dot2c_f32_bf16 v108, s50, v239
	v_dot2c_f32_bf16 v109, s51, v239
	v_dot2c_f32_bf16 v218, s50, v240
	v_dot2c_f32_bf16 v219, s51, v240
	v_dot2c_f32_bf16 v220, s50, v241
	v_dot2c_f32_bf16 v221, s51, v241
	ds_read_b128 v[238:241], v163 offset:4208
	s_waitcnt lgkmcnt(3)
	v_dot2c_f32_bf16 v106, s50, v242
	v_dot2c_f32_bf16 v107, s51, v242
	v_dot2c_f32_bf16 v108, s50, v243
	v_dot2c_f32_bf16 v109, s51, v243
	v_dot2c_f32_bf16 v218, s50, v244
	v_dot2c_f32_bf16 v219, s51, v244
	v_dot2c_f32_bf16 v220, s50, v245
	v_dot2c_f32_bf16 v221, s51, v245
	ds_read_b128 v[242:245], v163 offset:3936
	s_waitcnt lgkmcnt(3)
	v_dot2c_f32_bf16 v106, s50, v248
	v_dot2c_f32_bf16 v107, s51, v248
	v_dot2c_f32_bf16 v108, s50, v249
	v_dot2c_f32_bf16 v109, s51, v249
	v_dot2c_f32_bf16 v218, s50, v250
	v_dot2c_f32_bf16 v219, s51, v250
	v_dot2c_f32_bf16 v220, s50, v251
	v_dot2c_f32_bf16 v221, s51, v251
	ds_read_b128 v[248:251], v163 offset:3664
	s_waitcnt lgkmcnt(3)
	v_dot2c_f32_bf16 v106, s50, v252
	v_dot2c_f32_bf16 v107, s51, v252
	v_dot2c_f32_bf16 v108, s50, v253
	v_dot2c_f32_bf16 v109, s51, v253
	v_dot2c_f32_bf16 v218, s50, v254
	v_dot2c_f32_bf16 v219, s51, v254
	v_dot2c_f32_bf16 v220, s50, v255
	v_dot2c_f32_bf16 v221, s51, v255
	ds_read_b128 v[252:255], v163 offset:3392
	v_fma_f32 v106, v159, v106, -v98
	v_fma_f32 v107, v159, v107, -v99
	v_fma_f32 v108, v159, v108, -v100
	v_fma_f32 v109, v159, v109, -v101
	v_fma_f32 v218, v159, v218, -v102
	v_fma_f32 v219, v159, v219, -v103
	v_fma_f32 v220, v159, v220, -v104
	v_fma_f32 v221, v159, v221, -v105
	v_cvt_pk_bf16_f32 v106, v106, v107
	v_cvt_pk_bf16_f32 v107, v108, v109
	v_cvt_pk_bf16_f32 v108, v218, v219
	v_cvt_pk_bf16_f32 v109, v220, v221
	s_and_saveexec_b64 s[28:29], s[6:7]
	s_cbranch_execz .Lpu1_3
	global_store_dwordx4 v[192:193], v[98:101], off offset:192
	global_store_dwordx4 v[192:193], v[102:105], off offset:208
.Lpu1_3:
	s_or_b64 exec, exec, s[28:29]
	s_waitcnt vmcnt(8)
	v_mfma_f32_32x32x16_bf16 v[2:17], v[106:109], v[70:73], v[2:17]
	v_mfma_f32_32x32x16_bf16 v[18:33], v[106:109], v[74:77], v[18:33]
	v_mfma_f32_32x32x16_bf16 v[34:49], v[106:109], v[78:81], v[34:49]
	v_mfma_f32_32x32x16_bf16 v[50:65], v[106:109], v[66:69], v[50:65]
	global_load_dwordx4 v[70:73], v[112:113], off offset:3072
	global_load_dwordx4 v[74:77], v[114:115], off offset:3072
	global_load_dwordx4 v[78:81], v[116:117], off offset:3072
	global_load_dwordx4 v[66:69], v[118:119], off offset:3072
	s_waitcnt lgkmcnt(3)
	v_lshlrev_b32_e32 v98, 16, v238
	v_and_b32_e32 v99, 0xffff0000, v238
	v_lshlrev_b32_e32 v100, 16, v239
	v_and_b32_e32 v101, 0xffff0000, v239
	v_lshlrev_b32_e32 v102, 16, v240
	v_and_b32_e32 v103, 0xffff0000, v240
	v_lshlrev_b32_e32 v104, 16, v241
	v_and_b32_e32 v105, 0xffff0000, v241
	v_mov_b64_e32 v[106:107], v[98:99]
	v_mov_b64_e32 v[108:109], v[100:101]
	v_mov_b64_e32 v[218:219], v[102:103]
	v_mov_b64_e32 v[220:221], v[104:105]
	ds_read_b128 v[238:241], v163 offset:3120
	s_waitcnt lgkmcnt(3)
	v_dot2c_f32_bf16 v106, s50, v242
	v_dot2c_f32_bf16 v107, s51, v242
	v_dot2c_f32_bf16 v108, s50, v243
	v_dot2c_f32_bf16 v109, s51, v243
	v_dot2c_f32_bf16 v218, s50, v244
	v_dot2c_f32_bf16 v219, s51, v244
	v_dot2c_f32_bf16 v220, s50, v245
	v_dot2c_f32_bf16 v221, s51, v245
	ds_read_b128 v[242:245], v163 offset:2848
	s_waitcnt lgkmcnt(3)
	v_dot2c_f32_bf16 v106, s50, v248
	v_dot2c_f32_bf16 v107, s51, v248
	v_dot2c_f32_bf16 v108, s50, v249
	v_dot2c_f32_bf16 v109, s51, v249
	v_dot2c_f32_bf16 v218, s50, v250
	v_dot2c_f32_bf16 v219, s51, v250
	v_dot2c_f32_bf16 v220, s50, v251
	v_dot2c_f32_bf16 v221, s51, v251
	ds_read_b128 v[248:251], v163 offset:2576
	s_waitcnt lgkmcnt(3)
	v_dot2c_f32_bf16 v106, s50, v252
	v_dot2c_f32_bf16 v107, s51, v252
	v_dot2c_f32_bf16 v108, s50, v253
	v_dot2c_f32_bf16 v109, s51, v253
	v_dot2c_f32_bf16 v218, s50, v254
	v_dot2c_f32_bf16 v219, s51, v254
	v_dot2c_f32_bf16 v220, s50, v255
	v_dot2c_f32_bf16 v221, s51, v255
	ds_read_b128 v[252:255], v163 offset:2304
	s_waitcnt lgkmcnt(3)
	v_dot2c_f32_bf16 v106, s50, v238
	v_dot2c_f32_bf16 v107, s51, v238
	v_dot2c_f32_bf16 v108, s50, v239
	v_dot2c_f32_bf16 v109, s51, v239
	v_dot2c_f32_bf16 v218, s50, v240
	v_dot2c_f32_bf16 v219, s51, v240
	v_dot2c_f32_bf16 v220, s50, v241
	v_dot2c_f32_bf16 v221, s51, v241
	ds_read_b128 v[238:241], v163 offset:4240
	s_waitcnt lgkmcnt(3)
	v_dot2c_f32_bf16 v106, s50, v242
	v_dot2c_f32_bf16 v107, s51, v242
	v_dot2c_f32_bf16 v108, s50, v243
	v_dot2c_f32_bf16 v109, s51, v243
	v_dot2c_f32_bf16 v218, s50, v244
	v_dot2c_f32_bf16 v219, s51, v244
	v_dot2c_f32_bf16 v220, s50, v245
	v_dot2c_f32_bf16 v221, s51, v245
	ds_read_b128 v[242:245], v163 offset:3968
	s_waitcnt lgkmcnt(3)
	v_dot2c_f32_bf16 v106, s50, v248
	v_dot2c_f32_bf16 v107, s51, v248
	v_dot2c_f32_bf16 v108, s50, v249
	v_dot2c_f32_bf16 v109, s51, v249
	v_dot2c_f32_bf16 v218, s50, v250
	v_dot2c_f32_bf16 v219, s51, v250
	v_dot2c_f32_bf16 v220, s50, v251
	v_dot2c_f32_bf16 v221, s51, v251
	ds_read_b128 v[248:251], v163 offset:3696
	s_waitcnt lgkmcnt(3)
	v_dot2c_f32_bf16 v106, s50, v252
	v_dot2c_f32_bf16 v107, s51, v252
	v_dot2c_f32_bf16 v108, s50, v253
	v_dot2c_f32_bf16 v109, s51, v253
	v_dot2c_f32_bf16 v218, s50, v254
	v_dot2c_f32_bf16 v219, s51, v254
	v_dot2c_f32_bf16 v220, s50, v255
	v_dot2c_f32_bf16 v221, s51, v255
	ds_read_b128 v[252:255], v163 offset:3424
	v_fma_f32 v106, v159, v106, -v98
	v_fma_f32 v107, v159, v107, -v99
	v_fma_f32 v108, v159, v108, -v100
	v_fma_f32 v109, v159, v109, -v101
	v_fma_f32 v218, v159, v218, -v102
	v_fma_f32 v219, v159, v219, -v103
	v_fma_f32 v220, v159, v220, -v104
	v_fma_f32 v221, v159, v221, -v105
	v_cvt_pk_bf16_f32 v106, v106, v107
	v_cvt_pk_bf16_f32 v107, v108, v109
	v_cvt_pk_bf16_f32 v108, v218, v219
	v_cvt_pk_bf16_f32 v109, v220, v221
	s_and_saveexec_b64 s[28:29], s[6:7]
	s_cbranch_execz .Lpu1_4
	global_store_dwordx4 v[192:193], v[98:101], off offset:256
	global_store_dwordx4 v[192:193], v[102:105], off offset:272
.Lpu1_4:
	s_or_b64 exec, exec, s[28:29]
	s_waitcnt vmcnt(8)
	v_mfma_f32_32x32x16_bf16 v[2:17], v[106:109], v[82:85], v[2:17]
	v_mfma_f32_32x32x16_bf16 v[18:33], v[106:109], v[86:89], v[18:33]
	v_mfma_f32_32x32x16_bf16 v[34:49], v[106:109], v[90:93], v[34:49]
	v_mfma_f32_32x32x16_bf16 v[50:65], v[106:109], v[94:97], v[50:65]
	global_load_dwordx4 v[82:85], v[112:113], off offset:3584
	global_load_dwordx4 v[86:89], v[114:115], off offset:3584
	global_load_dwordx4 v[90:93], v[116:117], off offset:3584
	global_load_dwordx4 v[94:97], v[118:119], off offset:3584
	s_waitcnt lgkmcnt(3)
	v_lshlrev_b32_e32 v98, 16, v238
	v_and_b32_e32 v99, 0xffff0000, v238
	v_lshlrev_b32_e32 v100, 16, v239
	v_and_b32_e32 v101, 0xffff0000, v239
	v_lshlrev_b32_e32 v102, 16, v240
	v_and_b32_e32 v103, 0xffff0000, v240
	v_lshlrev_b32_e32 v104, 16, v241
	v_and_b32_e32 v105, 0xffff0000, v241
	v_mov_b64_e32 v[106:107], v[98:99]
	v_mov_b64_e32 v[108:109], v[100:101]
	v_mov_b64_e32 v[218:219], v[102:103]
	v_mov_b64_e32 v[220:221], v[104:105]
	ds_read_b128 v[238:241], v163 offset:3152
	s_waitcnt lgkmcnt(3)
	v_dot2c_f32_bf16 v106, s50, v242
	v_dot2c_f32_bf16 v107, s51, v242
	v_dot2c_f32_bf16 v108, s50, v243
	v_dot2c_f32_bf16 v109, s51, v243
	v_dot2c_f32_bf16 v218, s50, v244
	v_dot2c_f32_bf16 v219, s51, v244
	v_dot2c_f32_bf16 v220, s50, v245
	v_dot2c_f32_bf16 v221, s51, v245
	ds_read_b128 v[242:245], v163 offset:2880
	s_waitcnt lgkmcnt(3)
	v_dot2c_f32_bf16 v106, s50, v248
	v_dot2c_f32_bf16 v107, s51, v248
	v_dot2c_f32_bf16 v108, s50, v249
	v_dot2c_f32_bf16 v109, s51, v249
	v_dot2c_f32_bf16 v218, s50, v250
	v_dot2c_f32_bf16 v219, s51, v250
	v_dot2c_f32_bf16 v220, s50, v251
	v_dot2c_f32_bf16 v221, s51, v251
	ds_read_b128 v[248:251], v163 offset:2608
	s_waitcnt lgkmcnt(3)
	v_dot2c_f32_bf16 v106, s50, v252
	v_dot2c_f32_bf16 v107, s51, v252
	v_dot2c_f32_bf16 v108, s50, v253
	v_dot2c_f32_bf16 v109, s51, v253
	v_dot2c_f32_bf16 v218, s50, v254
	v_dot2c_f32_bf16 v219, s51, v254
	v_dot2c_f32_bf16 v220, s50, v255
	v_dot2c_f32_bf16 v221, s51, v255
	ds_read_b128 v[252:255], v163 offset:2336
	s_waitcnt lgkmcnt(3)
	v_dot2c_f32_bf16 v106, s50, v238
	v_dot2c_f32_bf16 v107, s51, v238
	v_dot2c_f32_bf16 v108, s50, v239
	v_dot2c_f32_bf16 v109, s51, v239
	v_dot2c_f32_bf16 v218, s50, v240
	v_dot2c_f32_bf16 v219, s51, v240
	v_dot2c_f32_bf16 v220, s50, v241
	v_dot2c_f32_bf16 v221, s51, v241
	ds_read_b128 v[238:241], v163 offset:4272
	s_waitcnt lgkmcnt(3)
	v_dot2c_f32_bf16 v106, s50, v242
	v_dot2c_f32_bf16 v107, s51, v242
	v_dot2c_f32_bf16 v108, s50, v243
	v_dot2c_f32_bf16 v109, s51, v243
	v_dot2c_f32_bf16 v218, s50, v244
	v_dot2c_f32_bf16 v219, s51, v244
	v_dot2c_f32_bf16 v220, s50, v245
	v_dot2c_f32_bf16 v221, s51, v245
	ds_read_b128 v[242:245], v163 offset:4000
	s_waitcnt lgkmcnt(3)
	v_dot2c_f32_bf16 v106, s50, v248
	v_dot2c_f32_bf16 v107, s51, v248
	v_dot2c_f32_bf16 v108, s50, v249
	v_dot2c_f32_bf16 v109, s51, v249
	v_dot2c_f32_bf16 v218, s50, v250
	v_dot2c_f32_bf16 v219, s51, v250
	v_dot2c_f32_bf16 v220, s50, v251
	v_dot2c_f32_bf16 v221, s51, v251
	ds_read_b128 v[248:251], v163 offset:3728
	s_waitcnt lgkmcnt(3)
	v_dot2c_f32_bf16 v106, s50, v252
	v_dot2c_f32_bf16 v107, s51, v252
	v_dot2c_f32_bf16 v108, s50, v253
	v_dot2c_f32_bf16 v109, s51, v253
	v_dot2c_f32_bf16 v218, s50, v254
	v_dot2c_f32_bf16 v219, s51, v254
	v_dot2c_f32_bf16 v220, s50, v255
	v_dot2c_f32_bf16 v221, s51, v255
	ds_read_b128 v[252:255], v163 offset:3456
	v_fma_f32 v106, v159, v106, -v98
	v_fma_f32 v107, v159, v107, -v99
	v_fma_f32 v108, v159, v108, -v100
	v_fma_f32 v109, v159, v109, -v101
	v_fma_f32 v218, v159, v218, -v102
	v_fma_f32 v219, v159, v219, -v103
	v_fma_f32 v220, v159, v220, -v104
	v_fma_f32 v221, v159, v221, -v105
	v_cvt_pk_bf16_f32 v106, v106, v107
	v_cvt_pk_bf16_f32 v107, v108, v109
	v_cvt_pk_bf16_f32 v108, v218, v219
	v_cvt_pk_bf16_f32 v109, v220, v221
	s_and_saveexec_b64 s[28:29], s[6:7]
	s_cbranch_execz .Lpu1_5
	global_store_dwordx4 v[192:193], v[98:101], off offset:320
	global_store_dwordx4 v[192:193], v[102:105], off offset:336
.Lpu1_5:
	s_or_b64 exec, exec, s[28:29]
	s_waitcnt vmcnt(8)
	v_mfma_f32_32x32x16_bf16 v[2:17], v[106:109], v[222:225], v[2:17]
	v_mfma_f32_32x32x16_bf16 v[18:33], v[106:109], v[226:229], v[18:33]
	v_mfma_f32_32x32x16_bf16 v[34:49], v[106:109], v[230:233], v[34:49]
	v_mfma_f32_32x32x16_bf16 v[50:65], v[106:109], v[234:237], v[50:65]
	s_waitcnt lgkmcnt(3)
	v_lshlrev_b32_e32 v98, 16, v238
	v_and_b32_e32 v99, 0xffff0000, v238
	v_lshlrev_b32_e32 v100, 16, v239
	v_and_b32_e32 v101, 0xffff0000, v239
	v_lshlrev_b32_e32 v102, 16, v240
	v_and_b32_e32 v103, 0xffff0000, v240
	v_lshlrev_b32_e32 v104, 16, v241
	v_and_b32_e32 v105, 0xffff0000, v241
	v_mov_b64_e32 v[106:107], v[98:99]
	v_mov_b64_e32 v[108:109], v[100:101]
	v_mov_b64_e32 v[218:219], v[102:103]
	v_mov_b64_e32 v[220:221], v[104:105]
	ds_read_b128 v[238:241], v163 offset:3184
	s_waitcnt lgkmcnt(3)
	v_dot2c_f32_bf16 v106, s50, v242
	v_dot2c_f32_bf16 v107, s51, v242
	v_dot2c_f32_bf16 v108, s50, v243
	v_dot2c_f32_bf16 v109, s51, v243
	v_dot2c_f32_bf16 v218, s50, v244
	v_dot2c_f32_bf16 v219, s51, v244
	v_dot2c_f32_bf16 v220, s50, v245
	v_dot2c_f32_bf16 v221, s51, v245
	ds_read_b128 v[242:245], v163 offset:2912
	s_waitcnt lgkmcnt(3)
	v_dot2c_f32_bf16 v106, s50, v248
	v_dot2c_f32_bf16 v107, s51, v248
	v_dot2c_f32_bf16 v108, s50, v249
	v_dot2c_f32_bf16 v109, s51, v249
	v_dot2c_f32_bf16 v218, s50, v250
	v_dot2c_f32_bf16 v219, s51, v250
	v_dot2c_f32_bf16 v220, s50, v251
	v_dot2c_f32_bf16 v221, s51, v251
	ds_read_b128 v[248:251], v163 offset:2640
	s_waitcnt lgkmcnt(3)
	v_dot2c_f32_bf16 v106, s50, v252
	v_dot2c_f32_bf16 v107, s51, v252
	v_dot2c_f32_bf16 v108, s50, v253
	v_dot2c_f32_bf16 v109, s51, v253
	v_dot2c_f32_bf16 v218, s50, v254
	v_dot2c_f32_bf16 v219, s51, v254
	v_dot2c_f32_bf16 v220, s50, v255
	v_dot2c_f32_bf16 v221, s51, v255
	ds_read_b128 v[252:255], v163 offset:2368
	s_waitcnt lgkmcnt(3)
	v_dot2c_f32_bf16 v106, s50, v238
	v_dot2c_f32_bf16 v107, s51, v238
	v_dot2c_f32_bf16 v108, s50, v239
	v_dot2c_f32_bf16 v109, s51, v239
	v_dot2c_f32_bf16 v218, s50, v240
	v_dot2c_f32_bf16 v219, s51, v240
	v_dot2c_f32_bf16 v220, s50, v241
	v_dot2c_f32_bf16 v221, s51, v241
	ds_read_b128 v[238:241], v163 offset:4304
	s_waitcnt lgkmcnt(3)
	v_dot2c_f32_bf16 v106, s50, v242
	v_dot2c_f32_bf16 v107, s51, v242
	v_dot2c_f32_bf16 v108, s50, v243
	v_dot2c_f32_bf16 v109, s51, v243
	v_dot2c_f32_bf16 v218, s50, v244
	v_dot2c_f32_bf16 v219, s51, v244
	v_dot2c_f32_bf16 v220, s50, v245
	v_dot2c_f32_bf16 v221, s51, v245
	ds_read_b128 v[242:245], v163 offset:4032
	s_waitcnt lgkmcnt(3)
	v_dot2c_f32_bf16 v106, s50, v248
	v_dot2c_f32_bf16 v107, s51, v248
	v_dot2c_f32_bf16 v108, s50, v249
	v_dot2c_f32_bf16 v109, s51, v249
	v_dot2c_f32_bf16 v218, s50, v250
	v_dot2c_f32_bf16 v219, s51, v250
	v_dot2c_f32_bf16 v220, s50, v251
	v_dot2c_f32_bf16 v221, s51, v251
	ds_read_b128 v[248:251], v163 offset:3760
	s_waitcnt lgkmcnt(3)
	v_dot2c_f32_bf16 v106, s50, v252
	v_dot2c_f32_bf16 v107, s51, v252
	v_dot2c_f32_bf16 v108, s50, v253
	v_dot2c_f32_bf16 v109, s51, v253
	v_dot2c_f32_bf16 v218, s50, v254
	v_dot2c_f32_bf16 v219, s51, v254
	v_dot2c_f32_bf16 v220, s50, v255
	v_dot2c_f32_bf16 v221, s51, v255
	ds_read_b128 v[252:255], v163 offset:3488
	v_fma_f32 v106, v159, v106, -v98
	v_fma_f32 v107, v159, v107, -v99
	v_fma_f32 v108, v159, v108, -v100
	v_fma_f32 v109, v159, v109, -v101
	v_fma_f32 v218, v159, v218, -v102
	v_fma_f32 v219, v159, v219, -v103
	v_fma_f32 v220, v159, v220, -v104
	v_fma_f32 v221, v159, v221, -v105
	v_cvt_pk_bf16_f32 v106, v106, v107
	v_cvt_pk_bf16_f32 v107, v108, v109
	v_cvt_pk_bf16_f32 v108, v218, v219
	v_cvt_pk_bf16_f32 v109, v220, v221
	s_and_saveexec_b64 s[28:29], s[6:7]
	s_cbranch_execz .Lpu1_6
	global_store_dwordx4 v[192:193], v[98:101], off offset:384
	global_store_dwordx4 v[192:193], v[102:105], off offset:400
.Lpu1_6:
	s_or_b64 exec, exec, s[28:29]
	s_waitcnt vmcnt(4)
	v_mfma_f32_32x32x16_bf16 v[2:17], v[106:109], v[70:73], v[2:17]
	v_mfma_f32_32x32x16_bf16 v[18:33], v[106:109], v[74:77], v[18:33]
	v_mfma_f32_32x32x16_bf16 v[34:49], v[106:109], v[78:81], v[34:49]
	v_mfma_f32_32x32x16_bf16 v[50:65], v[106:109], v[66:69], v[50:65]
	s_waitcnt lgkmcnt(3)
	v_lshlrev_b32_e32 v98, 16, v238
	v_and_b32_e32 v99, 0xffff0000, v238
	v_lshlrev_b32_e32 v100, 16, v239
	v_and_b32_e32 v101, 0xffff0000, v239
	v_lshlrev_b32_e32 v102, 16, v240
	v_and_b32_e32 v103, 0xffff0000, v240
	v_lshlrev_b32_e32 v104, 16, v241
	v_and_b32_e32 v105, 0xffff0000, v241
	v_mov_b64_e32 v[106:107], v[98:99]
	v_mov_b64_e32 v[108:109], v[100:101]
	v_mov_b64_e32 v[218:219], v[102:103]
	v_mov_b64_e32 v[220:221], v[104:105]
	ds_read_b128 v[238:241], v163 offset:3216
	s_waitcnt lgkmcnt(3)
	v_dot2c_f32_bf16 v106, s50, v242
	v_dot2c_f32_bf16 v107, s51, v242
	v_dot2c_f32_bf16 v108, s50, v243
	v_dot2c_f32_bf16 v109, s51, v243
	v_dot2c_f32_bf16 v218, s50, v244
	v_dot2c_f32_bf16 v219, s51, v244
	v_dot2c_f32_bf16 v220, s50, v245
	v_dot2c_f32_bf16 v221, s51, v245
	ds_read_b128 v[242:245], v163 offset:2944
	s_waitcnt lgkmcnt(3)
	v_dot2c_f32_bf16 v106, s50, v248
	v_dot2c_f32_bf16 v107, s51, v248
	v_dot2c_f32_bf16 v108, s50, v249
	v_dot2c_f32_bf16 v109, s51, v249
	v_dot2c_f32_bf16 v218, s50, v250
	v_dot2c_f32_bf16 v219, s51, v250
	v_dot2c_f32_bf16 v220, s50, v251
	v_dot2c_f32_bf16 v221, s51, v251
	ds_read_b128 v[248:251], v163 offset:2672
	s_waitcnt lgkmcnt(3)
	v_dot2c_f32_bf16 v106, s50, v252
	v_dot2c_f32_bf16 v107, s51, v252
	v_dot2c_f32_bf16 v108, s50, v253
	v_dot2c_f32_bf16 v109, s51, v253
	v_dot2c_f32_bf16 v218, s50, v254
	v_dot2c_f32_bf16 v219, s51, v254
	v_dot2c_f32_bf16 v220, s50, v255
	v_dot2c_f32_bf16 v221, s51, v255
	ds_read_b128 v[252:255], v163 offset:2400
	s_waitcnt lgkmcnt(3)
	v_dot2c_f32_bf16 v106, s50, v238
	v_dot2c_f32_bf16 v107, s51, v238
	v_dot2c_f32_bf16 v108, s50, v239
	v_dot2c_f32_bf16 v109, s51, v239
	v_dot2c_f32_bf16 v218, s50, v240
	v_dot2c_f32_bf16 v219, s51, v240
	v_dot2c_f32_bf16 v220, s50, v241
	v_dot2c_f32_bf16 v221, s51, v241
	s_waitcnt lgkmcnt(2)
	v_dot2c_f32_bf16 v106, s50, v242
	v_dot2c_f32_bf16 v107, s51, v242
	v_dot2c_f32_bf16 v108, s50, v243
	v_dot2c_f32_bf16 v109, s51, v243
	v_dot2c_f32_bf16 v218, s50, v244
	v_dot2c_f32_bf16 v219, s51, v244
	v_dot2c_f32_bf16 v220, s50, v245
	v_dot2c_f32_bf16 v221, s51, v245
	s_waitcnt lgkmcnt(1)
	v_dot2c_f32_bf16 v106, s50, v248
	v_dot2c_f32_bf16 v107, s51, v248
	v_dot2c_f32_bf16 v108, s50, v249
	v_dot2c_f32_bf16 v109, s51, v249
	v_dot2c_f32_bf16 v218, s50, v250
	v_dot2c_f32_bf16 v219, s51, v250
	v_dot2c_f32_bf16 v220, s50, v251
	v_dot2c_f32_bf16 v221, s51, v251
	s_waitcnt lgkmcnt(0)
	v_dot2c_f32_bf16 v106, s50, v252
	v_dot2c_f32_bf16 v107, s51, v252
	v_dot2c_f32_bf16 v108, s50, v253
	v_dot2c_f32_bf16 v109, s51, v253
	v_dot2c_f32_bf16 v218, s50, v254
	v_dot2c_f32_bf16 v219, s51, v254
	v_dot2c_f32_bf16 v220, s50, v255
	v_dot2c_f32_bf16 v221, s51, v255
	v_fma_f32 v106, v159, v106, -v98
	v_fma_f32 v107, v159, v107, -v99
	v_fma_f32 v108, v159, v108, -v100
	v_fma_f32 v109, v159, v109, -v101
	v_fma_f32 v218, v159, v218, -v102
	v_fma_f32 v219, v159, v219, -v103
	v_fma_f32 v220, v159, v220, -v104
	v_fma_f32 v221, v159, v221, -v105
	v_cvt_pk_bf16_f32 v106, v106, v107
	v_cvt_pk_bf16_f32 v107, v108, v109
	v_cvt_pk_bf16_f32 v108, v218, v219
	v_cvt_pk_bf16_f32 v109, v220, v221
	s_and_saveexec_b64 s[28:29], s[6:7]
	s_cbranch_execz .Lpu1_7
	global_store_dwordx4 v[192:193], v[98:101], off offset:448
	global_store_dwordx4 v[192:193], v[102:105], off offset:464

.LBB0_379:
	s_or_b64 exec, exec, s[6:7]
	s_waitcnt lgkmcnt(0)
	global_load_dwordx4 v[82:85], v[122:123], off offset:512
	global_load_dwordx4 v[86:89], v[124:125], off offset:512
	global_load_dwordx4 v[90:93], v[126:127], off offset:512
	global_load_dwordx4 v[94:97], v[128:129], off offset:512
	global_load_dwordx4 v[222:225], v[122:123], off offset:1024
	global_load_dwordx4 v[226:229], v[124:125], off offset:1024
	global_load_dwordx4 v[230:233], v[126:127], off offset:1024
	global_load_dwordx4 v[234:237], v[128:129], off offset:1024
	v_or_b32_e32 v2, s28, v1
	v_min_u32_e32 v3, 3, v2
	v_add_u32_e32 v3, 1, v3
	v_cvt_f32_ubyte0_e32 v3, v3
	v_div_scale_f32 v4, s[6:7], v3, v3, 1.0
	v_rcp_f32_e32 v5, v4
	s_ashr_i32 s8, s30, 6
	s_mul_i32 s10, s8, 15
	v_cmp_lt_u32_e64 s[6:7], s41, v2
	v_fma_f32 v6, -v4, v5, 1.0
	v_fmac_f32_e32 v5, v6, v5
	v_div_scale_f32 v6, vcc, 1.0, v3, 1.0
	v_mul_f32_e32 v7, v6, v5
	v_fma_f32 v8, -v4, v7, v6
	v_fmac_f32_e32 v7, v8, v5
	v_fma_f32 v4, -v4, v7, v6
	v_div_fmas_f32 v4, v4, v5, v7
	v_div_fixup_f32 v159, v4, v3, 1.0
	s_ashr_i32 s11, s10, 31
	v_add_u32_e32 v2, 0xfffff80f, v2
	v_mov_b32_e32 v3, v155
	v_lshl_add_u64 v[2:3], v[2:3], 0, s[10:11]
	v_lshlrev_b64 v[2:3], 11, v[2:3]
	v_lshl_add_u64 v[2:3], s[70:71], 0, v[2:3]
	v_mov_b32_e32 v163, v155
	v_lshl_add_u64 v[2:3], v[2:3], 0, v[162:163]
	v_lshl_add_u64 v[190:191], v[2:3], 0, s[24:25]
	v_mov_b32_e32 v2, 0
	s_mov_b32 s49, 0
	s_mov_b64 s[10:11], 0
	v_mov_b32_e32 v3, v2
	v_mov_b32_e32 v4, v2
	v_mov_b32_e32 v5, v2
	v_mov_b32_e32 v6, v2
	v_mov_b32_e32 v7, v2
	v_mov_b32_e32 v8, v2
	v_mov_b32_e32 v9, v2
	v_mov_b32_e32 v10, v2
	v_mov_b32_e32 v11, v2
	v_mov_b32_e32 v12, v2
	v_mov_b32_e32 v13, v2
	v_mov_b32_e32 v14, v2
	v_mov_b32_e32 v15, v2
	v_mov_b32_e32 v16, v2
	v_mov_b32_e32 v17, v2
	v_mov_b32_e32 v18, v2
	v_mov_b32_e32 v19, v2
	v_mov_b32_e32 v20, v2
	v_mov_b32_e32 v21, v2
	v_mov_b32_e32 v22, v2
	v_mov_b32_e32 v23, v2
	v_mov_b32_e32 v24, v2
	v_mov_b32_e32 v25, v2
	v_mov_b32_e32 v26, v2
	v_mov_b32_e32 v27, v2
	v_mov_b32_e32 v28, v2
	v_mov_b32_e32 v29, v2
	v_mov_b32_e32 v30, v2
	v_mov_b32_e32 v31, v2
	v_mov_b32_e32 v32, v2
	v_mov_b32_e32 v33, v2
	v_mov_b32_e32 v34, v2
	v_mov_b32_e32 v35, v2
	v_mov_b32_e32 v36, v2
	v_mov_b32_e32 v37, v2
	v_mov_b32_e32 v38, v2
	v_mov_b32_e32 v39, v2
	v_mov_b32_e32 v40, v2
	v_mov_b32_e32 v41, v2
	v_mov_b32_e32 v42, v2
	v_mov_b32_e32 v43, v2
	v_mov_b32_e32 v44, v2
	v_mov_b32_e32 v45, v2
	v_mov_b32_e32 v46, v2
	v_mov_b32_e32 v47, v2
	v_mov_b32_e32 v48, v2
	v_mov_b32_e32 v49, v2
	v_mov_b32_e32 v50, v2
	v_mov_b32_e32 v51, v2
	v_mov_b32_e32 v52, v2
	v_mov_b32_e32 v53, v2
	v_mov_b32_e32 v54, v2
	v_mov_b32_e32 v55, v2
	v_mov_b32_e32 v56, v2
	v_mov_b32_e32 v57, v2
	v_mov_b32_e32 v58, v2
	v_mov_b32_e32 v59, v2
	v_mov_b32_e32 v60, v2
	v_mov_b32_e32 v61, v2
	v_mov_b32_e32 v62, v2
	v_mov_b32_e32 v63, v2
	v_mov_b32_e32 v64, v2
	v_mov_b32_e32 v65, v2
	s_mov_b32 s50, 0x3f80
	s_mov_b32 s51, 0x3f800000
	v_lshl_add_u32 v163, v197, 1, v214
	ds_read_b128 v[238:241], v163 offset:4080
	ds_read_b128 v[242:245], v163 offset:3808
	ds_read_b128 v[248:251], v163 offset:3536
	ds_read_b128 v[252:255], v163 offset:3264
	s_waitcnt lgkmcnt(3)
	v_lshlrev_b32_e32 v98, 16, v238
	v_and_b32_e32 v99, 0xffff0000, v238
	v_lshlrev_b32_e32 v100, 16, v239
	v_and_b32_e32 v101, 0xffff0000, v239
	v_lshlrev_b32_e32 v102, 16, v240
	v_and_b32_e32 v103, 0xffff0000, v240
	v_lshlrev_b32_e32 v104, 16, v241
	v_and_b32_e32 v105, 0xffff0000, v241
	v_mov_b64_e32 v[106:107], v[98:99]
	v_mov_b64_e32 v[108:109], v[100:101]
	v_mov_b64_e32 v[218:219], v[102:103]
	v_mov_b64_e32 v[220:221], v[104:105]
	ds_read_b128 v[238:241], v163 offset:4112
	s_waitcnt lgkmcnt(3)
	v_dot2c_f32_bf16 v106, s50, v242
	v_dot2c_f32_bf16 v107, s51, v242
	v_dot2c_f32_bf16 v108, s50, v243
	v_dot2c_f32_bf16 v109, s51, v243
	v_dot2c_f32_bf16 v218, s50, v244
	v_dot2c_f32_bf16 v219, s51, v244
	v_dot2c_f32_bf16 v220, s50, v245
	v_dot2c_f32_bf16 v221, s51, v245
	ds_read_b128 v[242:245], v163 offset:3840
	s_waitcnt lgkmcnt(3)
	v_dot2c_f32_bf16 v106, s50, v248
	v_dot2c_f32_bf16 v107, s51, v248
	v_dot2c_f32_bf16 v108, s50, v249
	v_dot2c_f32_bf16 v109, s51, v249
	v_dot2c_f32_bf16 v218, s50, v250
	v_dot2c_f32_bf16 v219, s51, v250
	v_dot2c_f32_bf16 v220, s50, v251
	v_dot2c_f32_bf16 v221, s51, v251
	ds_read_b128 v[248:251], v163 offset:3568
	s_waitcnt lgkmcnt(3)
	v_dot2c_f32_bf16 v106, s50, v252
	v_dot2c_f32_bf16 v107, s51, v252
	v_dot2c_f32_bf16 v108, s50, v253
	v_dot2c_f32_bf16 v109, s51, v253
	v_dot2c_f32_bf16 v218, s50, v254
	v_dot2c_f32_bf16 v219, s51, v254
	v_dot2c_f32_bf16 v220, s50, v255
	v_dot2c_f32_bf16 v221, s51, v255
	ds_read_b128 v[252:255], v163 offset:3296
	v_fma_f32 v106, v159, v106, -v98
	v_fma_f32 v107, v159, v107, -v99
	v_fma_f32 v108, v159, v108, -v100
	v_fma_f32 v109, v159, v109, -v101
	v_fma_f32 v218, v159, v218, -v102
	v_fma_f32 v219, v159, v219, -v103
	v_fma_f32 v220, v159, v220, -v104
	v_fma_f32 v221, v159, v221, -v105
	v_cvt_pk_bf16_f32 v106, v106, v107
	v_cvt_pk_bf16_f32 v107, v108, v109
	v_cvt_pk_bf16_f32 v108, v218, v219
	v_cvt_pk_bf16_f32 v109, v220, v221
	s_and_saveexec_b64 s[28:29], s[6:7]
	s_cbranch_execz .Lpu2_0
	global_store_dwordx4 v[190:191], v[98:101], off offset:0
	global_store_dwordx4 v[190:191], v[102:105], off offset:16
.Lpu2_0:
	s_or_b64 exec, exec, s[28:29]
	s_waitcnt vmcnt(8)
	v_mfma_f32_32x32x16_bf16 v[2:17], v[106:109], v[70:73], v[2:17]
	v_mfma_f32_32x32x16_bf16 v[18:33], v[106:109], v[74:77], v[18:33]
	v_mfma_f32_32x32x16_bf16 v[34:49], v[106:109], v[78:81], v[34:49]
	v_mfma_f32_32x32x16_bf16 v[50:65], v[106:109], v[66:69], v[50:65]
	global_load_dwordx4 v[70:73], v[122:123], off offset:1536
	global_load_dwordx4 v[74:77], v[124:125], off offset:1536
	global_load_dwordx4 v[78:81], v[126:127], off offset:1536
	global_load_dwordx4 v[66:69], v[128:129], off offset:1536
	s_waitcnt lgkmcnt(3)
	v_lshlrev_b32_e32 v98, 16, v238
	v_and_b32_e32 v99, 0xffff0000, v238
	v_lshlrev_b32_e32 v100, 16, v239
	v_and_b32_e32 v101, 0xffff0000, v239
	v_lshlrev_b32_e32 v102, 16, v240
	v_and_b32_e32 v103, 0xffff0000, v240
	v_lshlrev_b32_e32 v104, 16, v241
	v_and_b32_e32 v105, 0xffff0000, v241
	v_mov_b64_e32 v[106:107], v[98:99]
	v_mov_b64_e32 v[108:109], v[100:101]
	v_mov_b64_e32 v[218:219], v[102:103]
	v_mov_b64_e32 v[220:221], v[104:105]
	ds_read_b128 v[238:241], v163 offset:4144
	s_waitcnt lgkmcnt(3)
	v_dot2c_f32_bf16 v106, s50, v242
	v_dot2c_f32_bf16 v107, s51, v242
	v_dot2c_f32_bf16 v108, s50, v243
	v_dot2c_f32_bf16 v109, s51, v243
	v_dot2c_f32_bf16 v218, s50, v244
	v_dot2c_f32_bf16 v219, s51, v244
	v_dot2c_f32_bf16 v220, s50, v245
	v_dot2c_f32_bf16 v221, s51, v245
	ds_read_b128 v[242:245], v163 offset:3872
	s_waitcnt lgkmcnt(3)
	v_dot2c_f32_bf16 v106, s50, v248
	v_dot2c_f32_bf16 v107, s51, v248
	v_dot2c_f32_bf16 v108, s50, v249
	v_dot2c_f32_bf16 v109, s51, v249
	v_dot2c_f32_bf16 v218, s50, v250
	v_dot2c_f32_bf16 v219, s51, v250
	v_dot2c_f32_bf16 v220, s50, v251
	v_dot2c_f32_bf16 v221, s51, v251
	ds_read_b128 v[248:251], v163 offset:3600
	s_waitcnt lgkmcnt(3)
	v_dot2c_f32_bf16 v106, s50, v252
	v_dot2c_f32_bf16 v107, s51, v252
	v_dot2c_f32_bf16 v108, s50, v253
	v_dot2c_f32_bf16 v109, s51, v253
	v_dot2c_f32_bf16 v218, s50, v254
	v_dot2c_f32_bf16 v219, s51, v254
	v_dot2c_f32_bf16 v220, s50, v255
	v_dot2c_f32_bf16 v221, s51, v255
	ds_read_b128 v[252:255], v163 offset:3328
	v_fma_f32 v106, v159, v106, -v98
	v_fma_f32 v107, v159, v107, -v99
	v_fma_f32 v108, v159, v108, -v100
	v_fma_f32 v109, v159, v109, -v101
	v_fma_f32 v218, v159, v218, -v102
	v_fma_f32 v219, v159, v219, -v103
	v_fma_f32 v220, v159, v220, -v104
	v_fma_f32 v221, v159, v221, -v105
	v_cvt_pk_bf16_f32 v106, v106, v107
	v_cvt_pk_bf16_f32 v107, v108, v109
	v_cvt_pk_bf16_f32 v108, v218, v219
	v_cvt_pk_bf16_f32 v109, v220, v221
	s_and_saveexec_b64 s[28:29], s[6:7]
	s_cbranch_execz .Lpu2_1
	global_store_dwordx4 v[190:191], v[98:101], off offset:64
	global_store_dwordx4 v[190:191], v[102:105], off offset:80
.Lpu2_1:
	s_or_b64 exec, exec, s[28:29]
	s_waitcnt vmcnt(8)
	v_mfma_f32_32x32x16_bf16 v[2:17], v[106:109], v[82:85], v[2:17]
	v_mfma_f32_32x32x16_bf16 v[18:33], v[106:109], v[86:89], v[18:33]
	v_mfma_f32_32x32x16_bf16 v[34:49], v[106:109], v[90:93], v[34:49]
	v_mfma_f32_32x32x16_bf16 v[50:65], v[106:109], v[94:97], v[50:65]
	global_load_dwordx4 v[82:85], v[122:123], off offset:2048
	global_load_dwordx4 v[86:89], v[124:125], off offset:2048
	global_load_dwordx4 v[90:93], v[126:127], off offset:2048
	global_load_dwordx4 v[94:97], v[128:129], off offset:2048
	s_waitcnt lgkmcnt(3)
	v_lshlrev_b32_e32 v98, 16, v238
	v_and_b32_e32 v99, 0xffff0000, v238
	v_lshlrev_b32_e32 v100, 16, v239
	v_and_b32_e32 v101, 0xffff0000, v239
	v_lshlrev_b32_e32 v102, 16, v240
	v_and_b32_e32 v103, 0xffff0000, v240
	v_lshlrev_b32_e32 v104, 16, v241
	v_and_b32_e32 v105, 0xffff0000, v241
	v_mov_b64_e32 v[106:107], v[98:99]
	v_mov_b64_e32 v[108:109], v[100:101]
	v_mov_b64_e32 v[218:219], v[102:103]
	v_mov_b64_e32 v[220:221], v[104:105]
	ds_read_b128 v[238:241], v163 offset:4176
	s_waitcnt lgkmcnt(3)
	v_dot2c_f32_bf16 v106, s50, v242
	v_dot2c_f32_bf16 v107, s51, v242
	v_dot2c_f32_bf16 v108, s50, v243
	v_dot2c_f32_bf16 v109, s51, v243
	v_dot2c_f32_bf16 v218, s50, v244
	v_dot2c_f32_bf16 v219, s51, v244
	v_dot2c_f32_bf16 v220, s50, v245
	v_dot2c_f32_bf16 v221, s51, v245
	ds_read_b128 v[242:245], v163 offset:3904
	s_waitcnt lgkmcnt(3)
	v_dot2c_f32_bf16 v106, s50, v248
	v_dot2c_f32_bf16 v107, s51, v248
	v_dot2c_f32_bf16 v108, s50, v249
	v_dot2c_f32_bf16 v109, s51, v249
	v_dot2c_f32_bf16 v218, s50, v250
	v_dot2c_f32_bf16 v219, s51, v250
	v_dot2c_f32_bf16 v220, s50, v251
	v_dot2c_f32_bf16 v221, s51, v251
	ds_read_b128 v[248:251], v163 offset:3632
	s_waitcnt lgkmcnt(3)
	v_dot2c_f32_bf16 v106, s50, v252
	v_dot2c_f32_bf16 v107, s51, v252
	v_dot2c_f32_bf16 v108, s50, v253
	v_dot2c_f32_bf16 v109, s51, v253
	v_dot2c_f32_bf16 v218, s50, v254
	v_dot2c_f32_bf16 v219, s51, v254
	v_dot2c_f32_bf16 v220, s50, v255
	v_dot2c_f32_bf16 v221, s51, v255
	ds_read_b128 v[252:255], v163 offset:3360
	v_fma_f32 v106, v159, v106, -v98
	v_fma_f32 v107, v159, v107, -v99
	v_fma_f32 v108, v159, v108, -v100
	v_fma_f32 v109, v159, v109, -v101
	v_fma_f32 v218, v159, v218, -v102
	v_fma_f32 v219, v159, v219, -v103
	v_fma_f32 v220, v159, v220, -v104
	v_fma_f32 v221, v159, v221, -v105
	v_cvt_pk_bf16_f32 v106, v106, v107
	v_cvt_pk_bf16_f32 v107, v108, v109
	v_cvt_pk_bf16_f32 v108, v218, v219
	v_cvt_pk_bf16_f32 v109, v220, v221
	s_and_saveexec_b64 s[28:29], s[6:7]
	s_cbranch_execz .Lpu2_2
	global_store_dwordx4 v[190:191], v[98:101], off offset:128
	global_store_dwordx4 v[190:191], v[102:105], off offset:144
.Lpu2_2:
	s_or_b64 exec, exec, s[28:29]
	s_waitcnt vmcnt(8)
	v_mfma_f32_32x32x16_bf16 v[2:17], v[106:109], v[222:225], v[2:17]
	v_mfma_f32_32x32x16_bf16 v[18:33], v[106:109], v[226:229], v[18:33]
	v_mfma_f32_32x32x16_bf16 v[34:49], v[106:109], v[230:233], v[34:49]
	v_mfma_f32_32x32x16_bf16 v[50:65], v[106:109], v[234:237], v[50:65]
	global_load_dwordx4 v[222:225], v[122:123], off offset:2560
	global_load_dwordx4 v[226:229], v[124:125], off offset:2560
	global_load_dwordx4 v[230:233], v[126:127], off offset:2560
	global_load_dwordx4 v[234:237], v[128:129], off offset:2560
	s_waitcnt lgkmcnt(3)
	v_lshlrev_b32_e32 v98, 16, v238
	v_and_b32_e32 v99, 0xffff0000, v238
	v_lshlrev_b32_e32 v100, 16, v239
	v_and_b32_e32 v101, 0xffff0000, v239
	v_lshlrev_b32_e32 v102, 16, v240
	v_and_b32_e32 v103, 0xffff0000, v240
	v_lshlrev_b32_e32 v104, 16, v241
	v_and_b32_e32 v105, 0xffff0000, v241
	v_mov_b64_e32 v[106:107], v[98:99]
	v_mov_b64_e32 v[108:109], v[100:101]
	v_mov_b64_e32 v[218:219], v[102:103]
	v_mov_b64_e32 v[220:221], v[104:105]
	ds_read_b128 v[238:241], v163 offset:4208
	s_waitcnt lgkmcnt(3)
	v_dot2c_f32_bf16 v106, s50, v242
	v_dot2c_f32_bf16 v107, s51, v242
	v_dot2c_f32_bf16 v108, s50, v243
	v_dot2c_f32_bf16 v109, s51, v243
	v_dot2c_f32_bf16 v218, s50, v244
	v_dot2c_f32_bf16 v219, s51, v244
	v_dot2c_f32_bf16 v220, s50, v245
	v_dot2c_f32_bf16 v221, s51, v245
	ds_read_b128 v[242:245], v163 offset:3936
	s_waitcnt lgkmcnt(3)
	v_dot2c_f32_bf16 v106, s50, v248
	v_dot2c_f32_bf16 v107, s51, v248
	v_dot2c_f32_bf16 v108, s50, v249
	v_dot2c_f32_bf16 v109, s51, v249
	v_dot2c_f32_bf16 v218, s50, v250
	v_dot2c_f32_bf16 v219, s51, v250
	v_dot2c_f32_bf16 v220, s50, v251
	v_dot2c_f32_bf16 v221, s51, v251
	ds_read_b128 v[248:251], v163 offset:3664
	s_waitcnt lgkmcnt(3)
	v_dot2c_f32_bf16 v106, s50, v252
	v_dot2c_f32_bf16 v107, s51, v252
	v_dot2c_f32_bf16 v108, s50, v253
	v_dot2c_f32_bf16 v109, s51, v253
	v_dot2c_f32_bf16 v218, s50, v254
	v_dot2c_f32_bf16 v219, s51, v254
	v_dot2c_f32_bf16 v220, s50, v255
	v_dot2c_f32_bf16 v221, s51, v255
	ds_read_b128 v[252:255], v163 offset:3392
	v_fma_f32 v106, v159, v106, -v98
	v_fma_f32 v107, v159, v107, -v99
	v_fma_f32 v108, v159, v108, -v100
	v_fma_f32 v109, v159, v109, -v101
	v_fma_f32 v218, v159, v218, -v102
	v_fma_f32 v219, v159, v219, -v103
	v_fma_f32 v220, v159, v220, -v104
	v_fma_f32 v221, v159, v221, -v105
	v_cvt_pk_bf16_f32 v106, v106, v107
	v_cvt_pk_bf16_f32 v107, v108, v109
	v_cvt_pk_bf16_f32 v108, v218, v219
	v_cvt_pk_bf16_f32 v109, v220, v221
	s_and_saveexec_b64 s[28:29], s[6:7]
	s_cbranch_execz .Lpu2_3
	global_store_dwordx4 v[190:191], v[98:101], off offset:192
	global_store_dwordx4 v[190:191], v[102:105], off offset:208
.Lpu2_3:
	s_or_b64 exec, exec, s[28:29]
	s_waitcnt vmcnt(8)
	v_mfma_f32_32x32x16_bf16 v[2:17], v[106:109], v[70:73], v[2:17]
	v_mfma_f32_32x32x16_bf16 v[18:33], v[106:109], v[74:77], v[18:33]
	v_mfma_f32_32x32x16_bf16 v[34:49], v[106:109], v[78:81], v[34:49]
	v_mfma_f32_32x32x16_bf16 v[50:65], v[106:109], v[66:69], v[50:65]
	global_load_dwordx4 v[70:73], v[122:123], off offset:3072
	global_load_dwordx4 v[74:77], v[124:125], off offset:3072
	global_load_dwordx4 v[78:81], v[126:127], off offset:3072
	global_load_dwordx4 v[66:69], v[128:129], off offset:3072
	s_waitcnt lgkmcnt(3)
	v_lshlrev_b32_e32 v98, 16, v238
	v_and_b32_e32 v99, 0xffff0000, v238
	v_lshlrev_b32_e32 v100, 16, v239
	v_and_b32_e32 v101, 0xffff0000, v239
	v_lshlrev_b32_e32 v102, 16, v240
	v_and_b32_e32 v103, 0xffff0000, v240
	v_lshlrev_b32_e32 v104, 16, v241
	v_and_b32_e32 v105, 0xffff0000, v241
	v_mov_b64_e32 v[106:107], v[98:99]
	v_mov_b64_e32 v[108:109], v[100:101]
	v_mov_b64_e32 v[218:219], v[102:103]
	v_mov_b64_e32 v[220:221], v[104:105]
	ds_read_b128 v[238:241], v163 offset:4240
	s_waitcnt lgkmcnt(3)
	v_dot2c_f32_bf16 v106, s50, v242
	v_dot2c_f32_bf16 v107, s51, v242
	v_dot2c_f32_bf16 v108, s50, v243
	v_dot2c_f32_bf16 v109, s51, v243
	v_dot2c_f32_bf16 v218, s50, v244
	v_dot2c_f32_bf16 v219, s51, v244
	v_dot2c_f32_bf16 v220, s50, v245
	v_dot2c_f32_bf16 v221, s51, v245
	ds_read_b128 v[242:245], v163 offset:3968
	s_waitcnt lgkmcnt(3)
	v_dot2c_f32_bf16 v106, s50, v248
	v_dot2c_f32_bf16 v107, s51, v248
	v_dot2c_f32_bf16 v108, s50, v249
	v_dot2c_f32_bf16 v109, s51, v249
	v_dot2c_f32_bf16 v218, s50, v250
	v_dot2c_f32_bf16 v219, s51, v250
	v_dot2c_f32_bf16 v220, s50, v251
	v_dot2c_f32_bf16 v221, s51, v251
	ds_read_b128 v[248:251], v163 offset:3696
	s_waitcnt lgkmcnt(3)
	v_dot2c_f32_bf16 v106, s50, v252
	v_dot2c_f32_bf16 v107, s51, v252
	v_dot2c_f32_bf16 v108, s50, v253
	v_dot2c_f32_bf16 v109, s51, v253
	v_dot2c_f32_bf16 v218, s50, v254
	v_dot2c_f32_bf16 v219, s51, v254
	v_dot2c_f32_bf16 v220, s50, v255
	v_dot2c_f32_bf16 v221, s51, v255
	ds_read_b128 v[252:255], v163 offset:3424
	v_fma_f32 v106, v159, v106, -v98
	v_fma_f32 v107, v159, v107, -v99
	v_fma_f32 v108, v159, v108, -v100
	v_fma_f32 v109, v159, v109, -v101
	v_fma_f32 v218, v159, v218, -v102
	v_fma_f32 v219, v159, v219, -v103
	v_fma_f32 v220, v159, v220, -v104
	v_fma_f32 v221, v159, v221, -v105
	v_cvt_pk_bf16_f32 v106, v106, v107
	v_cvt_pk_bf16_f32 v107, v108, v109
	v_cvt_pk_bf16_f32 v108, v218, v219
	v_cvt_pk_bf16_f32 v109, v220, v221
	s_and_saveexec_b64 s[28:29], s[6:7]
	s_cbranch_execz .Lpu2_4
	global_store_dwordx4 v[190:191], v[98:101], off offset:256
	global_store_dwordx4 v[190:191], v[102:105], off offset:272
.Lpu2_4:
	s_or_b64 exec, exec, s[28:29]
	s_waitcnt vmcnt(8)
	v_mfma_f32_32x32x16_bf16 v[2:17], v[106:109], v[82:85], v[2:17]
	v_mfma_f32_32x32x16_bf16 v[18:33], v[106:109], v[86:89], v[18:33]
	v_mfma_f32_32x32x16_bf16 v[34:49], v[106:109], v[90:93], v[34:49]
	v_mfma_f32_32x32x16_bf16 v[50:65], v[106:109], v[94:97], v[50:65]
	global_load_dwordx4 v[82:85], v[122:123], off offset:3584
	global_load_dwordx4 v[86:89], v[124:125], off offset:3584
	global_load_dwordx4 v[90:93], v[126:127], off offset:3584
	global_load_dwordx4 v[94:97], v[128:129], off offset:3584
	s_waitcnt lgkmcnt(3)
	v_lshlrev_b32_e32 v98, 16, v238
	v_and_b32_e32 v99, 0xffff0000, v238
	v_lshlrev_b32_e32 v100, 16, v239
	v_and_b32_e32 v101, 0xffff0000, v239
	v_lshlrev_b32_e32 v102, 16, v240
	v_and_b32_e32 v103, 0xffff0000, v240
	v_lshlrev_b32_e32 v104, 16, v241
	v_and_b32_e32 v105, 0xffff0000, v241
	v_mov_b64_e32 v[106:107], v[98:99]
	v_mov_b64_e32 v[108:109], v[100:101]
	v_mov_b64_e32 v[218:219], v[102:103]
	v_mov_b64_e32 v[220:221], v[104:105]
	ds_read_b128 v[238:241], v163 offset:4272
	s_waitcnt lgkmcnt(3)
	v_dot2c_f32_bf16 v106, s50, v242
	v_dot2c_f32_bf16 v107, s51, v242
	v_dot2c_f32_bf16 v108, s50, v243
	v_dot2c_f32_bf16 v109, s51, v243
	v_dot2c_f32_bf16 v218, s50, v244
	v_dot2c_f32_bf16 v219, s51, v244
	v_dot2c_f32_bf16 v220, s50, v245
	v_dot2c_f32_bf16 v221, s51, v245
	ds_read_b128 v[242:245], v163 offset:4000
	s_waitcnt lgkmcnt(3)
	v_dot2c_f32_bf16 v106, s50, v248
	v_dot2c_f32_bf16 v107, s51, v248
	v_dot2c_f32_bf16 v108, s50, v249
	v_dot2c_f32_bf16 v109, s51, v249
	v_dot2c_f32_bf16 v218, s50, v250
	v_dot2c_f32_bf16 v219, s51, v250
	v_dot2c_f32_bf16 v220, s50, v251
	v_dot2c_f32_bf16 v221, s51, v251
	ds_read_b128 v[248:251], v163 offset:3728
	s_waitcnt lgkmcnt(3)
	v_dot2c_f32_bf16 v106, s50, v252
	v_dot2c_f32_bf16 v107, s51, v252
	v_dot2c_f32_bf16 v108, s50, v253
	v_dot2c_f32_bf16 v109, s51, v253
	v_dot2c_f32_bf16 v218, s50, v254
	v_dot2c_f32_bf16 v219, s51, v254
	v_dot2c_f32_bf16 v220, s50, v255
	v_dot2c_f32_bf16 v221, s51, v255
	ds_read_b128 v[252:255], v163 offset:3456
	v_fma_f32 v106, v159, v106, -v98
	v_fma_f32 v107, v159, v107, -v99
	v_fma_f32 v108, v159, v108, -v100
	v_fma_f32 v109, v159, v109, -v101
	v_fma_f32 v218, v159, v218, -v102
	v_fma_f32 v219, v159, v219, -v103
	v_fma_f32 v220, v159, v220, -v104
	v_fma_f32 v221, v159, v221, -v105
	v_cvt_pk_bf16_f32 v106, v106, v107
	v_cvt_pk_bf16_f32 v107, v108, v109
	v_cvt_pk_bf16_f32 v108, v218, v219
	v_cvt_pk_bf16_f32 v109, v220, v221
	s_and_saveexec_b64 s[28:29], s[6:7]
	s_cbranch_execz .Lpu2_5
	global_store_dwordx4 v[190:191], v[98:101], off offset:320
	global_store_dwordx4 v[190:191], v[102:105], off offset:336
.Lpu2_5:
	s_or_b64 exec, exec, s[28:29]
	s_waitcnt vmcnt(8)
	v_mfma_f32_32x32x16_bf16 v[2:17], v[106:109], v[222:225], v[2:17]
	v_mfma_f32_32x32x16_bf16 v[18:33], v[106:109], v[226:229], v[18:33]
	v_mfma_f32_32x32x16_bf16 v[34:49], v[106:109], v[230:233], v[34:49]
	v_mfma_f32_32x32x16_bf16 v[50:65], v[106:109], v[234:237], v[50:65]
	s_waitcnt lgkmcnt(3)
	v_lshlrev_b32_e32 v98, 16, v238
	v_and_b32_e32 v99, 0xffff0000, v238
	v_lshlrev_b32_e32 v100, 16, v239
	v_and_b32_e32 v101, 0xffff0000, v239
	v_lshlrev_b32_e32 v102, 16, v240
	v_and_b32_e32 v103, 0xffff0000, v240
	v_lshlrev_b32_e32 v104, 16, v241
	v_and_b32_e32 v105, 0xffff0000, v241
	v_mov_b64_e32 v[106:107], v[98:99]
	v_mov_b64_e32 v[108:109], v[100:101]
	v_mov_b64_e32 v[218:219], v[102:103]
	v_mov_b64_e32 v[220:221], v[104:105]
	ds_read_b128 v[238:241], v163 offset:4304
	s_waitcnt lgkmcnt(3)
	v_dot2c_f32_bf16 v106, s50, v242
	v_dot2c_f32_bf16 v107, s51, v242
	v_dot2c_f32_bf16 v108, s50, v243
	v_dot2c_f32_bf16 v109, s51, v243
	v_dot2c_f32_bf16 v218, s50, v244
	v_dot2c_f32_bf16 v219, s51, v244
	v_dot2c_f32_bf16 v220, s50, v245
	v_dot2c_f32_bf16 v221, s51, v245
	ds_read_b128 v[242:245], v163 offset:4032
	s_waitcnt lgkmcnt(3)
	v_dot2c_f32_bf16 v106, s50, v248
	v_dot2c_f32_bf16 v107, s51, v248
	v_dot2c_f32_bf16 v108, s50, v249
	v_dot2c_f32_bf16 v109, s51, v249
	v_dot2c_f32_bf16 v218, s50, v250
	v_dot2c_f32_bf16 v219, s51, v250
	v_dot2c_f32_bf16 v220, s50, v251
	v_dot2c_f32_bf16 v221, s51, v251
	ds_read_b128 v[248:251], v163 offset:3760
	s_waitcnt lgkmcnt(3)
	v_dot2c_f32_bf16 v106, s50, v252
	v_dot2c_f32_bf16 v107, s51, v252
	v_dot2c_f32_bf16 v108, s50, v253
	v_dot2c_f32_bf16 v109, s51, v253
	v_dot2c_f32_bf16 v218, s50, v254
	v_dot2c_f32_bf16 v219, s51, v254
	v_dot2c_f32_bf16 v220, s50, v255
	v_dot2c_f32_bf16 v221, s51, v255
	ds_read_b128 v[252:255], v163 offset:3488
	v_fma_f32 v106, v159, v106, -v98
	v_fma_f32 v107, v159, v107, -v99
	v_fma_f32 v108, v159, v108, -v100
	v_fma_f32 v109, v159, v109, -v101
	v_fma_f32 v218, v159, v218, -v102
	v_fma_f32 v219, v159, v219, -v103
	v_fma_f32 v220, v159, v220, -v104
	v_fma_f32 v221, v159, v221, -v105
	v_cvt_pk_bf16_f32 v106, v106, v107
	v_cvt_pk_bf16_f32 v107, v108, v109
	v_cvt_pk_bf16_f32 v108, v218, v219
	v_cvt_pk_bf16_f32 v109, v220, v221
	s_and_saveexec_b64 s[28:29], s[6:7]
	s_cbranch_execz .Lpu2_6
	global_store_dwordx4 v[190:191], v[98:101], off offset:384
	global_store_dwordx4 v[190:191], v[102:105], off offset:400
.Lpu2_6:
	s_or_b64 exec, exec, s[28:29]
	s_waitcnt vmcnt(4)
	v_mfma_f32_32x32x16_bf16 v[2:17], v[106:109], v[70:73], v[2:17]
	v_mfma_f32_32x32x16_bf16 v[18:33], v[106:109], v[74:77], v[18:33]
	v_mfma_f32_32x32x16_bf16 v[34:49], v[106:109], v[78:81], v[34:49]
	v_mfma_f32_32x32x16_bf16 v[50:65], v[106:109], v[66:69], v[50:65]
	s_waitcnt lgkmcnt(3)
	v_lshlrev_b32_e32 v98, 16, v238
	v_and_b32_e32 v99, 0xffff0000, v238
	v_lshlrev_b32_e32 v100, 16, v239
	v_and_b32_e32 v101, 0xffff0000, v239
	v_lshlrev_b32_e32 v102, 16, v240
	v_and_b32_e32 v103, 0xffff0000, v240
	v_lshlrev_b32_e32 v104, 16, v241
	v_and_b32_e32 v105, 0xffff0000, v241
	v_mov_b64_e32 v[106:107], v[98:99]
	v_mov_b64_e32 v[108:109], v[100:101]
	v_mov_b64_e32 v[218:219], v[102:103]
	v_mov_b64_e32 v[220:221], v[104:105]
	s_waitcnt lgkmcnt(2)
	v_dot2c_f32_bf16 v106, s50, v242
	v_dot2c_f32_bf16 v107, s51, v242
	v_dot2c_f32_bf16 v108, s50, v243
	v_dot2c_f32_bf16 v109, s51, v243
	v_dot2c_f32_bf16 v218, s50, v244
	v_dot2c_f32_bf16 v219, s51, v244
	v_dot2c_f32_bf16 v220, s50, v245
	v_dot2c_f32_bf16 v221, s51, v245
	s_waitcnt lgkmcnt(1)
	v_dot2c_f32_bf16 v106, s50, v248
	v_dot2c_f32_bf16 v107, s51, v248
	v_dot2c_f32_bf16 v108, s50, v249
	v_dot2c_f32_bf16 v109, s51, v249
	v_dot2c_f32_bf16 v218, s50, v250
	v_dot2c_f32_bf16 v219, s51, v250
	v_dot2c_f32_bf16 v220, s50, v251
	v_dot2c_f32_bf16 v221, s51, v251
	s_waitcnt lgkmcnt(0)
	v_dot2c_f32_bf16 v106, s50, v252
	v_dot2c_f32_bf16 v107, s51, v252
	v_dot2c_f32_bf16 v108, s50, v253
	v_dot2c_f32_bf16 v109, s51, v253
	v_dot2c_f32_bf16 v218, s50, v254
	v_dot2c_f32_bf16 v219, s51, v254
	v_dot2c_f32_bf16 v220, s50, v255
	v_dot2c_f32_bf16 v221, s51, v255
	v_fma_f32 v106, v159, v106, -v98
	v_fma_f32 v107, v159, v107, -v99
	v_fma_f32 v108, v159, v108, -v100
	v_fma_f32 v109, v159, v109, -v101
	v_fma_f32 v218, v159, v218, -v102
	v_fma_f32 v219, v159, v219, -v103
	v_fma_f32 v220, v159, v220, -v104
	v_fma_f32 v221, v159, v221, -v105
	v_cvt_pk_bf16_f32 v106, v106, v107
	v_cvt_pk_bf16_f32 v107, v108, v109
	v_cvt_pk_bf16_f32 v108, v218, v219
	v_cvt_pk_bf16_f32 v109, v220, v221
	s_and_saveexec_b64 s[28:29], s[6:7]
	s_cbranch_execz .Lpu2_7
	global_store_dwordx4 v[190:191], v[98:101], off offset:448
	global_store_dwordx4 v[190:191], v[102:105], off offset:464

.LBB0_403:
	s_or_b64 exec, exec, s[2:3]
	s_waitcnt lgkmcnt(0)
	global_load_dwordx4 v[82:85], v[110:111], off offset:512
	global_load_dwordx4 v[86:89], v[134:135], off offset:512
	global_load_dwordx4 v[90:93], v[136:137], off offset:512
	global_load_dwordx4 v[94:97], v[138:139], off offset:512
	global_load_dwordx4 v[222:225], v[110:111], off offset:1024
	global_load_dwordx4 v[226:229], v[134:135], off offset:1024
	global_load_dwordx4 v[230:233], v[136:137], off offset:1024
	global_load_dwordx4 v[234:237], v[138:139], off offset:1024
	s_ashr_i32 s2, s30, 6
	v_or_b32_e32 v2, s28, v1
	s_mul_i32 s2, s2, 15
	v_cmp_eq_u32_e32 vcc, 0, v2
	v_cmp_lt_u32_e64 s[6:7], s41, v2
	s_ashr_i32 s3, s2, 31
	v_add_u32_e32 v2, 0xfffff80f, v2
	v_mov_b32_e32 v3, v155
	v_lshl_add_u64 v[2:3], v[2:3], 0, s[2:3]
	v_lshlrev_b64 v[2:3], 11, v[2:3]
	v_lshl_add_u64 v[184:185], v[140:141], 0, v[2:3]
	v_mov_b32_e32 v2, 0
	s_mov_b32 s28, 0
	v_cndmask_b32_e64 v159, 0.5, 1.0, vcc
	s_mov_b64 s[2:3], 0
	v_mov_b32_e32 v3, v2
	v_mov_b32_e32 v4, v2
	v_mov_b32_e32 v5, v2
	v_mov_b32_e32 v6, v2
	v_mov_b32_e32 v7, v2
	v_mov_b32_e32 v8, v2
	v_mov_b32_e32 v9, v2
	v_mov_b32_e32 v10, v2
	v_mov_b32_e32 v11, v2
	v_mov_b32_e32 v12, v2
	v_mov_b32_e32 v13, v2
	v_mov_b32_e32 v14, v2
	v_mov_b32_e32 v15, v2
	v_mov_b32_e32 v16, v2
	v_mov_b32_e32 v17, v2
	v_mov_b32_e32 v18, v2
	v_mov_b32_e32 v19, v2
	v_mov_b32_e32 v20, v2
	v_mov_b32_e32 v21, v2
	v_mov_b32_e32 v22, v2
	v_mov_b32_e32 v23, v2
	v_mov_b32_e32 v24, v2
	v_mov_b32_e32 v25, v2
	v_mov_b32_e32 v26, v2
	v_mov_b32_e32 v27, v2
	v_mov_b32_e32 v28, v2
	v_mov_b32_e32 v29, v2
	v_mov_b32_e32 v30, v2
	v_mov_b32_e32 v31, v2
	v_mov_b32_e32 v32, v2
	v_mov_b32_e32 v33, v2
	v_mov_b32_e32 v34, v2
	v_mov_b32_e32 v35, v2
	v_mov_b32_e32 v36, v2
	v_mov_b32_e32 v37, v2
	v_mov_b32_e32 v38, v2
	v_mov_b32_e32 v39, v2
	v_mov_b32_e32 v40, v2
	v_mov_b32_e32 v41, v2
	v_mov_b32_e32 v42, v2
	v_mov_b32_e32 v43, v2
	v_mov_b32_e32 v44, v2
	v_mov_b32_e32 v45, v2
	v_mov_b32_e32 v46, v2
	v_mov_b32_e32 v47, v2
	v_mov_b32_e32 v48, v2
	v_mov_b32_e32 v49, v2
	v_mov_b32_e32 v50, v2
	v_mov_b32_e32 v51, v2
	v_mov_b32_e32 v52, v2
	v_mov_b32_e32 v53, v2
	v_mov_b32_e32 v54, v2
	v_mov_b32_e32 v55, v2
	v_mov_b32_e32 v56, v2
	v_mov_b32_e32 v57, v2
	v_mov_b32_e32 v58, v2
	v_mov_b32_e32 v59, v2
	v_mov_b32_e32 v60, v2
	v_mov_b32_e32 v61, v2
	v_mov_b32_e32 v62, v2
	v_mov_b32_e32 v63, v2
	v_mov_b32_e32 v64, v2
	v_mov_b32_e32 v65, v2
	s_mov_b32 s50, 0x3f80
	s_mov_b32 s51, 0x3f800000
	v_lshl_add_u32 v163, v197, 1, v214
	ds_read_b128 v[238:241], v163 offset:4080
	ds_read_b128 v[242:245], v163 offset:3808
	ds_read_b128 v[248:251], v163 offset:4112
	ds_read_b128 v[252:255], v163 offset:3840
	s_waitcnt lgkmcnt(3)
	v_lshlrev_b32_e32 v98, 16, v238
	v_and_b32_e32 v99, 0xffff0000, v238
	v_lshlrev_b32_e32 v100, 16, v239
	v_and_b32_e32 v101, 0xffff0000, v239
	v_lshlrev_b32_e32 v102, 16, v240
	v_and_b32_e32 v103, 0xffff0000, v240
	v_lshlrev_b32_e32 v104, 16, v241
	v_and_b32_e32 v105, 0xffff0000, v241
	v_mov_b64_e32 v[106:107], v[98:99]
	v_mov_b64_e32 v[108:109], v[100:101]
	v_mov_b64_e32 v[218:219], v[102:103]
	v_mov_b64_e32 v[220:221], v[104:105]
	ds_read_b128 v[238:241], v163 offset:4144
	s_waitcnt lgkmcnt(3)
	v_dot2c_f32_bf16 v106, s50, v242
	v_dot2c_f32_bf16 v107, s51, v242
	v_dot2c_f32_bf16 v108, s50, v243
	v_dot2c_f32_bf16 v109, s51, v243
	v_dot2c_f32_bf16 v218, s50, v244
	v_dot2c_f32_bf16 v219, s51, v244
	v_dot2c_f32_bf16 v220, s50, v245
	v_dot2c_f32_bf16 v221, s51, v245
	ds_read_b128 v[242:245], v163 offset:3872
	v_fma_f32 v106, v159, v106, -v98
	v_fma_f32 v107, v159, v107, -v99
	v_fma_f32 v108, v159, v108, -v100
	v_fma_f32 v109, v159, v109, -v101
	v_fma_f32 v218, v159, v218, -v102
	v_fma_f32 v219, v159, v219, -v103
	v_fma_f32 v220, v159, v220, -v104
	v_fma_f32 v221, v159, v221, -v105
	v_cvt_pk_bf16_f32 v106, v106, v107
	v_cvt_pk_bf16_f32 v107, v108, v109
	v_cvt_pk_bf16_f32 v108, v218, v219
	v_cvt_pk_bf16_f32 v109, v220, v221
	s_and_saveexec_b64 s[10:11], s[6:7]
	s_cbranch_execz .Lpu3_0
	global_store_dwordx4 v[184:185], v[98:101], off offset:0
	global_store_dwordx4 v[184:185], v[102:105], off offset:16
.Lpu3_0:
	s_or_b64 exec, exec, s[10:11]
	s_waitcnt vmcnt(8)
	v_mfma_f32_32x32x16_bf16 v[2:17], v[106:109], v[70:73], v[2:17]
	v_mfma_f32_32x32x16_bf16 v[18:33], v[106:109], v[74:77], v[18:33]
	v_mfma_f32_32x32x16_bf16 v[34:49], v[106:109], v[78:81], v[34:49]
	v_mfma_f32_32x32x16_bf16 v[50:65], v[106:109], v[66:69], v[50:65]
	global_load_dwordx4 v[70:73], v[110:111], off offset:1536
	global_load_dwordx4 v[74:77], v[134:135], off offset:1536
	global_load_dwordx4 v[78:81], v[136:137], off offset:1536
	global_load_dwordx4 v[66:69], v[138:139], off offset:1536
	s_waitcnt lgkmcnt(3)
	v_lshlrev_b32_e32 v98, 16, v248
	v_and_b32_e32 v99, 0xffff0000, v248
	v_lshlrev_b32_e32 v100, 16, v249
	v_and_b32_e32 v101, 0xffff0000, v249
	v_lshlrev_b32_e32 v102, 16, v250
	v_and_b32_e32 v103, 0xffff0000, v250
	v_lshlrev_b32_e32 v104, 16, v251
	v_and_b32_e32 v105, 0xffff0000, v251
	v_mov_b64_e32 v[106:107], v[98:99]
	v_mov_b64_e32 v[108:109], v[100:101]
	v_mov_b64_e32 v[218:219], v[102:103]
	v_mov_b64_e32 v[220:221], v[104:105]
	ds_read_b128 v[248:251], v163 offset:4176
	s_waitcnt lgkmcnt(3)
	v_dot2c_f32_bf16 v106, s50, v252
	v_dot2c_f32_bf16 v107, s51, v252
	v_dot2c_f32_bf16 v108, s50, v253
	v_dot2c_f32_bf16 v109, s51, v253
	v_dot2c_f32_bf16 v218, s50, v254
	v_dot2c_f32_bf16 v219, s51, v254
	v_dot2c_f32_bf16 v220, s50, v255
	v_dot2c_f32_bf16 v221, s51, v255
	ds_read_b128 v[252:255], v163 offset:3904
	v_fma_f32 v106, v159, v106, -v98
	v_fma_f32 v107, v159, v107, -v99
	v_fma_f32 v108, v159, v108, -v100
	v_fma_f32 v109, v159, v109, -v101
	v_fma_f32 v218, v159, v218, -v102
	v_fma_f32 v219, v159, v219, -v103
	v_fma_f32 v220, v159, v220, -v104
	v_fma_f32 v221, v159, v221, -v105
	v_cvt_pk_bf16_f32 v106, v106, v107
	v_cvt_pk_bf16_f32 v107, v108, v109
	v_cvt_pk_bf16_f32 v108, v218, v219
	v_cvt_pk_bf16_f32 v109, v220, v221
	s_and_saveexec_b64 s[10:11], s[6:7]
	s_cbranch_execz .Lpu3_1
	global_store_dwordx4 v[184:185], v[98:101], off offset:64
	global_store_dwordx4 v[184:185], v[102:105], off offset:80
.Lpu3_1:
	s_or_b64 exec, exec, s[10:11]
	s_waitcnt vmcnt(8)
	v_mfma_f32_32x32x16_bf16 v[2:17], v[106:109], v[82:85], v[2:17]
	v_mfma_f32_32x32x16_bf16 v[18:33], v[106:109], v[86:89], v[18:33]
	v_mfma_f32_32x32x16_bf16 v[34:49], v[106:109], v[90:93], v[34:49]
	v_mfma_f32_32x32x16_bf16 v[50:65], v[106:109], v[94:97], v[50:65]
	global_load_dwordx4 v[82:85], v[110:111], off offset:2048
	global_load_dwordx4 v[86:89], v[134:135], off offset:2048
	global_load_dwordx4 v[90:93], v[136:137], off offset:2048
	global_load_dwordx4 v[94:97], v[138:139], off offset:2048
	s_waitcnt lgkmcnt(3)
	v_lshlrev_b32_e32 v98, 16, v238
	v_and_b32_e32 v99, 0xffff0000, v238
	v_lshlrev_b32_e32 v100, 16, v239
	v_and_b32_e32 v101, 0xffff0000, v239
	v_lshlrev_b32_e32 v102, 16, v240
	v_and_b32_e32 v103, 0xffff0000, v240
	v_lshlrev_b32_e32 v104, 16, v241
	v_and_b32_e32 v105, 0xffff0000, v241
	v_mov_b64_e32 v[106:107], v[98:99]
	v_mov_b64_e32 v[108:109], v[100:101]
	v_mov_b64_e32 v[218:219], v[102:103]
	v_mov_b64_e32 v[220:221], v[104:105]
	ds_read_b128 v[238:241], v163 offset:4208
	s_waitcnt lgkmcnt(3)
	v_dot2c_f32_bf16 v106, s50, v242
	v_dot2c_f32_bf16 v107, s51, v242
	v_dot2c_f32_bf16 v108, s50, v243
	v_dot2c_f32_bf16 v109, s51, v243
	v_dot2c_f32_bf16 v218, s50, v244
	v_dot2c_f32_bf16 v219, s51, v244
	v_dot2c_f32_bf16 v220, s50, v245
	v_dot2c_f32_bf16 v221, s51, v245
	ds_read_b128 v[242:245], v163 offset:3936
	v_fma_f32 v106, v159, v106, -v98
	v_fma_f32 v107, v159, v107, -v99
	v_fma_f32 v108, v159, v108, -v100
	v_fma_f32 v109, v159, v109, -v101
	v_fma_f32 v218, v159, v218, -v102
	v_fma_f32 v219, v159, v219, -v103
	v_fma_f32 v220, v159, v220, -v104
	v_fma_f32 v221, v159, v221, -v105
	v_cvt_pk_bf16_f32 v106, v106, v107
	v_cvt_pk_bf16_f32 v107, v108, v109
	v_cvt_pk_bf16_f32 v108, v218, v219
	v_cvt_pk_bf16_f32 v109, v220, v221
	s_and_saveexec_b64 s[10:11], s[6:7]
	s_cbranch_execz .Lpu3_2
	global_store_dwordx4 v[184:185], v[98:101], off offset:128
	global_store_dwordx4 v[184:185], v[102:105], off offset:144
.Lpu3_2:
	s_or_b64 exec, exec, s[10:11]
	s_waitcnt vmcnt(8)
	v_mfma_f32_32x32x16_bf16 v[2:17], v[106:109], v[222:225], v[2:17]
	v_mfma_f32_32x32x16_bf16 v[18:33], v[106:109], v[226:229], v[18:33]
	v_mfma_f32_32x32x16_bf16 v[34:49], v[106:109], v[230:233], v[34:49]
	v_mfma_f32_32x32x16_bf16 v[50:65], v[106:109], v[234:237], v[50:65]
	global_load_dwordx4 v[222:225], v[110:111], off offset:2560
	global_load_dwordx4 v[226:229], v[134:135], off offset:2560
	global_load_dwordx4 v[230:233], v[136:137], off offset:2560
	global_load_dwordx4 v[234:237], v[138:139], off offset:2560
	s_waitcnt lgkmcnt(3)
	v_lshlrev_b32_e32 v98, 16, v248
	v_and_b32_e32 v99, 0xffff0000, v248
	v_lshlrev_b32_e32 v100, 16, v249
	v_and_b32_e32 v101, 0xffff0000, v249
	v_lshlrev_b32_e32 v102, 16, v250
	v_and_b32_e32 v103, 0xffff0000, v250
	v_lshlrev_b32_e32 v104, 16, v251
	v_and_b32_e32 v105, 0xffff0000, v251
	v_mov_b64_e32 v[106:107], v[98:99]
	v_mov_b64_e32 v[108:109], v[100:101]
	v_mov_b64_e32 v[218:219], v[102:103]
	v_mov_b64_e32 v[220:221], v[104:105]
	ds_read_b128 v[248:251], v163 offset:4240
	s_waitcnt lgkmcnt(3)
	v_dot2c_f32_bf16 v106, s50, v252
	v_dot2c_f32_bf16 v107, s51, v252
	v_dot2c_f32_bf16 v108, s50, v253
	v_dot2c_f32_bf16 v109, s51, v253
	v_dot2c_f32_bf16 v218, s50, v254
	v_dot2c_f32_bf16 v219, s51, v254
	v_dot2c_f32_bf16 v220, s50, v255
	v_dot2c_f32_bf16 v221, s51, v255
	ds_read_b128 v[252:255], v163 offset:3968
	v_fma_f32 v106, v159, v106, -v98
	v_fma_f32 v107, v159, v107, -v99
	v_fma_f32 v108, v159, v108, -v100
	v_fma_f32 v109, v159, v109, -v101
	v_fma_f32 v218, v159, v218, -v102
	v_fma_f32 v219, v159, v219, -v103
	v_fma_f32 v220, v159, v220, -v104
	v_fma_f32 v221, v159, v221, -v105
	v_cvt_pk_bf16_f32 v106, v106, v107
	v_cvt_pk_bf16_f32 v107, v108, v109
	v_cvt_pk_bf16_f32 v108, v218, v219
	v_cvt_pk_bf16_f32 v109, v220, v221
	s_and_saveexec_b64 s[10:11], s[6:7]
	s_cbranch_execz .Lpu3_3
	global_store_dwordx4 v[184:185], v[98:101], off offset:192
	global_store_dwordx4 v[184:185], v[102:105], off offset:208
.Lpu3_3:
	s_or_b64 exec, exec, s[10:11]
	s_waitcnt vmcnt(8)
	v_mfma_f32_32x32x16_bf16 v[2:17], v[106:109], v[70:73], v[2:17]
	v_mfma_f32_32x32x16_bf16 v[18:33], v[106:109], v[74:77], v[18:33]
	v_mfma_f32_32x32x16_bf16 v[34:49], v[106:109], v[78:81], v[34:49]
	v_mfma_f32_32x32x16_bf16 v[50:65], v[106:109], v[66:69], v[50:65]
	global_load_dwordx4 v[70:73], v[110:111], off offset:3072
	global_load_dwordx4 v[74:77], v[134:135], off offset:3072
	global_load_dwordx4 v[78:81], v[136:137], off offset:3072
	global_load_dwordx4 v[66:69], v[138:139], off offset:3072
	s_waitcnt lgkmcnt(3)
	v_lshlrev_b32_e32 v98, 16, v238
	v_and_b32_e32 v99, 0xffff0000, v238
	v_lshlrev_b32_e32 v100, 16, v239
	v_and_b32_e32 v101, 0xffff0000, v239
	v_lshlrev_b32_e32 v102, 16, v240
	v_and_b32_e32 v103, 0xffff0000, v240
	v_lshlrev_b32_e32 v104, 16, v241
	v_and_b32_e32 v105, 0xffff0000, v241
	v_mov_b64_e32 v[106:107], v[98:99]
	v_mov_b64_e32 v[108:109], v[100:101]
	v_mov_b64_e32 v[218:219], v[102:103]
	v_mov_b64_e32 v[220:221], v[104:105]
	ds_read_b128 v[238:241], v163 offset:4272
	s_waitcnt lgkmcnt(3)
	v_dot2c_f32_bf16 v106, s50, v242
	v_dot2c_f32_bf16 v107, s51, v242
	v_dot2c_f32_bf16 v108, s50, v243
	v_dot2c_f32_bf16 v109, s51, v243
	v_dot2c_f32_bf16 v218, s50, v244
	v_dot2c_f32_bf16 v219, s51, v244
	v_dot2c_f32_bf16 v220, s50, v245
	v_dot2c_f32_bf16 v221, s51, v245
	ds_read_b128 v[242:245], v163 offset:4000
	v_fma_f32 v106, v159, v106, -v98
	v_fma_f32 v107, v159, v107, -v99
	v_fma_f32 v108, v159, v108, -v100
	v_fma_f32 v109, v159, v109, -v101
	v_fma_f32 v218, v159, v218, -v102
	v_fma_f32 v219, v159, v219, -v103
	v_fma_f32 v220, v159, v220, -v104
	v_fma_f32 v221, v159, v221, -v105
	v_cvt_pk_bf16_f32 v106, v106, v107
	v_cvt_pk_bf16_f32 v107, v108, v109
	v_cvt_pk_bf16_f32 v108, v218, v219
	v_cvt_pk_bf16_f32 v109, v220, v221
	s_and_saveexec_b64 s[10:11], s[6:7]
	s_cbranch_execz .Lpu3_4
	global_store_dwordx4 v[184:185], v[98:101], off offset:256
	global_store_dwordx4 v[184:185], v[102:105], off offset:272
.Lpu3_4:
	s_or_b64 exec, exec, s[10:11]
	s_waitcnt vmcnt(8)
	v_mfma_f32_32x32x16_bf16 v[2:17], v[106:109], v[82:85], v[2:17]
	v_mfma_f32_32x32x16_bf16 v[18:33], v[106:109], v[86:89], v[18:33]
	v_mfma_f32_32x32x16_bf16 v[34:49], v[106:109], v[90:93], v[34:49]
	v_mfma_f32_32x32x16_bf16 v[50:65], v[106:109], v[94:97], v[50:65]
	global_load_dwordx4 v[82:85], v[110:111], off offset:3584
	global_load_dwordx4 v[86:89], v[134:135], off offset:3584
	global_load_dwordx4 v[90:93], v[136:137], off offset:3584
	global_load_dwordx4 v[94:97], v[138:139], off offset:3584
	s_waitcnt lgkmcnt(3)
	v_lshlrev_b32_e32 v98, 16, v248
	v_and_b32_e32 v99, 0xffff0000, v248
	v_lshlrev_b32_e32 v100, 16, v249
	v_and_b32_e32 v101, 0xffff0000, v249
	v_lshlrev_b32_e32 v102, 16, v250
	v_and_b32_e32 v103, 0xffff0000, v250
	v_lshlrev_b32_e32 v104, 16, v251
	v_and_b32_e32 v105, 0xffff0000, v251
	v_mov_b64_e32 v[106:107], v[98:99]
	v_mov_b64_e32 v[108:109], v[100:101]
	v_mov_b64_e32 v[218:219], v[102:103]
	v_mov_b64_e32 v[220:221], v[104:105]
	ds_read_b128 v[248:251], v163 offset:4304
	s_waitcnt lgkmcnt(3)
	v_dot2c_f32_bf16 v106, s50, v252
	v_dot2c_f32_bf16 v107, s51, v252
	v_dot2c_f32_bf16 v108, s50, v253
	v_dot2c_f32_bf16 v109, s51, v253
	v_dot2c_f32_bf16 v218, s50, v254
	v_dot2c_f32_bf16 v219, s51, v254
	v_dot2c_f32_bf16 v220, s50, v255
	v_dot2c_f32_bf16 v221, s51, v255
	ds_read_b128 v[252:255], v163 offset:4032
	v_fma_f32 v106, v159, v106, -v98
	v_fma_f32 v107, v159, v107, -v99
	v_fma_f32 v108, v159, v108, -v100
	v_fma_f32 v109, v159, v109, -v101
	v_fma_f32 v218, v159, v218, -v102
	v_fma_f32 v219, v159, v219, -v103
	v_fma_f32 v220, v159, v220, -v104
	v_fma_f32 v221, v159, v221, -v105
	v_cvt_pk_bf16_f32 v106, v106, v107
	v_cvt_pk_bf16_f32 v107, v108, v109
	v_cvt_pk_bf16_f32 v108, v218, v219
	v_cvt_pk_bf16_f32 v109, v220, v221
	s_and_saveexec_b64 s[10:11], s[6:7]
	s_cbranch_execz .Lpu3_5
	global_store_dwordx4 v[184:185], v[98:101], off offset:320
	global_store_dwordx4 v[184:185], v[102:105], off offset:336
.Lpu3_5:
	s_or_b64 exec, exec, s[10:11]
	s_waitcnt vmcnt(8)
	v_mfma_f32_32x32x16_bf16 v[2:17], v[106:109], v[222:225], v[2:17]
	v_mfma_f32_32x32x16_bf16 v[18:33], v[106:109], v[226:229], v[18:33]
	v_mfma_f32_32x32x16_bf16 v[34:49], v[106:109], v[230:233], v[34:49]
	v_mfma_f32_32x32x16_bf16 v[50:65], v[106:109], v[234:237], v[50:65]
	s_waitcnt lgkmcnt(3)
	v_lshlrev_b32_e32 v98, 16, v238
	v_and_b32_e32 v99, 0xffff0000, v238
	v_lshlrev_b32_e32 v100, 16, v239
	v_and_b32_e32 v101, 0xffff0000, v239
	v_lshlrev_b32_e32 v102, 16, v240
	v_and_b32_e32 v103, 0xffff0000, v240
	v_lshlrev_b32_e32 v104, 16, v241
	v_and_b32_e32 v105, 0xffff0000, v241
	v_mov_b64_e32 v[106:107], v[98:99]
	v_mov_b64_e32 v[108:109], v[100:101]
	v_mov_b64_e32 v[218:219], v[102:103]
	v_mov_b64_e32 v[220:221], v[104:105]
	s_waitcnt lgkmcnt(2)
	v_dot2c_f32_bf16 v106, s50, v242
	v_dot2c_f32_bf16 v107, s51, v242
	v_dot2c_f32_bf16 v108, s50, v243
	v_dot2c_f32_bf16 v109, s51, v243
	v_dot2c_f32_bf16 v218, s50, v244
	v_dot2c_f32_bf16 v219, s51, v244
	v_dot2c_f32_bf16 v220, s50, v245
	v_dot2c_f32_bf16 v221, s51, v245
	v_fma_f32 v106, v159, v106, -v98
	v_fma_f32 v107, v159, v107, -v99
	v_fma_f32 v108, v159, v108, -v100
	v_fma_f32 v109, v159, v109, -v101
	v_fma_f32 v218, v159, v218, -v102
	v_fma_f32 v219, v159, v219, -v103
	v_fma_f32 v220, v159, v220, -v104
	v_fma_f32 v221, v159, v221, -v105
	v_cvt_pk_bf16_f32 v106, v106, v107
	v_cvt_pk_bf16_f32 v107, v108, v109
	v_cvt_pk_bf16_f32 v108, v218, v219
	v_cvt_pk_bf16_f32 v109, v220, v221
	s_and_saveexec_b64 s[10:11], s[6:7]
	s_cbranch_execz .Lpu3_6
	global_store_dwordx4 v[184:185], v[98:101], off offset:384
	global_store_dwordx4 v[184:185], v[102:105], off offset:400
.Lpu3_6:
	s_or_b64 exec, exec, s[10:11]
	s_waitcnt vmcnt(4)
	v_mfma_f32_32x32x16_bf16 v[2:17], v[106:109], v[70:73], v[2:17]
	v_mfma_f32_32x32x16_bf16 v[18:33], v[106:109], v[74:77], v[18:33]
	v_mfma_f32_32x32x16_bf16 v[34:49], v[106:109], v[78:81], v[34:49]
	v_mfma_f32_32x32x16_bf16 v[50:65], v[106:109], v[66:69], v[50:65]
	s_waitcnt lgkmcnt(1)
	v_lshlrev_b32_e32 v98, 16, v248
	v_and_b32_e32 v99, 0xffff0000, v248
	v_lshlrev_b32_e32 v100, 16, v249
	v_and_b32_e32 v101, 0xffff0000, v249
	v_lshlrev_b32_e32 v102, 16, v250
	v_and_b32_e32 v103, 0xffff0000, v250
	v_lshlrev_b32_e32 v104, 16, v251
	v_and_b32_e32 v105, 0xffff0000, v251
	v_mov_b64_e32 v[106:107], v[98:99]
	v_mov_b64_e32 v[108:109], v[100:101]
	v_mov_b64_e32 v[218:219], v[102:103]
	v_mov_b64_e32 v[220:221], v[104:105]
	s_waitcnt lgkmcnt(0)
	v_dot2c_f32_bf16 v106, s50, v252
	v_dot2c_f32_bf16 v107, s51, v252
	v_dot2c_f32_bf16 v108, s50, v253
	v_dot2c_f32_bf16 v109, s51, v253
	v_dot2c_f32_bf16 v218, s50, v254
	v_dot2c_f32_bf16 v219, s51, v254
	v_dot2c_f32_bf16 v220, s50, v255
	v_dot2c_f32_bf16 v221, s51, v255
	v_fma_f32 v106, v159, v106, -v98
	v_fma_f32 v107, v159, v107, -v99
	v_fma_f32 v108, v159, v108, -v100
	v_fma_f32 v109, v159, v109, -v101
	v_fma_f32 v218, v159, v218, -v102
	v_fma_f32 v219, v159, v219, -v103
	v_fma_f32 v220, v159, v220, -v104
	v_fma_f32 v221, v159, v221, -v105
	v_cvt_pk_bf16_f32 v106, v106, v107
	v_cvt_pk_bf16_f32 v107, v108, v109
	v_cvt_pk_bf16_f32 v108, v218, v219
	v_cvt_pk_bf16_f32 v109, v220, v221
	s_and_saveexec_b64 s[10:11], s[6:7]
	s_cbranch_execz .Lpu3_7
	global_store_dwordx4 v[184:185], v[98:101], off offset:448
	global_store_dwordx4 v[184:185], v[102:105], off offset:464
.Lpu3_7:
	s_or_b64 exec, exec, s[10:11]
	s_waitcnt vmcnt(0)
	v_mfma_f32_32x32x16_bf16 v[2:17], v[106:109], v[82:85], v[2:17]
	v_mfma_f32_32x32x16_bf16 v[18:33], v[106:109], v[86:89], v[18:33]
	v_mfma_f32_32x32x16_bf16 v[34:49], v[106:109], v[90:93], v[34:49]
	v_mfma_f32_32x32x16_bf16 v[50:65], v[106:109], v[94:97], v[50:65]
	s_branch .LBB0_312
